# no per-segment priority toggling: all 192 s_setprio removed from the 8-phase GEMM loops (v100 otherwise)
# baseline (speedup 1.0000x reference)
.LBB0_158:
	ds_read_b128 v[158:161], v155
	ds_read_b128 v[162:165], v155 offset:1024
	ds_read_b128 v[166:169], v155 offset:2048
	ds_read_b128 v[170:173], v155 offset:3072
	ds_read_b128 v[174:177], v156
	ds_read_b128 v[178:181], v156 offset:1024
	ds_read_b128 v[182:185], v156 offset:2048
	ds_read_b128 v[186:189], v156 offset:3072
	s_add_u32 s26, s24, 0xfff80080
	s_addc_u32 s27, s25, -1
	s_cmp_eq_u32 s61, 28
	s_cselect_b32 s37, s21, s27
	s_cselect_b32 s36, s20, s26
	s_cselect_b32 s27, s23, s60
	s_cselect_b32 s26, s22, s59
	v_lshl_add_u64 v[222:223], s[24:25], 0, v[138:139]
	s_add_i32 m0, s39, 0xc000
	ds_read_b128 v[190:193], v157
	ds_read_b128 v[194:197], v157 offset:1024
	ds_read_b128 v[198:201], v157 offset:2048
	ds_read_b128 v[202:205], v157 offset:3072
	ds_read_b128 v[206:209], v157 offset:4096
	ds_read_b128 v[210:213], v157 offset:5120
	ds_read_b128 v[214:217], v157 offset:6144
	ds_read_b128 v[218:221], v157 offset:7168
	global_load_lds_dwordx4 v[222:223], off
	v_lshl_add_u64 v[222:223], s[24:25], 0, v[140:141]
	s_add_i32 m0, s39, 0xe000
	s_nop 0
	global_load_lds_dwordx4 v[222:223], off
	s_waitcnt vmcnt(8)
	s_waitcnt lgkmcnt(0)
	s_barrier
	s_waitcnt lgkmcnt(0)
	v_mfma_f32_16x16x32_bf16 v[124:127], v[158:161], v[190:193], v[124:127]
	v_mfma_f32_16x16x32_bf16 v[120:123], v[166:169], v[190:193], v[120:123]
	v_mfma_f32_16x16x32_bf16 v[108:111], v[158:161], v[198:201], v[108:111]
	v_mfma_f32_16x16x32_bf16 v[104:107], v[166:169], v[198:201], v[104:107]
	v_mfma_f32_16x16x32_bf16 v[92:95], v[158:161], v[206:209], v[92:95]
	v_mfma_f32_16x16x32_bf16 v[88:91], v[166:169], v[206:209], v[88:91]
	v_mfma_f32_16x16x32_bf16 v[76:79], v[158:161], v[214:217], v[76:79]
	v_mfma_f32_16x16x32_bf16 v[72:75], v[166:169], v[214:217], v[72:75]
	v_mfma_f32_16x16x32_bf16 v[124:127], v[162:165], v[194:197], v[124:127]
	v_mfma_f32_16x16x32_bf16 v[120:123], v[170:173], v[194:197], v[120:123]
	v_mfma_f32_16x16x32_bf16 v[108:111], v[162:165], v[202:205], v[108:111]
	v_mfma_f32_16x16x32_bf16 v[104:107], v[170:173], v[202:205], v[104:107]
	v_mfma_f32_16x16x32_bf16 v[92:95], v[162:165], v[210:213], v[92:95]
	v_mfma_f32_16x16x32_bf16 v[88:91], v[170:173], v[210:213], v[88:91]
	v_mfma_f32_16x16x32_bf16 v[76:79], v[162:165], v[218:221], v[76:79]
	v_mfma_f32_16x16x32_bf16 v[72:75], v[170:173], v[218:221], v[72:75]
	v_mfma_f32_16x16x32_bf16 v[116:119], v[174:177], v[190:193], v[116:119]
	v_mfma_f32_16x16x32_bf16 v[112:115], v[182:185], v[190:193], v[112:115]
	v_mfma_f32_16x16x32_bf16 v[100:103], v[174:177], v[198:201], v[100:103]
	v_mfma_f32_16x16x32_bf16 v[96:99], v[182:185], v[198:201], v[96:99]
	v_mfma_f32_16x16x32_bf16 v[84:87], v[174:177], v[206:209], v[84:87]
	v_mfma_f32_16x16x32_bf16 v[80:83], v[182:185], v[206:209], v[80:83]
	v_mfma_f32_16x16x32_bf16 v[68:71], v[174:177], v[214:217], v[68:71]
	v_mfma_f32_16x16x32_bf16 v[64:67], v[182:185], v[214:217], v[64:67]
	v_mfma_f32_16x16x32_bf16 v[116:119], v[178:181], v[194:197], v[116:119]
	v_mfma_f32_16x16x32_bf16 v[112:115], v[186:189], v[194:197], v[112:115]
	v_mfma_f32_16x16x32_bf16 v[100:103], v[178:181], v[202:205], v[100:103]
	v_mfma_f32_16x16x32_bf16 v[96:99], v[186:189], v[202:205], v[96:99]
	v_mfma_f32_16x16x32_bf16 v[84:87], v[178:181], v[210:213], v[84:87]
	v_mfma_f32_16x16x32_bf16 v[80:83], v[186:189], v[210:213], v[80:83]
	v_mfma_f32_16x16x32_bf16 v[68:71], v[178:181], v[218:221], v[68:71]
	v_mfma_f32_16x16x32_bf16 v[64:67], v[186:189], v[218:221], v[64:67]
	s_barrier
	s_add_i32 s62, s47, s38
	v_lshl_add_u64 v[222:223], s[26:27], 0, v[130:131]
	s_mov_b32 m0, s62
	ds_read_b128 v[190:193], v157 offset:16384
	ds_read_b128 v[194:197], v157 offset:17408
	ds_read_b128 v[198:201], v157 offset:18432
	ds_read_b128 v[202:205], v157 offset:19456
	ds_read_b128 v[206:209], v157 offset:20480
	ds_read_b128 v[210:213], v157 offset:21504
	ds_read_b128 v[214:217], v157 offset:22528
	ds_read_b128 v[218:221], v157 offset:23552
	global_load_lds_dwordx4 v[222:223], off
	s_add_i32 m0, s62, 0x2000
	s_add_u32 s62, s26, 0x80000
	v_lshl_add_u64 v[224:225], s[26:27], 0, v[134:135]
	s_addc_u32 s63, s27, 0
	s_add_i32 s64, s54, s38
	global_load_lds_dwordx4 v[224:225], off
	v_lshl_add_u64 v[226:227], s[62:63], 0, v[130:131]
	s_mov_b32 m0, s64
	v_lshl_add_u64 v[228:229], s[36:37], 0, v[132:133]
	global_load_lds_dwordx4 v[226:227], off
	v_lshl_add_u64 v[226:227], s[62:63], 0, v[134:135]
	s_add_i32 m0, s64, 0x2000
	s_nop 0
	global_load_lds_dwordx4 v[226:227], off
	v_lshl_add_u64 v[226:227], s[36:37], 0, v[128:129]
	s_mov_b32 m0, s39
	s_nop 0
	global_load_lds_dwordx4 v[226:227], off
	s_mov_b32 m0, s40
	s_nop 0
	global_load_lds_dwordx4 v[228:229], off
	s_waitcnt vmcnt(8)
	s_waitcnt lgkmcnt(0)
	s_barrier
	s_waitcnt lgkmcnt(0)
	v_mfma_f32_16x16x32_bf16 v[60:63], v[158:161], v[190:193], v[60:63]
	v_mfma_f32_16x16x32_bf16 v[56:59], v[166:169], v[190:193], v[56:59]
	v_mfma_f32_16x16x32_bf16 v[44:47], v[158:161], v[198:201], v[44:47]
	v_mfma_f32_16x16x32_bf16 v[40:43], v[166:169], v[198:201], v[40:43]
	v_mfma_f32_16x16x32_bf16 v[28:31], v[158:161], v[206:209], v[28:31]
	v_mfma_f32_16x16x32_bf16 v[24:27], v[166:169], v[206:209], v[24:27]
	v_mfma_f32_16x16x32_bf16 v[12:15], v[158:161], v[214:217], v[12:15]
	v_mfma_f32_16x16x32_bf16 v[8:11], v[166:169], v[214:217], v[8:11]
	v_mfma_f32_16x16x32_bf16 v[60:63], v[162:165], v[194:197], v[60:63]
	v_mfma_f32_16x16x32_bf16 v[56:59], v[170:173], v[194:197], v[56:59]
	v_mfma_f32_16x16x32_bf16 v[44:47], v[162:165], v[202:205], v[44:47]
	v_mfma_f32_16x16x32_bf16 v[40:43], v[170:173], v[202:205], v[40:43]
	v_mfma_f32_16x16x32_bf16 v[28:31], v[162:165], v[210:213], v[28:31]
	v_mfma_f32_16x16x32_bf16 v[24:27], v[170:173], v[210:213], v[24:27]
	v_mfma_f32_16x16x32_bf16 v[12:15], v[162:165], v[218:221], v[12:15]
	v_mfma_f32_16x16x32_bf16 v[8:11], v[170:173], v[218:221], v[8:11]
	v_mfma_f32_16x16x32_bf16 v[52:55], v[174:177], v[190:193], v[52:55]
	v_mfma_f32_16x16x32_bf16 v[48:51], v[182:185], v[190:193], v[48:51]
	v_mfma_f32_16x16x32_bf16 v[36:39], v[174:177], v[198:201], v[36:39]
	v_mfma_f32_16x16x32_bf16 v[32:35], v[182:185], v[198:201], v[32:35]
	v_mfma_f32_16x16x32_bf16 v[20:23], v[174:177], v[206:209], v[20:23]
	v_mfma_f32_16x16x32_bf16 v[16:19], v[182:185], v[206:209], v[16:19]
	v_mfma_f32_16x16x32_bf16 v[4:7], v[174:177], v[214:217], v[4:7]
	v_mfma_f32_16x16x32_bf16 v[0:3], v[182:185], v[214:217], v[0:3]
	v_mfma_f32_16x16x32_bf16 v[52:55], v[178:181], v[194:197], v[52:55]
	v_mfma_f32_16x16x32_bf16 v[48:51], v[186:189], v[194:197], v[48:51]
	v_mfma_f32_16x16x32_bf16 v[36:39], v[178:181], v[202:205], v[36:39]
	v_mfma_f32_16x16x32_bf16 v[32:35], v[186:189], v[202:205], v[32:35]
	v_mfma_f32_16x16x32_bf16 v[20:23], v[178:181], v[210:213], v[20:23]
	v_mfma_f32_16x16x32_bf16 v[16:19], v[186:189], v[210:213], v[16:19]
	v_mfma_f32_16x16x32_bf16 v[4:7], v[178:181], v[218:221], v[4:7]
	v_mfma_f32_16x16x32_bf16 v[0:3], v[186:189], v[218:221], v[0:3]
	s_barrier
	s_add_i32 s62, 0, 0x18000
	s_add_i32 s63, 0, 0x1c000
	v_add_u32_e32 v170, s62, v154
	v_add_u32_e32 v186, s63, v154
	ds_read_b128 v[158:161], v170
	ds_read_b128 v[162:165], v170 offset:1024
	ds_read_b128 v[166:169], v170 offset:2048
	ds_read_b128 v[170:173], v170 offset:3072
	ds_read_b128 v[174:177], v186
	ds_read_b128 v[178:181], v186 offset:1024
	ds_read_b128 v[182:185], v186 offset:2048
	ds_read_b128 v[186:189], v186 offset:3072
	s_add_u32 s36, s36, 0x80000
	s_addc_u32 s37, s37, 0
	s_mov_b32 m0, s41
	v_lshl_add_u64 v[232:233], s[36:37], 0, v[128:129]
	ds_read_b128 v[190:193], v157 offset:32768
	ds_read_b128 v[194:197], v157 offset:33792
	ds_read_b128 v[198:201], v157 offset:34816
	ds_read_b128 v[202:205], v157 offset:35840
	ds_read_b128 v[206:209], v157 offset:36864
	ds_read_b128 v[210:213], v157 offset:37888
	ds_read_b128 v[214:217], v157 offset:38912
	ds_read_b128 v[218:221], v157 offset:39936
	global_load_lds_dwordx4 v[232:233], off
	v_lshl_add_u64 v[232:233], s[36:37], 0, v[132:133]
	s_mov_b32 m0, s42
	s_nop 0
	global_load_lds_dwordx4 v[232:233], off
	s_waitcnt vmcnt(8)
	s_waitcnt lgkmcnt(0)
	s_barrier
	s_waitcnt lgkmcnt(0)
	v_mfma_f32_16x16x32_bf16 v[124:127], v[158:161], v[190:193], v[124:127]
	v_mfma_f32_16x16x32_bf16 v[120:123], v[166:169], v[190:193], v[120:123]
	v_mfma_f32_16x16x32_bf16 v[108:111], v[158:161], v[198:201], v[108:111]
	v_mfma_f32_16x16x32_bf16 v[104:107], v[166:169], v[198:201], v[104:107]
	v_mfma_f32_16x16x32_bf16 v[92:95], v[158:161], v[206:209], v[92:95]
	v_mfma_f32_16x16x32_bf16 v[88:91], v[166:169], v[206:209], v[88:91]
	v_mfma_f32_16x16x32_bf16 v[76:79], v[158:161], v[214:217], v[76:79]
	v_mfma_f32_16x16x32_bf16 v[72:75], v[166:169], v[214:217], v[72:75]
	v_mfma_f32_16x16x32_bf16 v[124:127], v[162:165], v[194:197], v[124:127]
	v_mfma_f32_16x16x32_bf16 v[120:123], v[170:173], v[194:197], v[120:123]
	v_mfma_f32_16x16x32_bf16 v[108:111], v[162:165], v[202:205], v[108:111]
	v_mfma_f32_16x16x32_bf16 v[104:107], v[170:173], v[202:205], v[104:107]
	v_mfma_f32_16x16x32_bf16 v[92:95], v[162:165], v[210:213], v[92:95]
	v_mfma_f32_16x16x32_bf16 v[88:91], v[170:173], v[210:213], v[88:91]
	v_mfma_f32_16x16x32_bf16 v[76:79], v[162:165], v[218:221], v[76:79]
	v_mfma_f32_16x16x32_bf16 v[72:75], v[170:173], v[218:221], v[72:75]
	v_mfma_f32_16x16x32_bf16 v[116:119], v[174:177], v[190:193], v[116:119]
	v_mfma_f32_16x16x32_bf16 v[112:115], v[182:185], v[190:193], v[112:115]
	v_mfma_f32_16x16x32_bf16 v[100:103], v[174:177], v[198:201], v[100:103]
	v_mfma_f32_16x16x32_bf16 v[96:99], v[182:185], v[198:201], v[96:99]
	v_mfma_f32_16x16x32_bf16 v[84:87], v[174:177], v[206:209], v[84:87]
	v_mfma_f32_16x16x32_bf16 v[80:83], v[182:185], v[206:209], v[80:83]
	v_mfma_f32_16x16x32_bf16 v[68:71], v[174:177], v[214:217], v[68:71]
	v_mfma_f32_16x16x32_bf16 v[64:67], v[182:185], v[214:217], v[64:67]
	v_mfma_f32_16x16x32_bf16 v[116:119], v[178:181], v[194:197], v[116:119]
	v_mfma_f32_16x16x32_bf16 v[112:115], v[186:189], v[194:197], v[112:115]
	v_mfma_f32_16x16x32_bf16 v[100:103], v[178:181], v[202:205], v[100:103]
	v_mfma_f32_16x16x32_bf16 v[96:99], v[186:189], v[202:205], v[96:99]
	v_mfma_f32_16x16x32_bf16 v[84:87], v[178:181], v[210:213], v[84:87]
	v_mfma_f32_16x16x32_bf16 v[80:83], v[186:189], v[210:213], v[80:83]
	v_mfma_f32_16x16x32_bf16 v[68:71], v[178:181], v[218:221], v[68:71]
	v_mfma_f32_16x16x32_bf16 v[64:67], v[186:189], v[218:221], v[64:67]
	s_barrier
	s_add_i32 s36, s62, s38
	v_lshl_add_u64 v[222:223], v[222:223], 0, s[14:15]
	s_mov_b32 m0, s36
	ds_read_b128 v[190:193], v157 offset:49152
	ds_read_b128 v[194:197], v157 offset:50176
	ds_read_b128 v[198:201], v157 offset:51200
	ds_read_b128 v[202:205], v157 offset:52224
	ds_read_b128 v[206:209], v157 offset:53248
	ds_read_b128 v[210:213], v157 offset:54272
	ds_read_b128 v[214:217], v157 offset:55296
	ds_read_b128 v[218:221], v157 offset:56320
	global_load_lds_dwordx4 v[222:223], off
	s_add_i32 m0, s36, 0x2000
	s_add_u32 s26, s26, 0x80080
	v_lshl_add_u64 v[222:223], v[224:225], 0, s[14:15]
	s_addc_u32 s27, s27, 0
	s_add_i32 s36, s63, s38
	global_load_lds_dwordx4 v[222:223], off
	v_lshl_add_u64 v[222:223], s[26:27], 0, v[130:131]
	s_mov_b32 m0, s36
	s_nop 0
	global_load_lds_dwordx4 v[222:223], off
	v_lshl_add_u64 v[222:223], s[26:27], 0, v[134:135]
	s_add_i32 m0, s36, 0x2000
	s_nop 0
	global_load_lds_dwordx4 v[222:223], off
	v_lshl_add_u64 v[222:223], v[226:227], 0, s[14:15]
	s_mov_b32 m0, s45
	s_nop 0
	global_load_lds_dwordx4 v[222:223], off
	v_lshl_add_u64 v[222:223], v[228:229], 0, s[14:15]
	s_mov_b32 m0, s46
	s_nop 0
	global_load_lds_dwordx4 v[222:223], off
	s_waitcnt vmcnt(8)
	s_waitcnt lgkmcnt(0)
	s_barrier
	s_waitcnt lgkmcnt(0)
	v_mfma_f32_16x16x32_bf16 v[60:63], v[158:161], v[190:193], v[60:63]
	v_mfma_f32_16x16x32_bf16 v[56:59], v[166:169], v[190:193], v[56:59]
	v_mfma_f32_16x16x32_bf16 v[44:47], v[158:161], v[198:201], v[44:47]
	v_mfma_f32_16x16x32_bf16 v[40:43], v[166:169], v[198:201], v[40:43]
	v_mfma_f32_16x16x32_bf16 v[28:31], v[158:161], v[206:209], v[28:31]
	v_mfma_f32_16x16x32_bf16 v[24:27], v[166:169], v[206:209], v[24:27]
	v_mfma_f32_16x16x32_bf16 v[12:15], v[158:161], v[214:217], v[12:15]
	v_mfma_f32_16x16x32_bf16 v[8:11], v[166:169], v[214:217], v[8:11]
	v_mfma_f32_16x16x32_bf16 v[60:63], v[162:165], v[194:197], v[60:63]
	v_mfma_f32_16x16x32_bf16 v[56:59], v[170:173], v[194:197], v[56:59]
	v_mfma_f32_16x16x32_bf16 v[44:47], v[162:165], v[202:205], v[44:47]
	v_mfma_f32_16x16x32_bf16 v[40:43], v[170:173], v[202:205], v[40:43]
	v_mfma_f32_16x16x32_bf16 v[28:31], v[162:165], v[210:213], v[28:31]
	v_mfma_f32_16x16x32_bf16 v[24:27], v[170:173], v[210:213], v[24:27]
	v_mfma_f32_16x16x32_bf16 v[12:15], v[162:165], v[218:221], v[12:15]
	v_mfma_f32_16x16x32_bf16 v[8:11], v[170:173], v[218:221], v[8:11]
	v_mfma_f32_16x16x32_bf16 v[52:55], v[174:177], v[190:193], v[52:55]
	v_mfma_f32_16x16x32_bf16 v[48:51], v[182:185], v[190:193], v[48:51]
	v_mfma_f32_16x16x32_bf16 v[36:39], v[174:177], v[198:201], v[36:39]
	v_mfma_f32_16x16x32_bf16 v[32:35], v[182:185], v[198:201], v[32:35]
	v_mfma_f32_16x16x32_bf16 v[20:23], v[174:177], v[206:209], v[20:23]
	v_mfma_f32_16x16x32_bf16 v[16:19], v[182:185], v[206:209], v[16:19]
	v_mfma_f32_16x16x32_bf16 v[4:7], v[174:177], v[214:217], v[4:7]
	v_mfma_f32_16x16x32_bf16 v[0:3], v[182:185], v[214:217], v[0:3]
	v_mfma_f32_16x16x32_bf16 v[52:55], v[178:181], v[194:197], v[52:55]
	v_mfma_f32_16x16x32_bf16 v[48:51], v[186:189], v[194:197], v[48:51]
	v_mfma_f32_16x16x32_bf16 v[36:39], v[178:181], v[202:205], v[36:39]
	v_mfma_f32_16x16x32_bf16 v[32:35], v[186:189], v[202:205], v[32:35]
	v_mfma_f32_16x16x32_bf16 v[20:23], v[178:181], v[210:213], v[20:23]
	v_mfma_f32_16x16x32_bf16 v[16:19], v[186:189], v[210:213], v[16:19]
	v_mfma_f32_16x16x32_bf16 v[4:7], v[178:181], v[218:221], v[4:7]
	v_mfma_f32_16x16x32_bf16 v[0:3], v[186:189], v[218:221], v[0:3]
	s_barrier
	s_add_i32 s61, s61, 2
	s_add_u32 s24, s24, 0x100
	s_addc_u32 s25, s25, 0
	s_add_u32 s59, s59, 0x100
	s_addc_u32 s60, s60, 0
	s_cmp_gt_u32 s61, 29
	s_cbranch_scc0 .LBB0_158
	s_and_b64 vcc, exec, s[16:17]
	s_cbranch_vccz .LBB0_161
	s_barrier

.LBB0_196:
	ds_read_b128 v[142:145], v165
	ds_read_b128 v[146:149], v165 offset:1024
	ds_read_b128 v[150:153], v165 offset:2048
	ds_read_b128 v[170:173], v165 offset:3072
	ds_read_b128 v[174:177], v166
	ds_read_b128 v[178:181], v166 offset:1024
	ds_read_b128 v[182:185], v166 offset:2048
	ds_read_b128 v[186:189], v166 offset:3072
	s_add_u32 s40, s6, 0xfff80080
	s_addc_u32 s41, s7, -1
	s_cmp_eq_u32 s72, 28
	s_cselect_b32 s43, s37, s41
	s_cselect_b32 s42, s36, s40
	s_cselect_b32 s41, s39, s71
	s_cselect_b32 s40, s38, s70
	v_lshl_add_u64 v[222:223], s[6:7], 0, v[136:137]
	s_add_i32 m0, s56, 0xc000
	ds_read_b128 v[190:193], v167
	ds_read_b128 v[194:197], v167 offset:1024
	ds_read_b128 v[198:201], v167 offset:2048
	ds_read_b128 v[202:205], v167 offset:3072
	ds_read_b128 v[206:209], v167 offset:4096
	ds_read_b128 v[210:213], v167 offset:5120
	ds_read_b128 v[214:217], v167 offset:6144
	ds_read_b128 v[218:221], v167 offset:7168
	global_load_lds_dwordx4 v[222:223], off
	v_lshl_add_u64 v[222:223], s[6:7], 0, v[140:141]
	s_add_i32 m0, s56, 0xe000
	s_nop 0
	global_load_lds_dwordx4 v[222:223], off
	s_waitcnt vmcnt(8)
	s_waitcnt lgkmcnt(0)
	s_barrier
	s_waitcnt lgkmcnt(0)
	v_mfma_f32_16x16x32_bf16 v[124:127], v[142:145], v[190:193], v[124:127]
	v_mfma_f32_16x16x32_bf16 v[120:123], v[150:153], v[190:193], v[120:123]
	v_mfma_f32_16x16x32_bf16 v[108:111], v[142:145], v[198:201], v[108:111]
	v_mfma_f32_16x16x32_bf16 v[104:107], v[150:153], v[198:201], v[104:107]
	v_mfma_f32_16x16x32_bf16 v[92:95], v[142:145], v[206:209], v[92:95]
	v_mfma_f32_16x16x32_bf16 v[88:91], v[150:153], v[206:209], v[88:91]
	v_mfma_f32_16x16x32_bf16 v[76:79], v[142:145], v[214:217], v[76:79]
	v_mfma_f32_16x16x32_bf16 v[72:75], v[150:153], v[214:217], v[72:75]
	v_mfma_f32_16x16x32_bf16 v[124:127], v[146:149], v[194:197], v[124:127]
	v_mfma_f32_16x16x32_bf16 v[120:123], v[170:173], v[194:197], v[120:123]
	v_mfma_f32_16x16x32_bf16 v[108:111], v[146:149], v[202:205], v[108:111]
	v_mfma_f32_16x16x32_bf16 v[104:107], v[170:173], v[202:205], v[104:107]
	v_mfma_f32_16x16x32_bf16 v[92:95], v[146:149], v[210:213], v[92:95]
	v_mfma_f32_16x16x32_bf16 v[88:91], v[170:173], v[210:213], v[88:91]
	v_mfma_f32_16x16x32_bf16 v[76:79], v[146:149], v[218:221], v[76:79]
	v_mfma_f32_16x16x32_bf16 v[72:75], v[170:173], v[218:221], v[72:75]
	v_mfma_f32_16x16x32_bf16 v[116:119], v[174:177], v[190:193], v[116:119]
	v_mfma_f32_16x16x32_bf16 v[112:115], v[182:185], v[190:193], v[112:115]
	v_mfma_f32_16x16x32_bf16 v[100:103], v[174:177], v[198:201], v[100:103]
	v_mfma_f32_16x16x32_bf16 v[96:99], v[182:185], v[198:201], v[96:99]
	v_mfma_f32_16x16x32_bf16 v[84:87], v[174:177], v[206:209], v[84:87]
	v_mfma_f32_16x16x32_bf16 v[80:83], v[182:185], v[206:209], v[80:83]
	v_mfma_f32_16x16x32_bf16 v[68:71], v[174:177], v[214:217], v[68:71]
	v_mfma_f32_16x16x32_bf16 v[64:67], v[182:185], v[214:217], v[64:67]
	v_mfma_f32_16x16x32_bf16 v[116:119], v[178:181], v[194:197], v[116:119]
	v_mfma_f32_16x16x32_bf16 v[112:115], v[186:189], v[194:197], v[112:115]
	v_mfma_f32_16x16x32_bf16 v[100:103], v[178:181], v[202:205], v[100:103]
	v_mfma_f32_16x16x32_bf16 v[96:99], v[186:189], v[202:205], v[96:99]
	v_mfma_f32_16x16x32_bf16 v[84:87], v[178:181], v[210:213], v[84:87]
	v_mfma_f32_16x16x32_bf16 v[80:83], v[186:189], v[210:213], v[80:83]
	v_mfma_f32_16x16x32_bf16 v[68:71], v[178:181], v[218:221], v[68:71]
	v_mfma_f32_16x16x32_bf16 v[64:67], v[186:189], v[218:221], v[64:67]
	s_barrier
	s_add_i32 s73, s64, s55
	v_lshl_add_u64 v[222:223], s[40:41], 0, v[130:131]
	s_mov_b32 m0, s73
	ds_read_b128 v[190:193], v167 offset:16384
	ds_read_b128 v[194:197], v167 offset:17408
	ds_read_b128 v[198:201], v167 offset:18432
	ds_read_b128 v[202:205], v167 offset:19456
	ds_read_b128 v[206:209], v167 offset:20480
	ds_read_b128 v[210:213], v167 offset:21504
	ds_read_b128 v[214:217], v167 offset:22528
	ds_read_b128 v[218:221], v167 offset:23552
	global_load_lds_dwordx4 v[222:223], off
	s_add_i32 m0, s73, 0x2000
	s_add_u32 s74, s40, 0x80000
	v_lshl_add_u64 v[224:225], s[40:41], 0, v[134:135]
	s_addc_u32 s75, s41, 0
	s_add_i32 s73, s65, s55
	global_load_lds_dwordx4 v[224:225], off
	v_lshl_add_u64 v[226:227], s[74:75], 0, v[130:131]
	s_mov_b32 m0, s73
	v_lshl_add_u64 v[228:229], s[42:43], 0, v[132:133]
	global_load_lds_dwordx4 v[226:227], off
	v_lshl_add_u64 v[226:227], s[74:75], 0, v[134:135]
	s_add_i32 m0, s73, 0x2000
	s_nop 0
	global_load_lds_dwordx4 v[226:227], off
	v_lshl_add_u64 v[226:227], s[42:43], 0, v[128:129]
	s_mov_b32 m0, s56
	s_nop 0
	global_load_lds_dwordx4 v[226:227], off
	s_mov_b32 m0, s57
	s_nop 0
	global_load_lds_dwordx4 v[228:229], off
	s_waitcnt vmcnt(8)
	s_waitcnt lgkmcnt(0)
	s_barrier
	s_waitcnt lgkmcnt(0)
	v_mfma_f32_16x16x32_bf16 v[60:63], v[142:145], v[190:193], v[60:63]
	v_mfma_f32_16x16x32_bf16 v[56:59], v[150:153], v[190:193], v[56:59]
	v_mfma_f32_16x16x32_bf16 v[44:47], v[142:145], v[198:201], v[44:47]
	v_mfma_f32_16x16x32_bf16 v[40:43], v[150:153], v[198:201], v[40:43]
	v_mfma_f32_16x16x32_bf16 v[28:31], v[142:145], v[206:209], v[28:31]
	v_mfma_f32_16x16x32_bf16 v[24:27], v[150:153], v[206:209], v[24:27]
	v_mfma_f32_16x16x32_bf16 v[12:15], v[142:145], v[214:217], v[12:15]
	v_mfma_f32_16x16x32_bf16 v[8:11], v[150:153], v[214:217], v[8:11]
	v_mfma_f32_16x16x32_bf16 v[60:63], v[146:149], v[194:197], v[60:63]
	v_mfma_f32_16x16x32_bf16 v[56:59], v[170:173], v[194:197], v[56:59]
	v_mfma_f32_16x16x32_bf16 v[44:47], v[146:149], v[202:205], v[44:47]
	v_mfma_f32_16x16x32_bf16 v[40:43], v[170:173], v[202:205], v[40:43]
	v_mfma_f32_16x16x32_bf16 v[28:31], v[146:149], v[210:213], v[28:31]
	v_mfma_f32_16x16x32_bf16 v[24:27], v[170:173], v[210:213], v[24:27]
	v_mfma_f32_16x16x32_bf16 v[12:15], v[146:149], v[218:221], v[12:15]
	v_mfma_f32_16x16x32_bf16 v[8:11], v[170:173], v[218:221], v[8:11]
	v_mfma_f32_16x16x32_bf16 v[52:55], v[174:177], v[190:193], v[52:55]
	v_mfma_f32_16x16x32_bf16 v[48:51], v[182:185], v[190:193], v[48:51]
	v_mfma_f32_16x16x32_bf16 v[36:39], v[174:177], v[198:201], v[36:39]
	v_mfma_f32_16x16x32_bf16 v[32:35], v[182:185], v[198:201], v[32:35]
	v_mfma_f32_16x16x32_bf16 v[20:23], v[174:177], v[206:209], v[20:23]
	v_mfma_f32_16x16x32_bf16 v[16:19], v[182:185], v[206:209], v[16:19]
	v_mfma_f32_16x16x32_bf16 v[4:7], v[174:177], v[214:217], v[4:7]
	v_mfma_f32_16x16x32_bf16 v[0:3], v[182:185], v[214:217], v[0:3]
	v_mfma_f32_16x16x32_bf16 v[52:55], v[178:181], v[194:197], v[52:55]
	v_mfma_f32_16x16x32_bf16 v[48:51], v[186:189], v[194:197], v[48:51]
	v_mfma_f32_16x16x32_bf16 v[36:39], v[178:181], v[202:205], v[36:39]
	v_mfma_f32_16x16x32_bf16 v[32:35], v[186:189], v[202:205], v[32:35]
	v_mfma_f32_16x16x32_bf16 v[20:23], v[178:181], v[210:213], v[20:23]
	v_mfma_f32_16x16x32_bf16 v[16:19], v[186:189], v[210:213], v[16:19]
	v_mfma_f32_16x16x32_bf16 v[4:7], v[178:181], v[218:221], v[4:7]
	v_mfma_f32_16x16x32_bf16 v[0:3], v[186:189], v[218:221], v[0:3]
	s_barrier
	s_add_i32 s73, 0, 0x18000
	v_add_u32_e32 v138, s73, v155
	s_add_i32 s74, 0, 0x1c000
	ds_read_b128 v[142:145], v138
	ds_read_b128 v[146:149], v138 offset:1024
	ds_read_b128 v[150:153], v138 offset:2048
	ds_read_b128 v[170:173], v138 offset:3072
	v_add_u32_e32 v138, s74, v155
	ds_read_b128 v[174:177], v138
	ds_read_b128 v[178:181], v138 offset:1024
	ds_read_b128 v[182:185], v138 offset:2048
	ds_read_b128 v[186:189], v138 offset:3072
	s_add_u32 s42, s42, 0x80000
	s_addc_u32 s43, s43, 0
	s_mov_b32 m0, s58
	v_lshl_add_u64 v[232:233], s[42:43], 0, v[128:129]
	ds_read_b128 v[190:193], v167 offset:32768
	ds_read_b128 v[194:197], v167 offset:33792
	ds_read_b128 v[198:201], v167 offset:34816
	ds_read_b128 v[202:205], v167 offset:35840
	ds_read_b128 v[206:209], v167 offset:36864
	ds_read_b128 v[210:213], v167 offset:37888
	ds_read_b128 v[214:217], v167 offset:38912
	ds_read_b128 v[218:221], v167 offset:39936
	global_load_lds_dwordx4 v[232:233], off
	v_lshl_add_u64 v[232:233], s[42:43], 0, v[132:133]
	s_mov_b32 m0, s59
	s_nop 0
	global_load_lds_dwordx4 v[232:233], off
	s_waitcnt vmcnt(8)
	s_waitcnt lgkmcnt(0)
	s_barrier
	s_waitcnt lgkmcnt(0)
	v_mfma_f32_16x16x32_bf16 v[124:127], v[142:145], v[190:193], v[124:127]
	v_mfma_f32_16x16x32_bf16 v[120:123], v[150:153], v[190:193], v[120:123]
	v_mfma_f32_16x16x32_bf16 v[108:111], v[142:145], v[198:201], v[108:111]
	v_mfma_f32_16x16x32_bf16 v[104:107], v[150:153], v[198:201], v[104:107]
	v_mfma_f32_16x16x32_bf16 v[92:95], v[142:145], v[206:209], v[92:95]
	v_mfma_f32_16x16x32_bf16 v[88:91], v[150:153], v[206:209], v[88:91]
	v_mfma_f32_16x16x32_bf16 v[76:79], v[142:145], v[214:217], v[76:79]
	v_mfma_f32_16x16x32_bf16 v[72:75], v[150:153], v[214:217], v[72:75]
	v_mfma_f32_16x16x32_bf16 v[124:127], v[146:149], v[194:197], v[124:127]
	v_mfma_f32_16x16x32_bf16 v[120:123], v[170:173], v[194:197], v[120:123]
	v_mfma_f32_16x16x32_bf16 v[108:111], v[146:149], v[202:205], v[108:111]
	v_mfma_f32_16x16x32_bf16 v[104:107], v[170:173], v[202:205], v[104:107]
	v_mfma_f32_16x16x32_bf16 v[92:95], v[146:149], v[210:213], v[92:95]
	v_mfma_f32_16x16x32_bf16 v[88:91], v[170:173], v[210:213], v[88:91]
	v_mfma_f32_16x16x32_bf16 v[76:79], v[146:149], v[218:221], v[76:79]
	v_mfma_f32_16x16x32_bf16 v[72:75], v[170:173], v[218:221], v[72:75]
	v_mfma_f32_16x16x32_bf16 v[116:119], v[174:177], v[190:193], v[116:119]
	v_mfma_f32_16x16x32_bf16 v[112:115], v[182:185], v[190:193], v[112:115]
	v_mfma_f32_16x16x32_bf16 v[100:103], v[174:177], v[198:201], v[100:103]
	v_mfma_f32_16x16x32_bf16 v[96:99], v[182:185], v[198:201], v[96:99]
	v_mfma_f32_16x16x32_bf16 v[84:87], v[174:177], v[206:209], v[84:87]
	v_mfma_f32_16x16x32_bf16 v[80:83], v[182:185], v[206:209], v[80:83]
	v_mfma_f32_16x16x32_bf16 v[68:71], v[174:177], v[214:217], v[68:71]
	v_mfma_f32_16x16x32_bf16 v[64:67], v[182:185], v[214:217], v[64:67]
	v_mfma_f32_16x16x32_bf16 v[116:119], v[178:181], v[194:197], v[116:119]
	v_mfma_f32_16x16x32_bf16 v[112:115], v[186:189], v[194:197], v[112:115]
	v_mfma_f32_16x16x32_bf16 v[100:103], v[178:181], v[202:205], v[100:103]
	v_mfma_f32_16x16x32_bf16 v[96:99], v[186:189], v[202:205], v[96:99]
	v_mfma_f32_16x16x32_bf16 v[84:87], v[178:181], v[210:213], v[84:87]
	v_mfma_f32_16x16x32_bf16 v[80:83], v[186:189], v[210:213], v[80:83]
	v_mfma_f32_16x16x32_bf16 v[68:71], v[178:181], v[218:221], v[68:71]
	v_mfma_f32_16x16x32_bf16 v[64:67], v[186:189], v[218:221], v[64:67]
	s_barrier
	s_add_i32 s42, s73, s55
	v_lshl_add_u64 v[222:223], v[222:223], 0, s[20:21]
	s_mov_b32 m0, s42
	ds_read_b128 v[190:193], v167 offset:49152
	ds_read_b128 v[194:197], v167 offset:50176
	ds_read_b128 v[198:201], v167 offset:51200
	ds_read_b128 v[202:205], v167 offset:52224
	ds_read_b128 v[206:209], v167 offset:53248
	ds_read_b128 v[210:213], v167 offset:54272
	ds_read_b128 v[214:217], v167 offset:55296
	ds_read_b128 v[218:221], v167 offset:56320
	global_load_lds_dwordx4 v[222:223], off
	s_add_i32 m0, s42, 0x2000
	s_add_u32 s40, s40, 0x80080
	v_lshl_add_u64 v[222:223], v[224:225], 0, s[20:21]
	s_addc_u32 s41, s41, 0
	s_add_i32 s42, s74, s55
	global_load_lds_dwordx4 v[222:223], off
	v_lshl_add_u64 v[222:223], s[40:41], 0, v[130:131]
	s_mov_b32 m0, s42
	s_nop 0
	global_load_lds_dwordx4 v[222:223], off
	v_lshl_add_u64 v[222:223], s[40:41], 0, v[134:135]
	s_add_i32 m0, s42, 0x2000
	s_nop 0
	global_load_lds_dwordx4 v[222:223], off
	v_lshl_add_u64 v[222:223], v[226:227], 0, s[20:21]
	s_mov_b32 m0, s62
	s_nop 0
	global_load_lds_dwordx4 v[222:223], off
	v_lshl_add_u64 v[222:223], v[228:229], 0, s[20:21]
	s_mov_b32 m0, s63
	s_nop 0
	global_load_lds_dwordx4 v[222:223], off
	s_waitcnt vmcnt(8)
	s_waitcnt lgkmcnt(0)
	s_barrier
	s_waitcnt lgkmcnt(0)
	v_mfma_f32_16x16x32_bf16 v[60:63], v[142:145], v[190:193], v[60:63]
	v_mfma_f32_16x16x32_bf16 v[56:59], v[150:153], v[190:193], v[56:59]
	v_mfma_f32_16x16x32_bf16 v[44:47], v[142:145], v[198:201], v[44:47]
	v_mfma_f32_16x16x32_bf16 v[40:43], v[150:153], v[198:201], v[40:43]
	v_mfma_f32_16x16x32_bf16 v[28:31], v[142:145], v[206:209], v[28:31]
	v_mfma_f32_16x16x32_bf16 v[24:27], v[150:153], v[206:209], v[24:27]
	v_mfma_f32_16x16x32_bf16 v[12:15], v[142:145], v[214:217], v[12:15]
	v_mfma_f32_16x16x32_bf16 v[8:11], v[150:153], v[214:217], v[8:11]
	v_mfma_f32_16x16x32_bf16 v[60:63], v[146:149], v[194:197], v[60:63]
	v_mfma_f32_16x16x32_bf16 v[56:59], v[170:173], v[194:197], v[56:59]
	v_mfma_f32_16x16x32_bf16 v[44:47], v[146:149], v[202:205], v[44:47]
	v_mfma_f32_16x16x32_bf16 v[40:43], v[170:173], v[202:205], v[40:43]
	v_mfma_f32_16x16x32_bf16 v[28:31], v[146:149], v[210:213], v[28:31]
	v_mfma_f32_16x16x32_bf16 v[24:27], v[170:173], v[210:213], v[24:27]
	v_mfma_f32_16x16x32_bf16 v[12:15], v[146:149], v[218:221], v[12:15]
	v_mfma_f32_16x16x32_bf16 v[8:11], v[170:173], v[218:221], v[8:11]
	v_mfma_f32_16x16x32_bf16 v[52:55], v[174:177], v[190:193], v[52:55]
	v_mfma_f32_16x16x32_bf16 v[48:51], v[182:185], v[190:193], v[48:51]
	v_mfma_f32_16x16x32_bf16 v[36:39], v[174:177], v[198:201], v[36:39]
	v_mfma_f32_16x16x32_bf16 v[32:35], v[182:185], v[198:201], v[32:35]
	v_mfma_f32_16x16x32_bf16 v[20:23], v[174:177], v[206:209], v[20:23]
	v_mfma_f32_16x16x32_bf16 v[16:19], v[182:185], v[206:209], v[16:19]
	v_mfma_f32_16x16x32_bf16 v[4:7], v[174:177], v[214:217], v[4:7]
	v_mfma_f32_16x16x32_bf16 v[0:3], v[182:185], v[214:217], v[0:3]
	v_mfma_f32_16x16x32_bf16 v[52:55], v[178:181], v[194:197], v[52:55]
	v_mfma_f32_16x16x32_bf16 v[48:51], v[186:189], v[194:197], v[48:51]
	v_mfma_f32_16x16x32_bf16 v[36:39], v[178:181], v[202:205], v[36:39]
	v_mfma_f32_16x16x32_bf16 v[32:35], v[186:189], v[202:205], v[32:35]
	v_mfma_f32_16x16x32_bf16 v[20:23], v[178:181], v[210:213], v[20:23]
	v_mfma_f32_16x16x32_bf16 v[16:19], v[186:189], v[210:213], v[16:19]
	v_mfma_f32_16x16x32_bf16 v[4:7], v[178:181], v[218:221], v[4:7]
	v_mfma_f32_16x16x32_bf16 v[0:3], v[186:189], v[218:221], v[0:3]
	s_barrier
	s_add_i32 s72, s72, 2
	s_add_u32 s6, s6, 0x100
	s_addc_u32 s7, s7, 0
	s_add_u32 s70, s70, 0x100
	s_addc_u32 s71, s71, 0
	s_cmp_gt_u32 s72, 29
	s_cbranch_scc0 .LBB0_196
	s_and_b64 vcc, exec, s[22:23]
	s_cbranch_vccz .LBB0_199
	s_barrier

.LBB0_335:
	ds_read_b128 v[146:149], v156
	ds_read_b128 v[160:163], v156 offset:1024
	ds_read_b128 v[164:167], v156 offset:2048
	ds_read_b128 v[168:171], v156 offset:3072
	ds_read_b128 v[172:175], v157
	ds_read_b128 v[176:179], v157 offset:1024
	ds_read_b128 v[180:183], v157 offset:2048
	ds_read_b128 v[184:187], v157 offset:3072
	s_add_u32 s24, s22, 0xffea0080
	s_addc_u32 s25, s23, -1
	s_cmpk_eq_i32 s61, 0x54
	s_cselect_b32 s27, s19, s25
	s_cselect_b32 s26, s18, s24
	s_cselect_b32 s25, s21, s60
	s_cselect_b32 s24, s20, s59
	v_lshl_add_u64 v[220:221], s[22:23], 0, v[136:137]
	s_add_i32 m0, s36, 0xc000
	ds_read_b128 v[188:191], v158
	ds_read_b128 v[192:195], v158 offset:1024
	ds_read_b128 v[196:199], v158 offset:2048
	ds_read_b128 v[200:203], v158 offset:3072
	ds_read_b128 v[204:207], v158 offset:4096
	ds_read_b128 v[208:211], v158 offset:5120
	ds_read_b128 v[212:215], v158 offset:6144
	ds_read_b128 v[216:219], v158 offset:7168
	global_load_lds_dwordx4 v[220:221], off
	v_lshl_add_u64 v[220:221], s[22:23], 0, v[140:141]
	s_add_i32 m0, s36, 0xe000
	s_nop 0
	global_load_lds_dwordx4 v[220:221], off
	s_waitcnt vmcnt(8)
	s_waitcnt lgkmcnt(0)
	s_barrier
	s_waitcnt lgkmcnt(0)
	v_mfma_f32_16x16x32_bf16 v[124:127], v[146:149], v[188:191], v[124:127]
	v_mfma_f32_16x16x32_bf16 v[120:123], v[164:167], v[188:191], v[120:123]
	v_mfma_f32_16x16x32_bf16 v[108:111], v[146:149], v[196:199], v[108:111]
	v_mfma_f32_16x16x32_bf16 v[104:107], v[164:167], v[196:199], v[104:107]
	v_mfma_f32_16x16x32_bf16 v[92:95], v[146:149], v[204:207], v[92:95]
	v_mfma_f32_16x16x32_bf16 v[88:91], v[164:167], v[204:207], v[88:91]
	v_mfma_f32_16x16x32_bf16 v[76:79], v[146:149], v[212:215], v[76:79]
	v_mfma_f32_16x16x32_bf16 v[72:75], v[164:167], v[212:215], v[72:75]
	v_mfma_f32_16x16x32_bf16 v[124:127], v[160:163], v[192:195], v[124:127]
	v_mfma_f32_16x16x32_bf16 v[120:123], v[168:171], v[192:195], v[120:123]
	v_mfma_f32_16x16x32_bf16 v[108:111], v[160:163], v[200:203], v[108:111]
	v_mfma_f32_16x16x32_bf16 v[104:107], v[168:171], v[200:203], v[104:107]
	v_mfma_f32_16x16x32_bf16 v[92:95], v[160:163], v[208:211], v[92:95]
	v_mfma_f32_16x16x32_bf16 v[88:91], v[168:171], v[208:211], v[88:91]
	v_mfma_f32_16x16x32_bf16 v[76:79], v[160:163], v[216:219], v[76:79]
	v_mfma_f32_16x16x32_bf16 v[72:75], v[168:171], v[216:219], v[72:75]
	v_mfma_f32_16x16x32_bf16 v[116:119], v[172:175], v[188:191], v[116:119]
	v_mfma_f32_16x16x32_bf16 v[112:115], v[180:183], v[188:191], v[112:115]
	v_mfma_f32_16x16x32_bf16 v[100:103], v[172:175], v[196:199], v[100:103]
	v_mfma_f32_16x16x32_bf16 v[96:99], v[180:183], v[196:199], v[96:99]
	v_mfma_f32_16x16x32_bf16 v[84:87], v[172:175], v[204:207], v[84:87]
	v_mfma_f32_16x16x32_bf16 v[80:83], v[180:183], v[204:207], v[80:83]
	v_mfma_f32_16x16x32_bf16 v[68:71], v[172:175], v[212:215], v[68:71]
	v_mfma_f32_16x16x32_bf16 v[64:67], v[180:183], v[212:215], v[64:67]
	v_mfma_f32_16x16x32_bf16 v[116:119], v[176:179], v[192:195], v[116:119]
	v_mfma_f32_16x16x32_bf16 v[112:115], v[184:187], v[192:195], v[112:115]
	v_mfma_f32_16x16x32_bf16 v[100:103], v[176:179], v[200:203], v[100:103]
	v_mfma_f32_16x16x32_bf16 v[96:99], v[184:187], v[200:203], v[96:99]
	v_mfma_f32_16x16x32_bf16 v[84:87], v[176:179], v[208:211], v[84:87]
	v_mfma_f32_16x16x32_bf16 v[80:83], v[184:187], v[208:211], v[80:83]
	v_mfma_f32_16x16x32_bf16 v[68:71], v[176:179], v[216:219], v[68:71]
	v_mfma_f32_16x16x32_bf16 v[64:67], v[184:187], v[216:219], v[64:67]
	s_barrier
	s_add_i32 s65, s43, s17
	v_lshl_add_u64 v[220:221], s[24:25], 0, v[130:131]
	s_mov_b32 m0, s65
	ds_read_b128 v[188:191], v158 offset:16384
	ds_read_b128 v[192:195], v158 offset:17408
	ds_read_b128 v[196:199], v158 offset:18432
	ds_read_b128 v[200:203], v158 offset:19456
	ds_read_b128 v[204:207], v158 offset:20480
	ds_read_b128 v[208:211], v158 offset:21504
	ds_read_b128 v[212:215], v158 offset:22528
	ds_read_b128 v[216:219], v158 offset:23552
	global_load_lds_dwordx4 v[220:221], off
	s_add_i32 m0, s65, 0x2000
	s_add_u32 s66, s24, 0x160000
	v_lshl_add_u64 v[222:223], s[24:25], 0, v[134:135]
	s_addc_u32 s67, s25, 0
	s_add_i32 s65, s44, s17
	global_load_lds_dwordx4 v[222:223], off
	v_lshl_add_u64 v[224:225], s[66:67], 0, v[130:131]
	s_mov_b32 m0, s65
	v_lshl_add_u64 v[226:227], s[26:27], 0, v[132:133]
	global_load_lds_dwordx4 v[224:225], off
	v_lshl_add_u64 v[224:225], s[66:67], 0, v[134:135]
	s_add_i32 m0, s65, 0x2000
	s_nop 0
	global_load_lds_dwordx4 v[224:225], off
	v_lshl_add_u64 v[224:225], s[26:27], 0, v[128:129]
	s_mov_b32 m0, s36
	s_nop 0
	global_load_lds_dwordx4 v[224:225], off
	s_mov_b32 m0, s37
	s_nop 0
	global_load_lds_dwordx4 v[226:227], off
	s_waitcnt vmcnt(8)
	s_waitcnt lgkmcnt(0)
	s_barrier
	s_waitcnt lgkmcnt(0)
	v_mfma_f32_16x16x32_bf16 v[60:63], v[146:149], v[188:191], v[60:63]
	v_mfma_f32_16x16x32_bf16 v[56:59], v[164:167], v[188:191], v[56:59]
	v_mfma_f32_16x16x32_bf16 v[44:47], v[146:149], v[196:199], v[44:47]
	v_mfma_f32_16x16x32_bf16 v[40:43], v[164:167], v[196:199], v[40:43]
	v_mfma_f32_16x16x32_bf16 v[28:31], v[146:149], v[204:207], v[28:31]
	v_mfma_f32_16x16x32_bf16 v[24:27], v[164:167], v[204:207], v[24:27]
	v_mfma_f32_16x16x32_bf16 v[12:15], v[146:149], v[212:215], v[12:15]
	v_mfma_f32_16x16x32_bf16 v[8:11], v[164:167], v[212:215], v[8:11]
	v_mfma_f32_16x16x32_bf16 v[60:63], v[160:163], v[192:195], v[60:63]
	v_mfma_f32_16x16x32_bf16 v[56:59], v[168:171], v[192:195], v[56:59]
	v_mfma_f32_16x16x32_bf16 v[44:47], v[160:163], v[200:203], v[44:47]
	v_mfma_f32_16x16x32_bf16 v[40:43], v[168:171], v[200:203], v[40:43]
	v_mfma_f32_16x16x32_bf16 v[28:31], v[160:163], v[208:211], v[28:31]
	v_mfma_f32_16x16x32_bf16 v[24:27], v[168:171], v[208:211], v[24:27]
	v_mfma_f32_16x16x32_bf16 v[12:15], v[160:163], v[216:219], v[12:15]
	v_mfma_f32_16x16x32_bf16 v[8:11], v[168:171], v[216:219], v[8:11]
	v_mfma_f32_16x16x32_bf16 v[52:55], v[172:175], v[188:191], v[52:55]
	v_mfma_f32_16x16x32_bf16 v[48:51], v[180:183], v[188:191], v[48:51]
	v_mfma_f32_16x16x32_bf16 v[36:39], v[172:175], v[196:199], v[36:39]
	v_mfma_f32_16x16x32_bf16 v[32:35], v[180:183], v[196:199], v[32:35]
	v_mfma_f32_16x16x32_bf16 v[20:23], v[172:175], v[204:207], v[20:23]
	v_mfma_f32_16x16x32_bf16 v[16:19], v[180:183], v[204:207], v[16:19]
	v_mfma_f32_16x16x32_bf16 v[4:7], v[172:175], v[212:215], v[4:7]
	v_mfma_f32_16x16x32_bf16 v[0:3], v[180:183], v[212:215], v[0:3]
	v_mfma_f32_16x16x32_bf16 v[52:55], v[176:179], v[192:195], v[52:55]
	v_mfma_f32_16x16x32_bf16 v[48:51], v[184:187], v[192:195], v[48:51]
	v_mfma_f32_16x16x32_bf16 v[36:39], v[176:179], v[200:203], v[36:39]
	v_mfma_f32_16x16x32_bf16 v[32:35], v[184:187], v[200:203], v[32:35]
	v_mfma_f32_16x16x32_bf16 v[20:23], v[176:179], v[208:211], v[20:23]
	v_mfma_f32_16x16x32_bf16 v[16:19], v[184:187], v[208:211], v[16:19]
	v_mfma_f32_16x16x32_bf16 v[4:7], v[176:179], v[216:219], v[4:7]
	v_mfma_f32_16x16x32_bf16 v[0:3], v[184:187], v[216:219], v[0:3]
	s_barrier
	s_add_i32 s65, 0, 0x18000
	v_add_u32_e32 v159, s65, v154
	s_add_i32 s66, 0, 0x1c000
	ds_read_b128 v[146:149], v159
	ds_read_b128 v[160:163], v159 offset:1024
	ds_read_b128 v[164:167], v159 offset:2048
	ds_read_b128 v[168:171], v159 offset:3072
	v_add_u32_e32 v159, s66, v154
	ds_read_b128 v[172:175], v159
	ds_read_b128 v[176:179], v159 offset:1024
	ds_read_b128 v[180:183], v159 offset:2048
	ds_read_b128 v[184:187], v159 offset:3072
	s_add_u32 s26, s26, 0x160000
	s_addc_u32 s27, s27, 0
	s_mov_b32 m0, s38
	v_lshl_add_u64 v[228:229], s[26:27], 0, v[128:129]
	ds_read_b128 v[188:191], v158 offset:32768
	ds_read_b128 v[192:195], v158 offset:33792
	ds_read_b128 v[196:199], v158 offset:34816
	ds_read_b128 v[200:203], v158 offset:35840
	ds_read_b128 v[204:207], v158 offset:36864
	ds_read_b128 v[208:211], v158 offset:37888
	ds_read_b128 v[212:215], v158 offset:38912
	ds_read_b128 v[216:219], v158 offset:39936
	global_load_lds_dwordx4 v[228:229], off
	v_lshl_add_u64 v[228:229], s[26:27], 0, v[132:133]
	s_mov_b32 m0, s39
	s_nop 0
	global_load_lds_dwordx4 v[228:229], off
	s_waitcnt vmcnt(8)
	s_waitcnt lgkmcnt(0)
	s_barrier
	s_waitcnt lgkmcnt(0)
	v_mfma_f32_16x16x32_bf16 v[124:127], v[146:149], v[188:191], v[124:127]
	v_mfma_f32_16x16x32_bf16 v[120:123], v[164:167], v[188:191], v[120:123]
	v_mfma_f32_16x16x32_bf16 v[108:111], v[146:149], v[196:199], v[108:111]
	v_mfma_f32_16x16x32_bf16 v[104:107], v[164:167], v[196:199], v[104:107]
	v_mfma_f32_16x16x32_bf16 v[92:95], v[146:149], v[204:207], v[92:95]
	v_mfma_f32_16x16x32_bf16 v[88:91], v[164:167], v[204:207], v[88:91]
	v_mfma_f32_16x16x32_bf16 v[76:79], v[146:149], v[212:215], v[76:79]
	v_mfma_f32_16x16x32_bf16 v[72:75], v[164:167], v[212:215], v[72:75]
	v_mfma_f32_16x16x32_bf16 v[124:127], v[160:163], v[192:195], v[124:127]
	v_mfma_f32_16x16x32_bf16 v[120:123], v[168:171], v[192:195], v[120:123]
	v_mfma_f32_16x16x32_bf16 v[108:111], v[160:163], v[200:203], v[108:111]
	v_mfma_f32_16x16x32_bf16 v[104:107], v[168:171], v[200:203], v[104:107]
	v_mfma_f32_16x16x32_bf16 v[92:95], v[160:163], v[208:211], v[92:95]
	v_mfma_f32_16x16x32_bf16 v[88:91], v[168:171], v[208:211], v[88:91]
	v_mfma_f32_16x16x32_bf16 v[76:79], v[160:163], v[216:219], v[76:79]
	v_mfma_f32_16x16x32_bf16 v[72:75], v[168:171], v[216:219], v[72:75]
	v_mfma_f32_16x16x32_bf16 v[116:119], v[172:175], v[188:191], v[116:119]
	v_mfma_f32_16x16x32_bf16 v[112:115], v[180:183], v[188:191], v[112:115]
	v_mfma_f32_16x16x32_bf16 v[100:103], v[172:175], v[196:199], v[100:103]
	v_mfma_f32_16x16x32_bf16 v[96:99], v[180:183], v[196:199], v[96:99]
	v_mfma_f32_16x16x32_bf16 v[84:87], v[172:175], v[204:207], v[84:87]
	v_mfma_f32_16x16x32_bf16 v[80:83], v[180:183], v[204:207], v[80:83]
	v_mfma_f32_16x16x32_bf16 v[68:71], v[172:175], v[212:215], v[68:71]
	v_mfma_f32_16x16x32_bf16 v[64:67], v[180:183], v[212:215], v[64:67]
	v_mfma_f32_16x16x32_bf16 v[116:119], v[176:179], v[192:195], v[116:119]
	v_mfma_f32_16x16x32_bf16 v[112:115], v[184:187], v[192:195], v[112:115]
	v_mfma_f32_16x16x32_bf16 v[100:103], v[176:179], v[200:203], v[100:103]
	v_mfma_f32_16x16x32_bf16 v[96:99], v[184:187], v[200:203], v[96:99]
	v_mfma_f32_16x16x32_bf16 v[84:87], v[176:179], v[208:211], v[84:87]
	v_mfma_f32_16x16x32_bf16 v[80:83], v[184:187], v[208:211], v[80:83]
	v_mfma_f32_16x16x32_bf16 v[68:71], v[176:179], v[216:219], v[68:71]
	v_mfma_f32_16x16x32_bf16 v[64:67], v[184:187], v[216:219], v[64:67]
	s_barrier
	s_add_i32 s26, s65, s17
	v_lshl_add_u64 v[220:221], v[220:221], 0, s[12:13]
	s_mov_b32 m0, s26
	ds_read_b128 v[188:191], v158 offset:49152
	ds_read_b128 v[192:195], v158 offset:50176
	ds_read_b128 v[196:199], v158 offset:51200
	ds_read_b128 v[200:203], v158 offset:52224
	ds_read_b128 v[204:207], v158 offset:53248
	ds_read_b128 v[208:211], v158 offset:54272
	ds_read_b128 v[212:215], v158 offset:55296
	ds_read_b128 v[216:219], v158 offset:56320
	global_load_lds_dwordx4 v[220:221], off
	s_add_i32 m0, s26, 0x2000
	s_add_u32 s24, s24, 0x160080
	v_lshl_add_u64 v[220:221], v[222:223], 0, s[12:13]
	s_addc_u32 s25, s25, 0
	s_add_i32 s26, s66, s17
	global_load_lds_dwordx4 v[220:221], off
	v_lshl_add_u64 v[220:221], s[24:25], 0, v[130:131]
	s_mov_b32 m0, s26
	s_nop 0
	global_load_lds_dwordx4 v[220:221], off
	v_lshl_add_u64 v[220:221], s[24:25], 0, v[134:135]
	s_add_i32 m0, s26, 0x2000
	s_nop 0
	global_load_lds_dwordx4 v[220:221], off
	v_lshl_add_u64 v[220:221], v[224:225], 0, s[12:13]
	s_mov_b32 m0, s41
	s_nop 0
	global_load_lds_dwordx4 v[220:221], off
	v_lshl_add_u64 v[220:221], v[226:227], 0, s[12:13]
	s_mov_b32 m0, s42
	s_nop 0
	global_load_lds_dwordx4 v[220:221], off
	s_waitcnt vmcnt(8)
	s_waitcnt lgkmcnt(0)
	s_barrier
	s_waitcnt lgkmcnt(0)
	v_mfma_f32_16x16x32_bf16 v[60:63], v[146:149], v[188:191], v[60:63]
	v_mfma_f32_16x16x32_bf16 v[56:59], v[164:167], v[188:191], v[56:59]
	v_mfma_f32_16x16x32_bf16 v[44:47], v[146:149], v[196:199], v[44:47]
	v_mfma_f32_16x16x32_bf16 v[40:43], v[164:167], v[196:199], v[40:43]
	v_mfma_f32_16x16x32_bf16 v[28:31], v[146:149], v[204:207], v[28:31]
	v_mfma_f32_16x16x32_bf16 v[24:27], v[164:167], v[204:207], v[24:27]
	v_mfma_f32_16x16x32_bf16 v[12:15], v[146:149], v[212:215], v[12:15]
	v_mfma_f32_16x16x32_bf16 v[8:11], v[164:167], v[212:215], v[8:11]
	v_mfma_f32_16x16x32_bf16 v[60:63], v[160:163], v[192:195], v[60:63]
	v_mfma_f32_16x16x32_bf16 v[56:59], v[168:171], v[192:195], v[56:59]
	v_mfma_f32_16x16x32_bf16 v[44:47], v[160:163], v[200:203], v[44:47]
	v_mfma_f32_16x16x32_bf16 v[40:43], v[168:171], v[200:203], v[40:43]
	v_mfma_f32_16x16x32_bf16 v[28:31], v[160:163], v[208:211], v[28:31]
	v_mfma_f32_16x16x32_bf16 v[24:27], v[168:171], v[208:211], v[24:27]
	v_mfma_f32_16x16x32_bf16 v[12:15], v[160:163], v[216:219], v[12:15]
	v_mfma_f32_16x16x32_bf16 v[8:11], v[168:171], v[216:219], v[8:11]
	v_mfma_f32_16x16x32_bf16 v[52:55], v[172:175], v[188:191], v[52:55]
	v_mfma_f32_16x16x32_bf16 v[48:51], v[180:183], v[188:191], v[48:51]
	v_mfma_f32_16x16x32_bf16 v[36:39], v[172:175], v[196:199], v[36:39]
	v_mfma_f32_16x16x32_bf16 v[32:35], v[180:183], v[196:199], v[32:35]
	v_mfma_f32_16x16x32_bf16 v[20:23], v[172:175], v[204:207], v[20:23]
	v_mfma_f32_16x16x32_bf16 v[16:19], v[180:183], v[204:207], v[16:19]
	v_mfma_f32_16x16x32_bf16 v[4:7], v[172:175], v[212:215], v[4:7]
	v_mfma_f32_16x16x32_bf16 v[0:3], v[180:183], v[212:215], v[0:3]
	v_mfma_f32_16x16x32_bf16 v[52:55], v[176:179], v[192:195], v[52:55]
	v_mfma_f32_16x16x32_bf16 v[48:51], v[184:187], v[192:195], v[48:51]
	v_mfma_f32_16x16x32_bf16 v[36:39], v[176:179], v[200:203], v[36:39]
	v_mfma_f32_16x16x32_bf16 v[32:35], v[184:187], v[200:203], v[32:35]
	v_mfma_f32_16x16x32_bf16 v[20:23], v[176:179], v[208:211], v[20:23]
	v_mfma_f32_16x16x32_bf16 v[16:19], v[184:187], v[208:211], v[16:19]
	v_mfma_f32_16x16x32_bf16 v[4:7], v[176:179], v[216:219], v[4:7]
	v_mfma_f32_16x16x32_bf16 v[0:3], v[184:187], v[216:219], v[0:3]
	s_barrier
	s_add_i32 s61, s61, 2
	s_add_u32 s22, s22, 0x100
	s_addc_u32 s23, s23, 0
	s_add_u32 s59, s59, 0x100
	s_addc_u32 s60, s60, 0
	s_cmpk_gt_u32 s61, 0x55
	s_cbranch_scc0 .LBB0_335
	s_and_b64 vcc, exec, s[14:15]
	s_cbranch_vccz .LBB0_338
	s_barrier

.LBB0_498:
	ds_read_b128 v[150:153], v165
	ds_read_b128 v[168:171], v165 offset:1024
	ds_read_b128 v[172:175], v165 offset:2048
	ds_read_b128 v[176:179], v165 offset:3072
	ds_read_b128 v[180:183], v166
	ds_read_b128 v[184:187], v166 offset:1024
	ds_read_b128 v[188:191], v166 offset:2048
	ds_read_b128 v[192:195], v166 offset:3072
	s_add_u32 s36, s26, 0xfff80080
	s_addc_u32 s37, s27, -1
	s_cmp_eq_u32 s73, 28
	s_cselect_b32 s39, s23, s37
	s_cselect_b32 s38, s22, s36
	s_cselect_b32 s37, s25, s72
	s_cselect_b32 s36, s24, s71
	v_lshl_add_u64 v[154:155], s[26:27], 0, v[142:143]
	s_add_i32 m0, s43, 0xc000
	ds_read_b128 v[196:199], v167
	ds_read_b128 v[200:203], v167 offset:1024
	ds_read_b128 v[204:207], v167 offset:2048
	ds_read_b128 v[208:211], v167 offset:3072
	ds_read_b128 v[212:215], v167 offset:4096
	ds_read_b128 v[216:219], v167 offset:5120
	ds_read_b128 v[220:223], v167 offset:6144
	ds_read_b128 v[224:227], v167 offset:7168
	global_load_lds_dwordx4 v[154:155], off
	v_lshl_add_u64 v[154:155], s[26:27], 0, v[144:145]
	s_add_i32 m0, s43, 0xe000
	s_nop 0
	global_load_lds_dwordx4 v[154:155], off
	s_waitcnt vmcnt(8)
	s_waitcnt lgkmcnt(0)
	s_barrier
	s_waitcnt lgkmcnt(0)
	v_mfma_f32_16x16x32_bf16 v[124:127], v[150:153], v[196:199], v[124:127]
	v_mfma_f32_16x16x32_bf16 v[120:123], v[172:175], v[196:199], v[120:123]
	v_mfma_f32_16x16x32_bf16 v[108:111], v[150:153], v[204:207], v[108:111]
	v_mfma_f32_16x16x32_bf16 v[104:107], v[172:175], v[204:207], v[104:107]
	v_mfma_f32_16x16x32_bf16 v[92:95], v[150:153], v[212:215], v[92:95]
	v_mfma_f32_16x16x32_bf16 v[88:91], v[172:175], v[212:215], v[88:91]
	v_mfma_f32_16x16x32_bf16 v[76:79], v[150:153], v[220:223], v[76:79]
	v_mfma_f32_16x16x32_bf16 v[72:75], v[172:175], v[220:223], v[72:75]
	v_mfma_f32_16x16x32_bf16 v[124:127], v[168:171], v[200:203], v[124:127]
	v_mfma_f32_16x16x32_bf16 v[120:123], v[176:179], v[200:203], v[120:123]
	v_mfma_f32_16x16x32_bf16 v[108:111], v[168:171], v[208:211], v[108:111]
	v_mfma_f32_16x16x32_bf16 v[104:107], v[176:179], v[208:211], v[104:107]
	v_mfma_f32_16x16x32_bf16 v[92:95], v[168:171], v[216:219], v[92:95]
	v_mfma_f32_16x16x32_bf16 v[88:91], v[176:179], v[216:219], v[88:91]
	v_mfma_f32_16x16x32_bf16 v[76:79], v[168:171], v[224:227], v[76:79]
	v_mfma_f32_16x16x32_bf16 v[72:75], v[176:179], v[224:227], v[72:75]
	v_mfma_f32_16x16x32_bf16 v[116:119], v[180:183], v[196:199], v[116:119]
	v_mfma_f32_16x16x32_bf16 v[112:115], v[188:191], v[196:199], v[112:115]
	v_mfma_f32_16x16x32_bf16 v[100:103], v[180:183], v[204:207], v[100:103]
	v_mfma_f32_16x16x32_bf16 v[96:99], v[188:191], v[204:207], v[96:99]
	v_mfma_f32_16x16x32_bf16 v[84:87], v[180:183], v[212:215], v[84:87]
	v_mfma_f32_16x16x32_bf16 v[80:83], v[188:191], v[212:215], v[80:83]
	v_mfma_f32_16x16x32_bf16 v[68:71], v[180:183], v[220:223], v[68:71]
	v_mfma_f32_16x16x32_bf16 v[64:67], v[188:191], v[220:223], v[64:67]
	v_mfma_f32_16x16x32_bf16 v[116:119], v[184:187], v[200:203], v[116:119]
	v_mfma_f32_16x16x32_bf16 v[112:115], v[192:195], v[200:203], v[112:115]
	v_mfma_f32_16x16x32_bf16 v[100:103], v[184:187], v[208:211], v[100:103]
	v_mfma_f32_16x16x32_bf16 v[96:99], v[192:195], v[208:211], v[96:99]
	v_mfma_f32_16x16x32_bf16 v[84:87], v[184:187], v[216:219], v[84:87]
	v_mfma_f32_16x16x32_bf16 v[80:83], v[192:195], v[216:219], v[80:83]
	v_mfma_f32_16x16x32_bf16 v[68:71], v[184:187], v[224:227], v[68:71]
	v_mfma_f32_16x16x32_bf16 v[64:67], v[192:195], v[224:227], v[64:67]
	s_barrier
	s_add_i32 s74, s64, s42
	v_lshl_add_u64 v[154:155], s[36:37], 0, v[130:131]
	s_mov_b32 m0, s74
	ds_read_b128 v[196:199], v167 offset:16384
	ds_read_b128 v[200:203], v167 offset:17408
	ds_read_b128 v[204:207], v167 offset:18432
	ds_read_b128 v[208:211], v167 offset:19456
	ds_read_b128 v[212:215], v167 offset:20480
	ds_read_b128 v[216:219], v167 offset:21504
	ds_read_b128 v[220:223], v167 offset:22528
	ds_read_b128 v[224:227], v167 offset:23552
	global_load_lds_dwordx4 v[154:155], off
	s_add_i32 m0, s74, 0x2000
	s_add_u32 s74, s36, 0x80000
	v_lshl_add_u64 v[228:229], s[36:37], 0, v[134:135]
	s_addc_u32 s75, s37, 0
	s_add_i32 s76, s65, s42
	global_load_lds_dwordx4 v[228:229], off
	v_lshl_add_u64 v[240:241], s[74:75], 0, v[130:131]
	s_mov_b32 m0, s76
	v_lshl_add_u64 v[242:243], s[38:39], 0, v[132:133]
	global_load_lds_dwordx4 v[240:241], off
	v_lshl_add_u64 v[240:241], s[74:75], 0, v[134:135]
	s_add_i32 m0, s76, 0x2000
	s_nop 0
	global_load_lds_dwordx4 v[240:241], off
	v_lshl_add_u64 v[240:241], s[38:39], 0, v[128:129]
	s_mov_b32 m0, s43
	s_nop 0
	global_load_lds_dwordx4 v[240:241], off
	s_mov_b32 m0, s44
	s_nop 0
	global_load_lds_dwordx4 v[242:243], off
	s_waitcnt vmcnt(8)
	s_waitcnt lgkmcnt(0)
	s_barrier
	s_waitcnt lgkmcnt(0)
	v_mfma_f32_16x16x32_bf16 v[60:63], v[150:153], v[196:199], v[60:63]
	v_mfma_f32_16x16x32_bf16 v[56:59], v[172:175], v[196:199], v[56:59]
	v_mfma_f32_16x16x32_bf16 v[44:47], v[150:153], v[204:207], v[44:47]
	v_mfma_f32_16x16x32_bf16 v[40:43], v[172:175], v[204:207], v[40:43]
	v_mfma_f32_16x16x32_bf16 v[28:31], v[150:153], v[212:215], v[28:31]
	v_mfma_f32_16x16x32_bf16 v[24:27], v[172:175], v[212:215], v[24:27]
	v_mfma_f32_16x16x32_bf16 v[12:15], v[150:153], v[220:223], v[12:15]
	v_mfma_f32_16x16x32_bf16 v[8:11], v[172:175], v[220:223], v[8:11]
	v_mfma_f32_16x16x32_bf16 v[60:63], v[168:171], v[200:203], v[60:63]
	v_mfma_f32_16x16x32_bf16 v[56:59], v[176:179], v[200:203], v[56:59]
	v_mfma_f32_16x16x32_bf16 v[44:47], v[168:171], v[208:211], v[44:47]
	v_mfma_f32_16x16x32_bf16 v[40:43], v[176:179], v[208:211], v[40:43]
	v_mfma_f32_16x16x32_bf16 v[28:31], v[168:171], v[216:219], v[28:31]
	v_mfma_f32_16x16x32_bf16 v[24:27], v[176:179], v[216:219], v[24:27]
	v_mfma_f32_16x16x32_bf16 v[12:15], v[168:171], v[224:227], v[12:15]
	v_mfma_f32_16x16x32_bf16 v[8:11], v[176:179], v[224:227], v[8:11]
	v_mfma_f32_16x16x32_bf16 v[52:55], v[180:183], v[196:199], v[52:55]
	v_mfma_f32_16x16x32_bf16 v[48:51], v[188:191], v[196:199], v[48:51]
	v_mfma_f32_16x16x32_bf16 v[36:39], v[180:183], v[204:207], v[36:39]
	v_mfma_f32_16x16x32_bf16 v[32:35], v[188:191], v[204:207], v[32:35]
	v_mfma_f32_16x16x32_bf16 v[20:23], v[180:183], v[212:215], v[20:23]
	v_mfma_f32_16x16x32_bf16 v[16:19], v[188:191], v[212:215], v[16:19]
	v_mfma_f32_16x16x32_bf16 v[4:7], v[180:183], v[220:223], v[4:7]
	v_mfma_f32_16x16x32_bf16 v[0:3], v[188:191], v[220:223], v[0:3]
	v_mfma_f32_16x16x32_bf16 v[52:55], v[184:187], v[200:203], v[52:55]
	v_mfma_f32_16x16x32_bf16 v[48:51], v[192:195], v[200:203], v[48:51]
	v_mfma_f32_16x16x32_bf16 v[36:39], v[184:187], v[208:211], v[36:39]
	v_mfma_f32_16x16x32_bf16 v[32:35], v[192:195], v[208:211], v[32:35]
	v_mfma_f32_16x16x32_bf16 v[20:23], v[184:187], v[216:219], v[20:23]
	v_mfma_f32_16x16x32_bf16 v[16:19], v[192:195], v[216:219], v[16:19]
	v_mfma_f32_16x16x32_bf16 v[4:7], v[184:187], v[224:227], v[4:7]
	v_mfma_f32_16x16x32_bf16 v[0:3], v[192:195], v[224:227], v[0:3]
	s_barrier
	s_add_i32 s74, 0, 0x18000
	v_add_u32_e32 v140, s74, v156
	s_add_i32 s75, 0, 0x1c000
	ds_read_b128 v[150:153], v140
	ds_read_b128 v[168:171], v140 offset:1024
	ds_read_b128 v[172:175], v140 offset:2048
	ds_read_b128 v[176:179], v140 offset:3072
	v_add_u32_e32 v140, s75, v156
	ds_read_b128 v[180:183], v140
	ds_read_b128 v[184:187], v140 offset:1024
	ds_read_b128 v[188:191], v140 offset:2048
	ds_read_b128 v[192:195], v140 offset:3072
	s_add_u32 s38, s38, 0x80000
	s_addc_u32 s39, s39, 0
	s_mov_b32 m0, s45
	v_lshl_add_u64 v[244:245], s[38:39], 0, v[128:129]
	ds_read_b128 v[196:199], v167 offset:32768
	ds_read_b128 v[200:203], v167 offset:33792
	ds_read_b128 v[204:207], v167 offset:34816
	ds_read_b128 v[208:211], v167 offset:35840
	ds_read_b128 v[212:215], v167 offset:36864
	ds_read_b128 v[216:219], v167 offset:37888
	ds_read_b128 v[220:223], v167 offset:38912
	ds_read_b128 v[224:227], v167 offset:39936
	global_load_lds_dwordx4 v[244:245], off
	v_lshl_add_u64 v[244:245], s[38:39], 0, v[132:133]
	s_mov_b32 m0, s46
	s_nop 0
	global_load_lds_dwordx4 v[244:245], off
	s_waitcnt vmcnt(8)
	s_waitcnt lgkmcnt(0)
	s_barrier
	s_waitcnt lgkmcnt(0)
	v_mfma_f32_16x16x32_bf16 v[124:127], v[150:153], v[196:199], v[124:127]
	v_mfma_f32_16x16x32_bf16 v[120:123], v[172:175], v[196:199], v[120:123]
	v_mfma_f32_16x16x32_bf16 v[108:111], v[150:153], v[204:207], v[108:111]
	v_mfma_f32_16x16x32_bf16 v[104:107], v[172:175], v[204:207], v[104:107]
	v_mfma_f32_16x16x32_bf16 v[92:95], v[150:153], v[212:215], v[92:95]
	v_mfma_f32_16x16x32_bf16 v[88:91], v[172:175], v[212:215], v[88:91]
	v_mfma_f32_16x16x32_bf16 v[76:79], v[150:153], v[220:223], v[76:79]
	v_mfma_f32_16x16x32_bf16 v[72:75], v[172:175], v[220:223], v[72:75]
	v_mfma_f32_16x16x32_bf16 v[124:127], v[168:171], v[200:203], v[124:127]
	v_mfma_f32_16x16x32_bf16 v[120:123], v[176:179], v[200:203], v[120:123]
	v_mfma_f32_16x16x32_bf16 v[108:111], v[168:171], v[208:211], v[108:111]
	v_mfma_f32_16x16x32_bf16 v[104:107], v[176:179], v[208:211], v[104:107]
	v_mfma_f32_16x16x32_bf16 v[92:95], v[168:171], v[216:219], v[92:95]
	v_mfma_f32_16x16x32_bf16 v[88:91], v[176:179], v[216:219], v[88:91]
	v_mfma_f32_16x16x32_bf16 v[76:79], v[168:171], v[224:227], v[76:79]
	v_mfma_f32_16x16x32_bf16 v[72:75], v[176:179], v[224:227], v[72:75]
	v_mfma_f32_16x16x32_bf16 v[116:119], v[180:183], v[196:199], v[116:119]
	v_mfma_f32_16x16x32_bf16 v[112:115], v[188:191], v[196:199], v[112:115]
	v_mfma_f32_16x16x32_bf16 v[100:103], v[180:183], v[204:207], v[100:103]
	v_mfma_f32_16x16x32_bf16 v[96:99], v[188:191], v[204:207], v[96:99]
	v_mfma_f32_16x16x32_bf16 v[84:87], v[180:183], v[212:215], v[84:87]
	v_mfma_f32_16x16x32_bf16 v[80:83], v[188:191], v[212:215], v[80:83]
	v_mfma_f32_16x16x32_bf16 v[68:71], v[180:183], v[220:223], v[68:71]
	v_mfma_f32_16x16x32_bf16 v[64:67], v[188:191], v[220:223], v[64:67]
	v_mfma_f32_16x16x32_bf16 v[116:119], v[184:187], v[200:203], v[116:119]
	v_mfma_f32_16x16x32_bf16 v[112:115], v[192:195], v[200:203], v[112:115]
	v_mfma_f32_16x16x32_bf16 v[100:103], v[184:187], v[208:211], v[100:103]
	v_mfma_f32_16x16x32_bf16 v[96:99], v[192:195], v[208:211], v[96:99]
	v_mfma_f32_16x16x32_bf16 v[84:87], v[184:187], v[216:219], v[84:87]
	v_mfma_f32_16x16x32_bf16 v[80:83], v[192:195], v[216:219], v[80:83]
	v_mfma_f32_16x16x32_bf16 v[68:71], v[184:187], v[224:227], v[68:71]
	v_mfma_f32_16x16x32_bf16 v[64:67], v[192:195], v[224:227], v[64:67]
	s_barrier
	s_add_i32 s38, s74, s42
	v_lshl_add_u64 v[154:155], v[154:155], 0, s[16:17]
	s_mov_b32 m0, s38
	ds_read_b128 v[196:199], v167 offset:49152
	ds_read_b128 v[200:203], v167 offset:50176
	ds_read_b128 v[204:207], v167 offset:51200
	ds_read_b128 v[208:211], v167 offset:52224
	ds_read_b128 v[212:215], v167 offset:53248
	ds_read_b128 v[216:219], v167 offset:54272
	ds_read_b128 v[220:223], v167 offset:55296
	ds_read_b128 v[224:227], v167 offset:56320
	global_load_lds_dwordx4 v[154:155], off
	s_add_i32 m0, s38, 0x2000
	s_add_u32 s36, s36, 0x80080
	v_lshl_add_u64 v[154:155], v[228:229], 0, s[16:17]
	s_addc_u32 s37, s37, 0
	s_add_i32 s38, s75, s42
	global_load_lds_dwordx4 v[154:155], off
	v_lshl_add_u64 v[154:155], s[36:37], 0, v[130:131]
	s_mov_b32 m0, s38
	s_nop 0
	global_load_lds_dwordx4 v[154:155], off
	v_lshl_add_u64 v[154:155], s[36:37], 0, v[134:135]
	s_add_i32 m0, s38, 0x2000
	s_nop 0
	global_load_lds_dwordx4 v[154:155], off
	v_lshl_add_u64 v[154:155], v[240:241], 0, s[16:17]
	s_mov_b32 m0, s61
	s_nop 0
	global_load_lds_dwordx4 v[154:155], off
	v_lshl_add_u64 v[154:155], v[242:243], 0, s[16:17]
	s_mov_b32 m0, s62
	s_nop 0
	global_load_lds_dwordx4 v[154:155], off
	s_waitcnt vmcnt(8)
	s_waitcnt lgkmcnt(0)
	s_barrier
	s_waitcnt lgkmcnt(0)
	v_mfma_f32_16x16x32_bf16 v[60:63], v[150:153], v[196:199], v[60:63]
	v_mfma_f32_16x16x32_bf16 v[56:59], v[172:175], v[196:199], v[56:59]
	v_mfma_f32_16x16x32_bf16 v[44:47], v[150:153], v[204:207], v[44:47]
	v_mfma_f32_16x16x32_bf16 v[40:43], v[172:175], v[204:207], v[40:43]
	v_mfma_f32_16x16x32_bf16 v[28:31], v[150:153], v[212:215], v[28:31]
	v_mfma_f32_16x16x32_bf16 v[24:27], v[172:175], v[212:215], v[24:27]
	v_mfma_f32_16x16x32_bf16 v[12:15], v[150:153], v[220:223], v[12:15]
	v_mfma_f32_16x16x32_bf16 v[8:11], v[172:175], v[220:223], v[8:11]
	v_mfma_f32_16x16x32_bf16 v[60:63], v[168:171], v[200:203], v[60:63]
	v_mfma_f32_16x16x32_bf16 v[56:59], v[176:179], v[200:203], v[56:59]
	v_mfma_f32_16x16x32_bf16 v[44:47], v[168:171], v[208:211], v[44:47]
	v_mfma_f32_16x16x32_bf16 v[40:43], v[176:179], v[208:211], v[40:43]
	v_mfma_f32_16x16x32_bf16 v[28:31], v[168:171], v[216:219], v[28:31]
	v_mfma_f32_16x16x32_bf16 v[24:27], v[176:179], v[216:219], v[24:27]
	v_mfma_f32_16x16x32_bf16 v[12:15], v[168:171], v[224:227], v[12:15]
	v_mfma_f32_16x16x32_bf16 v[8:11], v[176:179], v[224:227], v[8:11]
	v_mfma_f32_16x16x32_bf16 v[52:55], v[180:183], v[196:199], v[52:55]
	v_mfma_f32_16x16x32_bf16 v[48:51], v[188:191], v[196:199], v[48:51]
	v_mfma_f32_16x16x32_bf16 v[36:39], v[180:183], v[204:207], v[36:39]
	v_mfma_f32_16x16x32_bf16 v[32:35], v[188:191], v[204:207], v[32:35]
	v_mfma_f32_16x16x32_bf16 v[20:23], v[180:183], v[212:215], v[20:23]
	v_mfma_f32_16x16x32_bf16 v[16:19], v[188:191], v[212:215], v[16:19]
	v_mfma_f32_16x16x32_bf16 v[4:7], v[180:183], v[220:223], v[4:7]
	v_mfma_f32_16x16x32_bf16 v[0:3], v[188:191], v[220:223], v[0:3]
	v_mfma_f32_16x16x32_bf16 v[52:55], v[184:187], v[200:203], v[52:55]
	v_mfma_f32_16x16x32_bf16 v[48:51], v[192:195], v[200:203], v[48:51]
	v_mfma_f32_16x16x32_bf16 v[36:39], v[184:187], v[208:211], v[36:39]
	v_mfma_f32_16x16x32_bf16 v[32:35], v[192:195], v[208:211], v[32:35]
	v_mfma_f32_16x16x32_bf16 v[20:23], v[184:187], v[216:219], v[20:23]
	v_mfma_f32_16x16x32_bf16 v[16:19], v[192:195], v[216:219], v[16:19]
	v_mfma_f32_16x16x32_bf16 v[4:7], v[184:187], v[224:227], v[4:7]
	v_mfma_f32_16x16x32_bf16 v[0:3], v[192:195], v[224:227], v[0:3]
	s_barrier
	s_add_i32 s73, s73, 2
	s_add_u32 s26, s26, 0x100
	s_addc_u32 s27, s27, 0
	s_add_u32 s71, s71, 0x100
	s_addc_u32 s72, s72, 0
	s_cmp_gt_u32 s73, 29
	s_cbranch_scc0 .LBB0_498
	s_and_b64 vcc, exec, s[18:19]
	s_cbranch_vccz .LBB0_501
	s_barrier

.LBB0_775:
	ds_read_b128 v[128:131], v172
	ds_read_b128 v[132:135], v172 offset:1024
	ds_read_b128 v[158:161], v172 offset:2048
	ds_read_b128 v[176:179], v172 offset:3072
	ds_read_b128 v[180:183], v173
	ds_read_b128 v[184:187], v173 offset:1024
	ds_read_b128 v[188:191], v173 offset:2048
	ds_read_b128 v[192:195], v173 offset:3072
	s_add_u32 s10, s8, 0xfffe8080
	s_addc_u32 s11, s9, -1
	s_cmp_eq_u32 s43, 2
	s_cselect_b32 s39, s27, s11
	s_cselect_b32 s38, s26, s10
	s_cselect_b32 s11, s37, s42
	s_cselect_b32 s10, s36, s41
	v_lshl_add_u64 v[162:163], s[8:9], 0, v[150:151]
	s_add_i32 m0, s58, 0xc000
	ds_read_b128 v[196:199], v174
	ds_read_b128 v[200:203], v174 offset:1024
	ds_read_b128 v[204:207], v174 offset:2048
	ds_read_b128 v[208:211], v174 offset:3072
	ds_read_b128 v[212:215], v174 offset:4096
	ds_read_b128 v[216:219], v174 offset:5120
	ds_read_b128 v[220:223], v174 offset:6144
	ds_read_b128 v[224:227], v174 offset:7168
	global_load_lds_dwordx4 v[162:163], off
	v_lshl_add_u64 v[162:163], s[8:9], 0, v[152:153]
	s_add_i32 m0, s58, 0xe000
	s_nop 0
	global_load_lds_dwordx4 v[162:163], off
	s_waitcnt vmcnt(8)
	s_waitcnt lgkmcnt(0)
	s_barrier
	s_waitcnt lgkmcnt(0)
	v_mfma_f32_16x16x32_bf16 v[124:127], v[128:131], v[196:199], v[124:127]
	v_mfma_f32_16x16x32_bf16 v[120:123], v[158:161], v[196:199], v[120:123]
	v_mfma_f32_16x16x32_bf16 v[108:111], v[128:131], v[204:207], v[108:111]
	v_mfma_f32_16x16x32_bf16 v[104:107], v[158:161], v[204:207], v[104:107]
	v_mfma_f32_16x16x32_bf16 v[92:95], v[128:131], v[212:215], v[92:95]
	v_mfma_f32_16x16x32_bf16 v[88:91], v[158:161], v[212:215], v[88:91]
	v_mfma_f32_16x16x32_bf16 v[76:79], v[128:131], v[220:223], v[76:79]
	v_mfma_f32_16x16x32_bf16 v[72:75], v[158:161], v[220:223], v[72:75]
	v_mfma_f32_16x16x32_bf16 v[124:127], v[132:135], v[200:203], v[124:127]
	v_mfma_f32_16x16x32_bf16 v[120:123], v[176:179], v[200:203], v[120:123]
	v_mfma_f32_16x16x32_bf16 v[108:111], v[132:135], v[208:211], v[108:111]
	v_mfma_f32_16x16x32_bf16 v[104:107], v[176:179], v[208:211], v[104:107]
	v_mfma_f32_16x16x32_bf16 v[92:95], v[132:135], v[216:219], v[92:95]
	v_mfma_f32_16x16x32_bf16 v[88:91], v[176:179], v[216:219], v[88:91]
	v_mfma_f32_16x16x32_bf16 v[76:79], v[132:135], v[224:227], v[76:79]
	v_mfma_f32_16x16x32_bf16 v[72:75], v[176:179], v[224:227], v[72:75]
	v_mfma_f32_16x16x32_bf16 v[116:119], v[180:183], v[196:199], v[116:119]
	v_mfma_f32_16x16x32_bf16 v[112:115], v[188:191], v[196:199], v[112:115]
	v_mfma_f32_16x16x32_bf16 v[100:103], v[180:183], v[204:207], v[100:103]
	v_mfma_f32_16x16x32_bf16 v[96:99], v[188:191], v[204:207], v[96:99]
	v_mfma_f32_16x16x32_bf16 v[84:87], v[180:183], v[212:215], v[84:87]
	v_mfma_f32_16x16x32_bf16 v[80:83], v[188:191], v[212:215], v[80:83]
	v_mfma_f32_16x16x32_bf16 v[68:71], v[180:183], v[220:223], v[68:71]
	v_mfma_f32_16x16x32_bf16 v[64:67], v[188:191], v[220:223], v[64:67]
	v_mfma_f32_16x16x32_bf16 v[116:119], v[184:187], v[200:203], v[116:119]
	v_mfma_f32_16x16x32_bf16 v[112:115], v[192:195], v[200:203], v[112:115]
	v_mfma_f32_16x16x32_bf16 v[100:103], v[184:187], v[208:211], v[100:103]
	v_mfma_f32_16x16x32_bf16 v[96:99], v[192:195], v[208:211], v[96:99]
	v_mfma_f32_16x16x32_bf16 v[84:87], v[184:187], v[216:219], v[84:87]
	v_mfma_f32_16x16x32_bf16 v[80:83], v[192:195], v[216:219], v[80:83]
	v_mfma_f32_16x16x32_bf16 v[68:71], v[184:187], v[224:227], v[68:71]
	v_mfma_f32_16x16x32_bf16 v[64:67], v[192:195], v[224:227], v[64:67]
	s_barrier
	s_add_i32 s76, s68, s47
	v_lshl_add_u64 v[162:163], s[10:11], 0, v[142:143]
	s_mov_b32 m0, s76
	ds_read_b128 v[196:199], v174 offset:16384
	ds_read_b128 v[200:203], v174 offset:17408
	ds_read_b128 v[204:207], v174 offset:18432
	ds_read_b128 v[208:211], v174 offset:19456
	ds_read_b128 v[212:215], v174 offset:20480
	ds_read_b128 v[216:219], v174 offset:21504
	ds_read_b128 v[220:223], v174 offset:22528
	ds_read_b128 v[224:227], v174 offset:23552
	global_load_lds_dwordx4 v[162:163], off
	s_add_i32 m0, s76, 0x2000
	s_add_u32 s76, s10, 0x18000
	v_lshl_add_u64 v[228:229], s[10:11], 0, v[146:147]
	s_addc_u32 s77, s11, 0
	s_add_i32 s78, s69, s47
	global_load_lds_dwordx4 v[228:229], off
	v_lshl_add_u64 v[240:241], s[76:77], 0, v[142:143]
	s_mov_b32 m0, s78
	v_lshl_add_u64 v[242:243], s[38:39], 0, v[144:145]
	global_load_lds_dwordx4 v[240:241], off
	v_lshl_add_u64 v[240:241], s[76:77], 0, v[146:147]
	s_add_i32 m0, s78, 0x2000
	s_nop 0
	global_load_lds_dwordx4 v[240:241], off
	v_lshl_add_u64 v[240:241], s[38:39], 0, v[140:141]
	s_mov_b32 m0, s58
	s_nop 0
	global_load_lds_dwordx4 v[240:241], off
	s_mov_b32 m0, s59
	s_nop 0
	global_load_lds_dwordx4 v[242:243], off
	s_waitcnt vmcnt(8)
	s_waitcnt lgkmcnt(0)
	s_barrier
	s_waitcnt lgkmcnt(0)
	v_mfma_f32_16x16x32_bf16 v[60:63], v[128:131], v[196:199], v[60:63]
	v_mfma_f32_16x16x32_bf16 v[56:59], v[158:161], v[196:199], v[56:59]
	v_mfma_f32_16x16x32_bf16 v[44:47], v[128:131], v[204:207], v[44:47]
	v_mfma_f32_16x16x32_bf16 v[40:43], v[158:161], v[204:207], v[40:43]
	v_mfma_f32_16x16x32_bf16 v[28:31], v[128:131], v[212:215], v[28:31]
	v_mfma_f32_16x16x32_bf16 v[24:27], v[158:161], v[212:215], v[24:27]
	v_mfma_f32_16x16x32_bf16 v[12:15], v[128:131], v[220:223], v[12:15]
	v_mfma_f32_16x16x32_bf16 v[8:11], v[158:161], v[220:223], v[8:11]
	v_mfma_f32_16x16x32_bf16 v[60:63], v[132:135], v[200:203], v[60:63]
	v_mfma_f32_16x16x32_bf16 v[56:59], v[176:179], v[200:203], v[56:59]
	v_mfma_f32_16x16x32_bf16 v[44:47], v[132:135], v[208:211], v[44:47]
	v_mfma_f32_16x16x32_bf16 v[40:43], v[176:179], v[208:211], v[40:43]
	v_mfma_f32_16x16x32_bf16 v[28:31], v[132:135], v[216:219], v[28:31]
	v_mfma_f32_16x16x32_bf16 v[24:27], v[176:179], v[216:219], v[24:27]
	v_mfma_f32_16x16x32_bf16 v[12:15], v[132:135], v[224:227], v[12:15]
	v_mfma_f32_16x16x32_bf16 v[8:11], v[176:179], v[224:227], v[8:11]
	v_mfma_f32_16x16x32_bf16 v[52:55], v[180:183], v[196:199], v[52:55]
	v_mfma_f32_16x16x32_bf16 v[48:51], v[188:191], v[196:199], v[48:51]
	v_mfma_f32_16x16x32_bf16 v[36:39], v[180:183], v[204:207], v[36:39]
	v_mfma_f32_16x16x32_bf16 v[32:35], v[188:191], v[204:207], v[32:35]
	v_mfma_f32_16x16x32_bf16 v[20:23], v[180:183], v[212:215], v[20:23]
	v_mfma_f32_16x16x32_bf16 v[16:19], v[188:191], v[212:215], v[16:19]
	v_mfma_f32_16x16x32_bf16 v[4:7], v[180:183], v[220:223], v[4:7]
	v_mfma_f32_16x16x32_bf16 v[0:3], v[188:191], v[220:223], v[0:3]
	v_mfma_f32_16x16x32_bf16 v[52:55], v[184:187], v[200:203], v[52:55]
	v_mfma_f32_16x16x32_bf16 v[48:51], v[192:195], v[200:203], v[48:51]
	v_mfma_f32_16x16x32_bf16 v[36:39], v[184:187], v[208:211], v[36:39]
	v_mfma_f32_16x16x32_bf16 v[32:35], v[192:195], v[208:211], v[32:35]
	v_mfma_f32_16x16x32_bf16 v[20:23], v[184:187], v[216:219], v[20:23]
	v_mfma_f32_16x16x32_bf16 v[16:19], v[192:195], v[216:219], v[16:19]
	v_mfma_f32_16x16x32_bf16 v[4:7], v[184:187], v[224:227], v[4:7]
	v_mfma_f32_16x16x32_bf16 v[0:3], v[192:195], v[224:227], v[0:3]
	s_barrier
	s_add_i32 s76, 0, 0x18000
	v_add_u32_e32 v148, s76, v164
	s_add_i32 s77, 0, 0x1c000
	ds_read_b128 v[128:131], v148
	ds_read_b128 v[132:135], v148 offset:1024
	ds_read_b128 v[158:161], v148 offset:2048
	ds_read_b128 v[176:179], v148 offset:3072
	v_add_u32_e32 v148, s77, v164
	ds_read_b128 v[180:183], v148
	ds_read_b128 v[184:187], v148 offset:1024
	ds_read_b128 v[188:191], v148 offset:2048
	ds_read_b128 v[192:195], v148 offset:3072
	s_add_u32 s38, s38, 0x18000
	s_addc_u32 s39, s39, 0
	s_mov_b32 m0, s60
	v_lshl_add_u64 v[244:245], s[38:39], 0, v[140:141]
	ds_read_b128 v[196:199], v174 offset:32768
	ds_read_b128 v[200:203], v174 offset:33792
	ds_read_b128 v[204:207], v174 offset:34816
	ds_read_b128 v[208:211], v174 offset:35840
	ds_read_b128 v[212:215], v174 offset:36864
	ds_read_b128 v[216:219], v174 offset:37888
	ds_read_b128 v[220:223], v174 offset:38912
	ds_read_b128 v[224:227], v174 offset:39936
	global_load_lds_dwordx4 v[244:245], off
	v_lshl_add_u64 v[244:245], s[38:39], 0, v[144:145]
	s_mov_b32 m0, s61
	s_nop 0
	global_load_lds_dwordx4 v[244:245], off
	s_waitcnt vmcnt(8)
	s_waitcnt lgkmcnt(0)
	s_barrier
	s_waitcnt lgkmcnt(0)
	v_mfma_f32_16x16x32_bf16 v[124:127], v[128:131], v[196:199], v[124:127]
	v_mfma_f32_16x16x32_bf16 v[120:123], v[158:161], v[196:199], v[120:123]
	v_mfma_f32_16x16x32_bf16 v[108:111], v[128:131], v[204:207], v[108:111]
	v_mfma_f32_16x16x32_bf16 v[104:107], v[158:161], v[204:207], v[104:107]
	v_mfma_f32_16x16x32_bf16 v[92:95], v[128:131], v[212:215], v[92:95]
	v_mfma_f32_16x16x32_bf16 v[88:91], v[158:161], v[212:215], v[88:91]
	v_mfma_f32_16x16x32_bf16 v[76:79], v[128:131], v[220:223], v[76:79]
	v_mfma_f32_16x16x32_bf16 v[72:75], v[158:161], v[220:223], v[72:75]
	v_mfma_f32_16x16x32_bf16 v[124:127], v[132:135], v[200:203], v[124:127]
	v_mfma_f32_16x16x32_bf16 v[120:123], v[176:179], v[200:203], v[120:123]
	v_mfma_f32_16x16x32_bf16 v[108:111], v[132:135], v[208:211], v[108:111]
	v_mfma_f32_16x16x32_bf16 v[104:107], v[176:179], v[208:211], v[104:107]
	v_mfma_f32_16x16x32_bf16 v[92:95], v[132:135], v[216:219], v[92:95]
	v_mfma_f32_16x16x32_bf16 v[88:91], v[176:179], v[216:219], v[88:91]
	v_mfma_f32_16x16x32_bf16 v[76:79], v[132:135], v[224:227], v[76:79]
	v_mfma_f32_16x16x32_bf16 v[72:75], v[176:179], v[224:227], v[72:75]
	v_mfma_f32_16x16x32_bf16 v[116:119], v[180:183], v[196:199], v[116:119]
	v_mfma_f32_16x16x32_bf16 v[112:115], v[188:191], v[196:199], v[112:115]
	v_mfma_f32_16x16x32_bf16 v[100:103], v[180:183], v[204:207], v[100:103]
	v_mfma_f32_16x16x32_bf16 v[96:99], v[188:191], v[204:207], v[96:99]
	v_mfma_f32_16x16x32_bf16 v[84:87], v[180:183], v[212:215], v[84:87]
	v_mfma_f32_16x16x32_bf16 v[80:83], v[188:191], v[212:215], v[80:83]
	v_mfma_f32_16x16x32_bf16 v[68:71], v[180:183], v[220:223], v[68:71]
	v_mfma_f32_16x16x32_bf16 v[64:67], v[188:191], v[220:223], v[64:67]
	v_mfma_f32_16x16x32_bf16 v[116:119], v[184:187], v[200:203], v[116:119]
	v_mfma_f32_16x16x32_bf16 v[112:115], v[192:195], v[200:203], v[112:115]
	v_mfma_f32_16x16x32_bf16 v[100:103], v[184:187], v[208:211], v[100:103]
	v_mfma_f32_16x16x32_bf16 v[96:99], v[192:195], v[208:211], v[96:99]
	v_mfma_f32_16x16x32_bf16 v[84:87], v[184:187], v[216:219], v[84:87]
	v_mfma_f32_16x16x32_bf16 v[80:83], v[192:195], v[216:219], v[80:83]
	v_mfma_f32_16x16x32_bf16 v[68:71], v[184:187], v[224:227], v[68:71]
	v_mfma_f32_16x16x32_bf16 v[64:67], v[192:195], v[224:227], v[64:67]
	s_barrier
	s_add_i32 s38, s76, s47
	v_lshl_add_u64 v[162:163], v[162:163], 0, s[22:23]
	s_mov_b32 m0, s38
	ds_read_b128 v[196:199], v174 offset:49152
	ds_read_b128 v[200:203], v174 offset:50176
	ds_read_b128 v[204:207], v174 offset:51200
	ds_read_b128 v[208:211], v174 offset:52224
	ds_read_b128 v[212:215], v174 offset:53248
	ds_read_b128 v[216:219], v174 offset:54272
	ds_read_b128 v[220:223], v174 offset:55296
	ds_read_b128 v[224:227], v174 offset:56320
	global_load_lds_dwordx4 v[162:163], off
	s_add_i32 m0, s38, 0x2000
	s_add_u32 s10, s10, 0x18080
	v_lshl_add_u64 v[162:163], v[228:229], 0, s[22:23]
	s_addc_u32 s11, s11, 0
	s_add_i32 s38, s77, s47
	global_load_lds_dwordx4 v[162:163], off
	v_lshl_add_u64 v[162:163], s[10:11], 0, v[142:143]
	s_mov_b32 m0, s38
	s_nop 0
	global_load_lds_dwordx4 v[162:163], off
	v_lshl_add_u64 v[162:163], s[10:11], 0, v[146:147]
	s_add_i32 m0, s38, 0x2000
	s_nop 0
	global_load_lds_dwordx4 v[162:163], off
	v_lshl_add_u64 v[162:163], v[240:241], 0, s[22:23]
	s_mov_b32 m0, s65
	s_nop 0
	global_load_lds_dwordx4 v[162:163], off
	v_lshl_add_u64 v[162:163], v[242:243], 0, s[22:23]
	s_mov_b32 m0, s66
	s_nop 0
	global_load_lds_dwordx4 v[162:163], off
	s_waitcnt vmcnt(8)
	s_waitcnt lgkmcnt(0)
	s_barrier
	s_waitcnt lgkmcnt(0)
	v_mfma_f32_16x16x32_bf16 v[60:63], v[128:131], v[196:199], v[60:63]
	v_mfma_f32_16x16x32_bf16 v[56:59], v[158:161], v[196:199], v[56:59]
	v_mfma_f32_16x16x32_bf16 v[44:47], v[128:131], v[204:207], v[44:47]
	v_mfma_f32_16x16x32_bf16 v[40:43], v[158:161], v[204:207], v[40:43]
	v_mfma_f32_16x16x32_bf16 v[28:31], v[128:131], v[212:215], v[28:31]
	v_mfma_f32_16x16x32_bf16 v[24:27], v[158:161], v[212:215], v[24:27]
	v_mfma_f32_16x16x32_bf16 v[12:15], v[128:131], v[220:223], v[12:15]
	v_mfma_f32_16x16x32_bf16 v[8:11], v[158:161], v[220:223], v[8:11]
	v_mfma_f32_16x16x32_bf16 v[60:63], v[132:135], v[200:203], v[60:63]
	v_mfma_f32_16x16x32_bf16 v[56:59], v[176:179], v[200:203], v[56:59]
	v_mfma_f32_16x16x32_bf16 v[44:47], v[132:135], v[208:211], v[44:47]
	v_mfma_f32_16x16x32_bf16 v[40:43], v[176:179], v[208:211], v[40:43]
	v_mfma_f32_16x16x32_bf16 v[28:31], v[132:135], v[216:219], v[28:31]
	v_mfma_f32_16x16x32_bf16 v[24:27], v[176:179], v[216:219], v[24:27]
	v_mfma_f32_16x16x32_bf16 v[12:15], v[132:135], v[224:227], v[12:15]
	v_mfma_f32_16x16x32_bf16 v[8:11], v[176:179], v[224:227], v[8:11]
	v_mfma_f32_16x16x32_bf16 v[52:55], v[180:183], v[196:199], v[52:55]
	v_mfma_f32_16x16x32_bf16 v[48:51], v[188:191], v[196:199], v[48:51]
	v_mfma_f32_16x16x32_bf16 v[36:39], v[180:183], v[204:207], v[36:39]
	v_mfma_f32_16x16x32_bf16 v[32:35], v[188:191], v[204:207], v[32:35]
	v_mfma_f32_16x16x32_bf16 v[20:23], v[180:183], v[212:215], v[20:23]
	v_mfma_f32_16x16x32_bf16 v[16:19], v[188:191], v[212:215], v[16:19]
	v_mfma_f32_16x16x32_bf16 v[4:7], v[180:183], v[220:223], v[4:7]
	v_mfma_f32_16x16x32_bf16 v[0:3], v[188:191], v[220:223], v[0:3]
	v_mfma_f32_16x16x32_bf16 v[52:55], v[184:187], v[200:203], v[52:55]
	v_mfma_f32_16x16x32_bf16 v[48:51], v[192:195], v[200:203], v[48:51]
	v_mfma_f32_16x16x32_bf16 v[36:39], v[184:187], v[208:211], v[36:39]
	v_mfma_f32_16x16x32_bf16 v[32:35], v[192:195], v[208:211], v[32:35]
	v_mfma_f32_16x16x32_bf16 v[20:23], v[184:187], v[216:219], v[20:23]
	v_mfma_f32_16x16x32_bf16 v[16:19], v[192:195], v[216:219], v[16:19]
	v_mfma_f32_16x16x32_bf16 v[4:7], v[184:187], v[224:227], v[4:7]
	v_mfma_f32_16x16x32_bf16 v[0:3], v[192:195], v[224:227], v[0:3]
	s_barrier
	s_add_i32 s43, s43, 2
	s_add_u32 s8, s8, 0x100
	s_addc_u32 s9, s9, 0
	s_add_u32 s41, s41, 0x100
	s_addc_u32 s42, s42, 0
	s_cmp_gt_u32 s43, 3
	s_cbranch_scc0 .LBB0_775
	s_and_b64 vcc, exec, s[24:25]
	s_cbranch_vccz .LBB0_778
	s_barrier

.LBB0_1649:
	ds_read_b128 v[148:151], v157
	ds_read_b128 v[160:163], v157 offset:1024
	ds_read_b128 v[164:167], v157 offset:2048
	ds_read_b128 v[168:171], v157 offset:3072
	ds_read_b128 v[172:175], v158
	ds_read_b128 v[176:179], v158 offset:1024
	ds_read_b128 v[180:183], v158 offset:2048
	ds_read_b128 v[184:187], v158 offset:3072
	s_add_u32 s24, s22, 0xfff80080
	s_addc_u32 s25, s23, -1
	s_cmp_eq_u32 s66, 28
	s_cselect_b32 s27, s19, s25
	s_cselect_b32 s26, s18, s24
	s_cselect_b32 s25, s21, s65
	s_cselect_b32 s24, s20, s61
	v_lshl_add_u64 v[220:221], s[22:23], 0, v[140:141]
	s_add_i32 m0, s38, 0xc000
	ds_read_b128 v[188:191], v159
	ds_read_b128 v[192:195], v159 offset:1024
	ds_read_b128 v[196:199], v159 offset:2048
	ds_read_b128 v[200:203], v159 offset:3072
	ds_read_b128 v[204:207], v159 offset:4096
	ds_read_b128 v[208:211], v159 offset:5120
	ds_read_b128 v[212:215], v159 offset:6144
	ds_read_b128 v[216:219], v159 offset:7168
	global_load_lds_dwordx4 v[220:221], off
	v_lshl_add_u64 v[220:221], s[22:23], 0, v[142:143]
	s_add_i32 m0, s38, 0xe000
	s_nop 0
	global_load_lds_dwordx4 v[220:221], off
	s_waitcnt vmcnt(8)
	s_waitcnt lgkmcnt(0)
	s_barrier
	s_waitcnt lgkmcnt(0)
	v_mfma_f32_16x16x32_bf16 v[124:127], v[148:151], v[188:191], v[124:127]
	v_mfma_f32_16x16x32_bf16 v[120:123], v[164:167], v[188:191], v[120:123]
	v_mfma_f32_16x16x32_bf16 v[108:111], v[148:151], v[196:199], v[108:111]
	v_mfma_f32_16x16x32_bf16 v[104:107], v[164:167], v[196:199], v[104:107]
	v_mfma_f32_16x16x32_bf16 v[92:95], v[148:151], v[204:207], v[92:95]
	v_mfma_f32_16x16x32_bf16 v[88:91], v[164:167], v[204:207], v[88:91]
	v_mfma_f32_16x16x32_bf16 v[76:79], v[148:151], v[212:215], v[76:79]
	v_mfma_f32_16x16x32_bf16 v[72:75], v[164:167], v[212:215], v[72:75]
	v_mfma_f32_16x16x32_bf16 v[124:127], v[160:163], v[192:195], v[124:127]
	v_mfma_f32_16x16x32_bf16 v[120:123], v[168:171], v[192:195], v[120:123]
	v_mfma_f32_16x16x32_bf16 v[108:111], v[160:163], v[200:203], v[108:111]
	v_mfma_f32_16x16x32_bf16 v[104:107], v[168:171], v[200:203], v[104:107]
	v_mfma_f32_16x16x32_bf16 v[92:95], v[160:163], v[208:211], v[92:95]
	v_mfma_f32_16x16x32_bf16 v[88:91], v[168:171], v[208:211], v[88:91]
	v_mfma_f32_16x16x32_bf16 v[76:79], v[160:163], v[216:219], v[76:79]
	v_mfma_f32_16x16x32_bf16 v[72:75], v[168:171], v[216:219], v[72:75]
	v_mfma_f32_16x16x32_bf16 v[116:119], v[172:175], v[188:191], v[116:119]
	v_mfma_f32_16x16x32_bf16 v[112:115], v[180:183], v[188:191], v[112:115]
	v_mfma_f32_16x16x32_bf16 v[100:103], v[172:175], v[196:199], v[100:103]
	v_mfma_f32_16x16x32_bf16 v[96:99], v[180:183], v[196:199], v[96:99]
	v_mfma_f32_16x16x32_bf16 v[84:87], v[172:175], v[204:207], v[84:87]
	v_mfma_f32_16x16x32_bf16 v[80:83], v[180:183], v[204:207], v[80:83]
	v_mfma_f32_16x16x32_bf16 v[68:71], v[172:175], v[212:215], v[68:71]
	v_mfma_f32_16x16x32_bf16 v[64:67], v[180:183], v[212:215], v[64:67]
	v_mfma_f32_16x16x32_bf16 v[116:119], v[176:179], v[192:195], v[116:119]
	v_mfma_f32_16x16x32_bf16 v[112:115], v[184:187], v[192:195], v[112:115]
	v_mfma_f32_16x16x32_bf16 v[100:103], v[176:179], v[200:203], v[100:103]
	v_mfma_f32_16x16x32_bf16 v[96:99], v[184:187], v[200:203], v[96:99]
	v_mfma_f32_16x16x32_bf16 v[84:87], v[176:179], v[208:211], v[84:87]
	v_mfma_f32_16x16x32_bf16 v[80:83], v[184:187], v[208:211], v[80:83]
	v_mfma_f32_16x16x32_bf16 v[68:71], v[176:179], v[216:219], v[68:71]
	v_mfma_f32_16x16x32_bf16 v[64:67], v[184:187], v[216:219], v[64:67]
	s_barrier
	s_add_i32 s67, s45, s37
	v_lshl_add_u64 v[220:221], s[24:25], 0, v[130:131]
	s_mov_b32 m0, s67
	ds_read_b128 v[188:191], v159 offset:16384
	ds_read_b128 v[192:195], v159 offset:17408
	ds_read_b128 v[196:199], v159 offset:18432
	ds_read_b128 v[200:203], v159 offset:19456
	ds_read_b128 v[204:207], v159 offset:20480
	ds_read_b128 v[208:211], v159 offset:21504
	ds_read_b128 v[212:215], v159 offset:22528
	ds_read_b128 v[216:219], v159 offset:23552
	global_load_lds_dwordx4 v[220:221], off
	s_add_i32 m0, s67, 0x2000
	s_add_u32 s68, s24, 0x80000
	v_lshl_add_u64 v[222:223], s[24:25], 0, v[134:135]
	s_addc_u32 s69, s25, 0
	s_add_i32 s67, s46, s37
	global_load_lds_dwordx4 v[222:223], off
	v_lshl_add_u64 v[224:225], s[68:69], 0, v[130:131]
	s_mov_b32 m0, s67
	v_lshl_add_u64 v[226:227], s[26:27], 0, v[132:133]
	global_load_lds_dwordx4 v[224:225], off
	v_lshl_add_u64 v[224:225], s[68:69], 0, v[134:135]
	s_add_i32 m0, s67, 0x2000
	s_nop 0
	global_load_lds_dwordx4 v[224:225], off
	v_lshl_add_u64 v[224:225], s[26:27], 0, v[128:129]
	s_mov_b32 m0, s38
	s_nop 0
	global_load_lds_dwordx4 v[224:225], off
	s_mov_b32 m0, s39
	s_nop 0
	global_load_lds_dwordx4 v[226:227], off
	s_waitcnt vmcnt(8)
	s_waitcnt lgkmcnt(0)
	s_barrier
	s_waitcnt lgkmcnt(0)
	v_mfma_f32_16x16x32_bf16 v[60:63], v[148:151], v[188:191], v[60:63]
	v_mfma_f32_16x16x32_bf16 v[56:59], v[164:167], v[188:191], v[56:59]
	v_mfma_f32_16x16x32_bf16 v[44:47], v[148:151], v[196:199], v[44:47]
	v_mfma_f32_16x16x32_bf16 v[40:43], v[164:167], v[196:199], v[40:43]
	v_mfma_f32_16x16x32_bf16 v[28:31], v[148:151], v[204:207], v[28:31]
	v_mfma_f32_16x16x32_bf16 v[24:27], v[164:167], v[204:207], v[24:27]
	v_mfma_f32_16x16x32_bf16 v[12:15], v[148:151], v[212:215], v[12:15]
	v_mfma_f32_16x16x32_bf16 v[8:11], v[164:167], v[212:215], v[8:11]
	v_mfma_f32_16x16x32_bf16 v[60:63], v[160:163], v[192:195], v[60:63]
	v_mfma_f32_16x16x32_bf16 v[56:59], v[168:171], v[192:195], v[56:59]
	v_mfma_f32_16x16x32_bf16 v[44:47], v[160:163], v[200:203], v[44:47]
	v_mfma_f32_16x16x32_bf16 v[40:43], v[168:171], v[200:203], v[40:43]
	v_mfma_f32_16x16x32_bf16 v[28:31], v[160:163], v[208:211], v[28:31]
	v_mfma_f32_16x16x32_bf16 v[24:27], v[168:171], v[208:211], v[24:27]
	v_mfma_f32_16x16x32_bf16 v[12:15], v[160:163], v[216:219], v[12:15]
	v_mfma_f32_16x16x32_bf16 v[8:11], v[168:171], v[216:219], v[8:11]
	v_mfma_f32_16x16x32_bf16 v[52:55], v[172:175], v[188:191], v[52:55]
	v_mfma_f32_16x16x32_bf16 v[48:51], v[180:183], v[188:191], v[48:51]
	v_mfma_f32_16x16x32_bf16 v[36:39], v[172:175], v[196:199], v[36:39]
	v_mfma_f32_16x16x32_bf16 v[32:35], v[180:183], v[196:199], v[32:35]
	v_mfma_f32_16x16x32_bf16 v[20:23], v[172:175], v[204:207], v[20:23]
	v_mfma_f32_16x16x32_bf16 v[16:19], v[180:183], v[204:207], v[16:19]
	v_mfma_f32_16x16x32_bf16 v[4:7], v[172:175], v[212:215], v[4:7]
	v_mfma_f32_16x16x32_bf16 v[0:3], v[180:183], v[212:215], v[0:3]
	v_mfma_f32_16x16x32_bf16 v[52:55], v[176:179], v[192:195], v[52:55]
	v_mfma_f32_16x16x32_bf16 v[48:51], v[184:187], v[192:195], v[48:51]
	v_mfma_f32_16x16x32_bf16 v[36:39], v[176:179], v[200:203], v[36:39]
	v_mfma_f32_16x16x32_bf16 v[32:35], v[184:187], v[200:203], v[32:35]
	v_mfma_f32_16x16x32_bf16 v[20:23], v[176:179], v[208:211], v[20:23]
	v_mfma_f32_16x16x32_bf16 v[16:19], v[184:187], v[208:211], v[16:19]
	v_mfma_f32_16x16x32_bf16 v[4:7], v[176:179], v[216:219], v[4:7]
	v_mfma_f32_16x16x32_bf16 v[0:3], v[184:187], v[216:219], v[0:3]
	s_barrier
	s_add_i32 s67, 0, 0x18000
	s_add_i32 s68, 0, 0x1c000
	v_add_u32_e32 v168, s67, v155
	v_add_u32_e32 v184, s68, v155
	ds_read_b128 v[148:151], v168
	ds_read_b128 v[160:163], v168 offset:1024
	ds_read_b128 v[164:167], v168 offset:2048
	ds_read_b128 v[168:171], v168 offset:3072
	ds_read_b128 v[172:175], v184
	ds_read_b128 v[176:179], v184 offset:1024
	ds_read_b128 v[180:183], v184 offset:2048
	ds_read_b128 v[184:187], v184 offset:3072
	s_add_u32 s26, s26, 0x80000
	s_addc_u32 s27, s27, 0
	s_mov_b32 m0, s40
	v_lshl_add_u64 v[228:229], s[26:27], 0, v[128:129]
	ds_read_b128 v[188:191], v159 offset:32768
	ds_read_b128 v[192:195], v159 offset:33792
	ds_read_b128 v[196:199], v159 offset:34816
	ds_read_b128 v[200:203], v159 offset:35840
	ds_read_b128 v[204:207], v159 offset:36864
	ds_read_b128 v[208:211], v159 offset:37888
	ds_read_b128 v[212:215], v159 offset:38912
	ds_read_b128 v[216:219], v159 offset:39936
	global_load_lds_dwordx4 v[228:229], off
	v_lshl_add_u64 v[228:229], s[26:27], 0, v[132:133]
	s_mov_b32 m0, s41
	s_nop 0
	global_load_lds_dwordx4 v[228:229], off
	s_waitcnt vmcnt(8)
	s_waitcnt lgkmcnt(0)
	s_barrier
	s_waitcnt lgkmcnt(0)
	v_mfma_f32_16x16x32_bf16 v[124:127], v[148:151], v[188:191], v[124:127]
	v_mfma_f32_16x16x32_bf16 v[120:123], v[164:167], v[188:191], v[120:123]
	v_mfma_f32_16x16x32_bf16 v[108:111], v[148:151], v[196:199], v[108:111]
	v_mfma_f32_16x16x32_bf16 v[104:107], v[164:167], v[196:199], v[104:107]
	v_mfma_f32_16x16x32_bf16 v[92:95], v[148:151], v[204:207], v[92:95]
	v_mfma_f32_16x16x32_bf16 v[88:91], v[164:167], v[204:207], v[88:91]
	v_mfma_f32_16x16x32_bf16 v[76:79], v[148:151], v[212:215], v[76:79]
	v_mfma_f32_16x16x32_bf16 v[72:75], v[164:167], v[212:215], v[72:75]
	v_mfma_f32_16x16x32_bf16 v[124:127], v[160:163], v[192:195], v[124:127]
	v_mfma_f32_16x16x32_bf16 v[120:123], v[168:171], v[192:195], v[120:123]
	v_mfma_f32_16x16x32_bf16 v[108:111], v[160:163], v[200:203], v[108:111]
	v_mfma_f32_16x16x32_bf16 v[104:107], v[168:171], v[200:203], v[104:107]
	v_mfma_f32_16x16x32_bf16 v[92:95], v[160:163], v[208:211], v[92:95]
	v_mfma_f32_16x16x32_bf16 v[88:91], v[168:171], v[208:211], v[88:91]
	v_mfma_f32_16x16x32_bf16 v[76:79], v[160:163], v[216:219], v[76:79]
	v_mfma_f32_16x16x32_bf16 v[72:75], v[168:171], v[216:219], v[72:75]
	v_mfma_f32_16x16x32_bf16 v[116:119], v[172:175], v[188:191], v[116:119]
	v_mfma_f32_16x16x32_bf16 v[112:115], v[180:183], v[188:191], v[112:115]
	v_mfma_f32_16x16x32_bf16 v[100:103], v[172:175], v[196:199], v[100:103]
	v_mfma_f32_16x16x32_bf16 v[96:99], v[180:183], v[196:199], v[96:99]
	v_mfma_f32_16x16x32_bf16 v[84:87], v[172:175], v[204:207], v[84:87]
	v_mfma_f32_16x16x32_bf16 v[80:83], v[180:183], v[204:207], v[80:83]
	v_mfma_f32_16x16x32_bf16 v[68:71], v[172:175], v[212:215], v[68:71]
	v_mfma_f32_16x16x32_bf16 v[64:67], v[180:183], v[212:215], v[64:67]
	v_mfma_f32_16x16x32_bf16 v[116:119], v[176:179], v[192:195], v[116:119]
	v_mfma_f32_16x16x32_bf16 v[112:115], v[184:187], v[192:195], v[112:115]
	v_mfma_f32_16x16x32_bf16 v[100:103], v[176:179], v[200:203], v[100:103]
	v_mfma_f32_16x16x32_bf16 v[96:99], v[184:187], v[200:203], v[96:99]
	v_mfma_f32_16x16x32_bf16 v[84:87], v[176:179], v[208:211], v[84:87]
	v_mfma_f32_16x16x32_bf16 v[80:83], v[184:187], v[208:211], v[80:83]
	v_mfma_f32_16x16x32_bf16 v[68:71], v[176:179], v[216:219], v[68:71]
	v_mfma_f32_16x16x32_bf16 v[64:67], v[184:187], v[216:219], v[64:67]
	s_barrier
	s_add_i32 s26, s67, s37
	v_lshl_add_u64 v[220:221], v[220:221], 0, s[12:13]
	s_mov_b32 m0, s26
	ds_read_b128 v[188:191], v159 offset:49152
	ds_read_b128 v[192:195], v159 offset:50176
	ds_read_b128 v[196:199], v159 offset:51200
	ds_read_b128 v[200:203], v159 offset:52224
	ds_read_b128 v[204:207], v159 offset:53248
	ds_read_b128 v[208:211], v159 offset:54272
	ds_read_b128 v[212:215], v159 offset:55296
	ds_read_b128 v[216:219], v159 offset:56320
	global_load_lds_dwordx4 v[220:221], off
	s_add_i32 m0, s26, 0x2000
	s_add_u32 s24, s24, 0x80080
	v_lshl_add_u64 v[220:221], v[222:223], 0, s[12:13]
	s_addc_u32 s25, s25, 0
	s_add_i32 s26, s68, s37
	global_load_lds_dwordx4 v[220:221], off
	v_lshl_add_u64 v[220:221], s[24:25], 0, v[130:131]
	s_mov_b32 m0, s26
	s_nop 0
	global_load_lds_dwordx4 v[220:221], off
	v_lshl_add_u64 v[220:221], s[24:25], 0, v[134:135]
	s_add_i32 m0, s26, 0x2000
	s_nop 0
	global_load_lds_dwordx4 v[220:221], off
	v_lshl_add_u64 v[220:221], v[224:225], 0, s[12:13]
	s_mov_b32 m0, s43
	s_nop 0
	global_load_lds_dwordx4 v[220:221], off
	v_lshl_add_u64 v[220:221], v[226:227], 0, s[12:13]
	s_mov_b32 m0, s44
	s_nop 0
	global_load_lds_dwordx4 v[220:221], off
	s_waitcnt vmcnt(8)
	s_waitcnt lgkmcnt(0)
	s_barrier
	s_waitcnt lgkmcnt(0)
	v_mfma_f32_16x16x32_bf16 v[60:63], v[148:151], v[188:191], v[60:63]
	v_mfma_f32_16x16x32_bf16 v[56:59], v[164:167], v[188:191], v[56:59]
	v_mfma_f32_16x16x32_bf16 v[44:47], v[148:151], v[196:199], v[44:47]
	v_mfma_f32_16x16x32_bf16 v[40:43], v[164:167], v[196:199], v[40:43]
	v_mfma_f32_16x16x32_bf16 v[28:31], v[148:151], v[204:207], v[28:31]
	v_mfma_f32_16x16x32_bf16 v[24:27], v[164:167], v[204:207], v[24:27]
	v_mfma_f32_16x16x32_bf16 v[12:15], v[148:151], v[212:215], v[12:15]
	v_mfma_f32_16x16x32_bf16 v[8:11], v[164:167], v[212:215], v[8:11]
	v_mfma_f32_16x16x32_bf16 v[60:63], v[160:163], v[192:195], v[60:63]
	v_mfma_f32_16x16x32_bf16 v[56:59], v[168:171], v[192:195], v[56:59]
	v_mfma_f32_16x16x32_bf16 v[44:47], v[160:163], v[200:203], v[44:47]
	v_mfma_f32_16x16x32_bf16 v[40:43], v[168:171], v[200:203], v[40:43]
	v_mfma_f32_16x16x32_bf16 v[28:31], v[160:163], v[208:211], v[28:31]
	v_mfma_f32_16x16x32_bf16 v[24:27], v[168:171], v[208:211], v[24:27]
	v_mfma_f32_16x16x32_bf16 v[12:15], v[160:163], v[216:219], v[12:15]
	v_mfma_f32_16x16x32_bf16 v[8:11], v[168:171], v[216:219], v[8:11]
	v_mfma_f32_16x16x32_bf16 v[52:55], v[172:175], v[188:191], v[52:55]
	v_mfma_f32_16x16x32_bf16 v[48:51], v[180:183], v[188:191], v[48:51]
	v_mfma_f32_16x16x32_bf16 v[36:39], v[172:175], v[196:199], v[36:39]
	v_mfma_f32_16x16x32_bf16 v[32:35], v[180:183], v[196:199], v[32:35]
	v_mfma_f32_16x16x32_bf16 v[20:23], v[172:175], v[204:207], v[20:23]
	v_mfma_f32_16x16x32_bf16 v[16:19], v[180:183], v[204:207], v[16:19]
	v_mfma_f32_16x16x32_bf16 v[4:7], v[172:175], v[212:215], v[4:7]
	v_mfma_f32_16x16x32_bf16 v[0:3], v[180:183], v[212:215], v[0:3]
	v_mfma_f32_16x16x32_bf16 v[52:55], v[176:179], v[192:195], v[52:55]
	v_mfma_f32_16x16x32_bf16 v[48:51], v[184:187], v[192:195], v[48:51]
	v_mfma_f32_16x16x32_bf16 v[36:39], v[176:179], v[200:203], v[36:39]
	v_mfma_f32_16x16x32_bf16 v[32:35], v[184:187], v[200:203], v[32:35]
	v_mfma_f32_16x16x32_bf16 v[20:23], v[176:179], v[208:211], v[20:23]
	v_mfma_f32_16x16x32_bf16 v[16:19], v[184:187], v[208:211], v[16:19]
	v_mfma_f32_16x16x32_bf16 v[4:7], v[176:179], v[216:219], v[4:7]
	v_mfma_f32_16x16x32_bf16 v[0:3], v[184:187], v[216:219], v[0:3]
	s_barrier
	s_add_i32 s66, s66, 2
	s_add_u32 s22, s22, 0x100
	s_addc_u32 s23, s23, 0
	s_add_u32 s61, s61, 0x100
	s_addc_u32 s65, s65, 0
	s_cmp_gt_u32 s66, 29
	s_cbranch_scc0 .LBB0_1649
	s_and_b64 vcc, exec, s[14:15]
	s_cbranch_vccz .LBB0_1652
	s_barrier

.LBB0_1809:
	ds_read_b128 v[162:165], v158
	ds_read_b128 v[166:169], v158 offset:1024
	ds_read_b128 v[170:173], v158 offset:2048
	ds_read_b128 v[174:177], v158 offset:3072
	ds_read_b128 v[178:181], v159
	ds_read_b128 v[182:185], v159 offset:1024
	ds_read_b128 v[186:189], v159 offset:2048
	ds_read_b128 v[190:193], v159 offset:3072
	s_add_u32 s38, s36, 0xfff80080
	s_addc_u32 s39, s37, -1
	s_cmp_eq_u32 s69, 28
	s_cselect_b32 s41, s25, s39
	s_cselect_b32 s40, s24, s38
	s_cselect_b32 s39, s27, s14
	s_cselect_b32 s38, s26, s11
	v_lshl_add_u64 v[150:151], s[36:37], 0, v[142:143]
	s_add_i32 m0, s42, 0xc000
	ds_read_b128 v[194:197], v160
	ds_read_b128 v[198:201], v160 offset:1024
	ds_read_b128 v[202:205], v160 offset:2048
	ds_read_b128 v[206:209], v160 offset:3072
	ds_read_b128 v[210:213], v160 offset:4096
	ds_read_b128 v[214:217], v160 offset:5120
	ds_read_b128 v[218:221], v160 offset:6144
	ds_read_b128 v[222:225], v160 offset:7168
	global_load_lds_dwordx4 v[150:151], off
	v_lshl_add_u64 v[150:151], s[36:37], 0, v[144:145]
	s_add_i32 m0, s42, 0xe000
	s_nop 0
	global_load_lds_dwordx4 v[150:151], off
	s_waitcnt vmcnt(8)
	s_waitcnt lgkmcnt(0)
	s_barrier
	s_waitcnt lgkmcnt(0)
	v_mfma_f32_16x16x32_bf16 v[124:127], v[162:165], v[194:197], v[124:127]
	v_mfma_f32_16x16x32_bf16 v[120:123], v[170:173], v[194:197], v[120:123]
	v_mfma_f32_16x16x32_bf16 v[108:111], v[162:165], v[202:205], v[108:111]
	v_mfma_f32_16x16x32_bf16 v[104:107], v[170:173], v[202:205], v[104:107]
	v_mfma_f32_16x16x32_bf16 v[92:95], v[162:165], v[210:213], v[92:95]
	v_mfma_f32_16x16x32_bf16 v[88:91], v[170:173], v[210:213], v[88:91]
	v_mfma_f32_16x16x32_bf16 v[76:79], v[162:165], v[218:221], v[76:79]
	v_mfma_f32_16x16x32_bf16 v[72:75], v[170:173], v[218:221], v[72:75]
	v_mfma_f32_16x16x32_bf16 v[124:127], v[166:169], v[198:201], v[124:127]
	v_mfma_f32_16x16x32_bf16 v[120:123], v[174:177], v[198:201], v[120:123]
	v_mfma_f32_16x16x32_bf16 v[108:111], v[166:169], v[206:209], v[108:111]
	v_mfma_f32_16x16x32_bf16 v[104:107], v[174:177], v[206:209], v[104:107]
	v_mfma_f32_16x16x32_bf16 v[92:95], v[166:169], v[214:217], v[92:95]
	v_mfma_f32_16x16x32_bf16 v[88:91], v[174:177], v[214:217], v[88:91]
	v_mfma_f32_16x16x32_bf16 v[76:79], v[166:169], v[222:225], v[76:79]
	v_mfma_f32_16x16x32_bf16 v[72:75], v[174:177], v[222:225], v[72:75]
	v_mfma_f32_16x16x32_bf16 v[116:119], v[178:181], v[194:197], v[116:119]
	v_mfma_f32_16x16x32_bf16 v[112:115], v[186:189], v[194:197], v[112:115]
	v_mfma_f32_16x16x32_bf16 v[100:103], v[178:181], v[202:205], v[100:103]
	v_mfma_f32_16x16x32_bf16 v[96:99], v[186:189], v[202:205], v[96:99]
	v_mfma_f32_16x16x32_bf16 v[84:87], v[178:181], v[210:213], v[84:87]
	v_mfma_f32_16x16x32_bf16 v[80:83], v[186:189], v[210:213], v[80:83]
	v_mfma_f32_16x16x32_bf16 v[68:71], v[178:181], v[218:221], v[68:71]
	v_mfma_f32_16x16x32_bf16 v[64:67], v[186:189], v[218:221], v[64:67]
	v_mfma_f32_16x16x32_bf16 v[116:119], v[182:185], v[198:201], v[116:119]
	v_mfma_f32_16x16x32_bf16 v[112:115], v[190:193], v[198:201], v[112:115]
	v_mfma_f32_16x16x32_bf16 v[100:103], v[182:185], v[206:209], v[100:103]
	v_mfma_f32_16x16x32_bf16 v[96:99], v[190:193], v[206:209], v[96:99]
	v_mfma_f32_16x16x32_bf16 v[84:87], v[182:185], v[214:217], v[84:87]
	v_mfma_f32_16x16x32_bf16 v[80:83], v[190:193], v[214:217], v[80:83]
	v_mfma_f32_16x16x32_bf16 v[68:71], v[182:185], v[222:225], v[68:71]
	v_mfma_f32_16x16x32_bf16 v[64:67], v[190:193], v[222:225], v[64:67]
	s_barrier
	s_add_i32 s70, s59, s23
	v_lshl_add_u64 v[150:151], s[38:39], 0, v[130:131]
	s_mov_b32 m0, s70
	ds_read_b128 v[194:197], v160 offset:16384
	ds_read_b128 v[198:201], v160 offset:17408
	ds_read_b128 v[202:205], v160 offset:18432
	ds_read_b128 v[206:209], v160 offset:19456
	ds_read_b128 v[210:213], v160 offset:20480
	ds_read_b128 v[214:217], v160 offset:21504
	ds_read_b128 v[218:221], v160 offset:22528
	ds_read_b128 v[222:225], v160 offset:23552
	global_load_lds_dwordx4 v[150:151], off
	s_add_i32 m0, s70, 0x2000
	s_add_u32 s70, s38, 0x80000
	v_lshl_add_u64 v[226:227], s[38:39], 0, v[134:135]
	s_addc_u32 s71, s39, 0
	s_add_i32 s72, s60, s23
	global_load_lds_dwordx4 v[226:227], off
	v_lshl_add_u64 v[228:229], s[70:71], 0, v[130:131]
	s_mov_b32 m0, s72
	v_lshl_add_u64 v[240:241], s[40:41], 0, v[132:133]
	global_load_lds_dwordx4 v[228:229], off
	v_lshl_add_u64 v[228:229], s[70:71], 0, v[134:135]
	s_add_i32 m0, s72, 0x2000
	s_nop 0
	global_load_lds_dwordx4 v[228:229], off
	v_lshl_add_u64 v[228:229], s[40:41], 0, v[128:129]
	s_mov_b32 m0, s42
	s_nop 0
	global_load_lds_dwordx4 v[228:229], off
	s_mov_b32 m0, s43
	s_nop 0
	global_load_lds_dwordx4 v[240:241], off
	s_waitcnt vmcnt(8)
	s_waitcnt lgkmcnt(0)
	s_barrier
	s_waitcnt lgkmcnt(0)
	v_mfma_f32_16x16x32_bf16 v[60:63], v[162:165], v[194:197], v[60:63]
	v_mfma_f32_16x16x32_bf16 v[56:59], v[170:173], v[194:197], v[56:59]
	v_mfma_f32_16x16x32_bf16 v[44:47], v[162:165], v[202:205], v[44:47]
	v_mfma_f32_16x16x32_bf16 v[40:43], v[170:173], v[202:205], v[40:43]
	v_mfma_f32_16x16x32_bf16 v[28:31], v[162:165], v[210:213], v[28:31]
	v_mfma_f32_16x16x32_bf16 v[24:27], v[170:173], v[210:213], v[24:27]
	v_mfma_f32_16x16x32_bf16 v[12:15], v[162:165], v[218:221], v[12:15]
	v_mfma_f32_16x16x32_bf16 v[8:11], v[170:173], v[218:221], v[8:11]
	v_mfma_f32_16x16x32_bf16 v[60:63], v[166:169], v[198:201], v[60:63]
	v_mfma_f32_16x16x32_bf16 v[56:59], v[174:177], v[198:201], v[56:59]
	v_mfma_f32_16x16x32_bf16 v[44:47], v[166:169], v[206:209], v[44:47]
	v_mfma_f32_16x16x32_bf16 v[40:43], v[174:177], v[206:209], v[40:43]
	v_mfma_f32_16x16x32_bf16 v[28:31], v[166:169], v[214:217], v[28:31]
	v_mfma_f32_16x16x32_bf16 v[24:27], v[174:177], v[214:217], v[24:27]
	v_mfma_f32_16x16x32_bf16 v[12:15], v[166:169], v[222:225], v[12:15]
	v_mfma_f32_16x16x32_bf16 v[8:11], v[174:177], v[222:225], v[8:11]
	v_mfma_f32_16x16x32_bf16 v[52:55], v[178:181], v[194:197], v[52:55]
	v_mfma_f32_16x16x32_bf16 v[48:51], v[186:189], v[194:197], v[48:51]
	v_mfma_f32_16x16x32_bf16 v[36:39], v[178:181], v[202:205], v[36:39]
	v_mfma_f32_16x16x32_bf16 v[32:35], v[186:189], v[202:205], v[32:35]
	v_mfma_f32_16x16x32_bf16 v[20:23], v[178:181], v[210:213], v[20:23]
	v_mfma_f32_16x16x32_bf16 v[16:19], v[186:189], v[210:213], v[16:19]
	v_mfma_f32_16x16x32_bf16 v[4:7], v[178:181], v[218:221], v[4:7]
	v_mfma_f32_16x16x32_bf16 v[0:3], v[186:189], v[218:221], v[0:3]
	v_mfma_f32_16x16x32_bf16 v[52:55], v[182:185], v[198:201], v[52:55]
	v_mfma_f32_16x16x32_bf16 v[48:51], v[190:193], v[198:201], v[48:51]
	v_mfma_f32_16x16x32_bf16 v[36:39], v[182:185], v[206:209], v[36:39]
	v_mfma_f32_16x16x32_bf16 v[32:35], v[190:193], v[206:209], v[32:35]
	v_mfma_f32_16x16x32_bf16 v[20:23], v[182:185], v[214:217], v[20:23]
	v_mfma_f32_16x16x32_bf16 v[16:19], v[190:193], v[214:217], v[16:19]
	v_mfma_f32_16x16x32_bf16 v[4:7], v[182:185], v[222:225], v[4:7]
	v_mfma_f32_16x16x32_bf16 v[0:3], v[190:193], v[222:225], v[0:3]
	s_barrier
	s_add_i32 s70, 0, 0x18000
	v_add_u32_e32 v161, s70, v154
	s_add_i32 s71, 0, 0x1c000
	ds_read_b128 v[162:165], v161
	ds_read_b128 v[166:169], v161 offset:1024
	ds_read_b128 v[170:173], v161 offset:2048
	ds_read_b128 v[174:177], v161 offset:3072
	v_add_u32_e32 v161, s71, v154
	ds_read_b128 v[178:181], v161
	ds_read_b128 v[182:185], v161 offset:1024
	ds_read_b128 v[186:189], v161 offset:2048
	ds_read_b128 v[190:193], v161 offset:3072
	s_add_u32 s40, s40, 0x80000
	s_addc_u32 s41, s41, 0
	s_mov_b32 m0, s44
	v_lshl_add_u64 v[242:243], s[40:41], 0, v[128:129]
	ds_read_b128 v[194:197], v160 offset:32768
	ds_read_b128 v[198:201], v160 offset:33792
	ds_read_b128 v[202:205], v160 offset:34816
	ds_read_b128 v[206:209], v160 offset:35840
	ds_read_b128 v[210:213], v160 offset:36864
	ds_read_b128 v[214:217], v160 offset:37888
	ds_read_b128 v[218:221], v160 offset:38912
	ds_read_b128 v[222:225], v160 offset:39936
	global_load_lds_dwordx4 v[242:243], off
	v_lshl_add_u64 v[242:243], s[40:41], 0, v[132:133]
	s_mov_b32 m0, s45
	s_nop 0
	global_load_lds_dwordx4 v[242:243], off
	s_waitcnt vmcnt(8)
	s_waitcnt lgkmcnt(0)
	s_barrier
	s_waitcnt lgkmcnt(0)
	v_mfma_f32_16x16x32_bf16 v[124:127], v[162:165], v[194:197], v[124:127]
	v_mfma_f32_16x16x32_bf16 v[120:123], v[170:173], v[194:197], v[120:123]
	v_mfma_f32_16x16x32_bf16 v[108:111], v[162:165], v[202:205], v[108:111]
	v_mfma_f32_16x16x32_bf16 v[104:107], v[170:173], v[202:205], v[104:107]
	v_mfma_f32_16x16x32_bf16 v[92:95], v[162:165], v[210:213], v[92:95]
	v_mfma_f32_16x16x32_bf16 v[88:91], v[170:173], v[210:213], v[88:91]
	v_mfma_f32_16x16x32_bf16 v[76:79], v[162:165], v[218:221], v[76:79]
	v_mfma_f32_16x16x32_bf16 v[72:75], v[170:173], v[218:221], v[72:75]
	v_mfma_f32_16x16x32_bf16 v[124:127], v[166:169], v[198:201], v[124:127]
	v_mfma_f32_16x16x32_bf16 v[120:123], v[174:177], v[198:201], v[120:123]
	v_mfma_f32_16x16x32_bf16 v[108:111], v[166:169], v[206:209], v[108:111]
	v_mfma_f32_16x16x32_bf16 v[104:107], v[174:177], v[206:209], v[104:107]
	v_mfma_f32_16x16x32_bf16 v[92:95], v[166:169], v[214:217], v[92:95]
	v_mfma_f32_16x16x32_bf16 v[88:91], v[174:177], v[214:217], v[88:91]
	v_mfma_f32_16x16x32_bf16 v[76:79], v[166:169], v[222:225], v[76:79]
	v_mfma_f32_16x16x32_bf16 v[72:75], v[174:177], v[222:225], v[72:75]
	v_mfma_f32_16x16x32_bf16 v[116:119], v[178:181], v[194:197], v[116:119]
	v_mfma_f32_16x16x32_bf16 v[112:115], v[186:189], v[194:197], v[112:115]
	v_mfma_f32_16x16x32_bf16 v[100:103], v[178:181], v[202:205], v[100:103]
	v_mfma_f32_16x16x32_bf16 v[96:99], v[186:189], v[202:205], v[96:99]
	v_mfma_f32_16x16x32_bf16 v[84:87], v[178:181], v[210:213], v[84:87]
	v_mfma_f32_16x16x32_bf16 v[80:83], v[186:189], v[210:213], v[80:83]
	v_mfma_f32_16x16x32_bf16 v[68:71], v[178:181], v[218:221], v[68:71]
	v_mfma_f32_16x16x32_bf16 v[64:67], v[186:189], v[218:221], v[64:67]
	v_mfma_f32_16x16x32_bf16 v[116:119], v[182:185], v[198:201], v[116:119]
	v_mfma_f32_16x16x32_bf16 v[112:115], v[190:193], v[198:201], v[112:115]
	v_mfma_f32_16x16x32_bf16 v[100:103], v[182:185], v[206:209], v[100:103]
	v_mfma_f32_16x16x32_bf16 v[96:99], v[190:193], v[206:209], v[96:99]
	v_mfma_f32_16x16x32_bf16 v[84:87], v[182:185], v[214:217], v[84:87]
	v_mfma_f32_16x16x32_bf16 v[80:83], v[190:193], v[214:217], v[80:83]
	v_mfma_f32_16x16x32_bf16 v[68:71], v[182:185], v[222:225], v[68:71]
	v_mfma_f32_16x16x32_bf16 v[64:67], v[190:193], v[222:225], v[64:67]
	s_barrier
	s_add_i32 s40, s70, s23
	v_lshl_add_u64 v[150:151], v[150:151], 0, s[18:19]
	s_mov_b32 m0, s40
	ds_read_b128 v[194:197], v160 offset:49152
	ds_read_b128 v[198:201], v160 offset:50176
	ds_read_b128 v[202:205], v160 offset:51200
	ds_read_b128 v[206:209], v160 offset:52224
	ds_read_b128 v[210:213], v160 offset:53248
	ds_read_b128 v[214:217], v160 offset:54272
	ds_read_b128 v[218:221], v160 offset:55296
	ds_read_b128 v[222:225], v160 offset:56320
	global_load_lds_dwordx4 v[150:151], off
	s_add_i32 m0, s40, 0x2000
	s_add_u32 s38, s38, 0x80080
	v_lshl_add_u64 v[150:151], v[226:227], 0, s[18:19]
	s_addc_u32 s39, s39, 0
	s_add_i32 s40, s71, s23
	global_load_lds_dwordx4 v[150:151], off
	v_lshl_add_u64 v[150:151], s[38:39], 0, v[130:131]
	s_mov_b32 m0, s40
	s_nop 0
	global_load_lds_dwordx4 v[150:151], off
	v_lshl_add_u64 v[150:151], s[38:39], 0, v[134:135]
	s_add_i32 m0, s40, 0x2000
	s_nop 0
	global_load_lds_dwordx4 v[150:151], off
	v_lshl_add_u64 v[150:151], v[228:229], 0, s[18:19]
	s_mov_b32 m0, s47
	s_nop 0
	global_load_lds_dwordx4 v[150:151], off
	v_lshl_add_u64 v[150:151], v[240:241], 0, s[18:19]
	s_mov_b32 m0, s58
	s_nop 0
	global_load_lds_dwordx4 v[150:151], off
	s_waitcnt vmcnt(8)
	s_waitcnt lgkmcnt(0)
	s_barrier
	s_waitcnt lgkmcnt(0)
	v_mfma_f32_16x16x32_bf16 v[60:63], v[162:165], v[194:197], v[60:63]
	v_mfma_f32_16x16x32_bf16 v[56:59], v[170:173], v[194:197], v[56:59]
	v_mfma_f32_16x16x32_bf16 v[44:47], v[162:165], v[202:205], v[44:47]
	v_mfma_f32_16x16x32_bf16 v[40:43], v[170:173], v[202:205], v[40:43]
	v_mfma_f32_16x16x32_bf16 v[28:31], v[162:165], v[210:213], v[28:31]
	v_mfma_f32_16x16x32_bf16 v[24:27], v[170:173], v[210:213], v[24:27]
	v_mfma_f32_16x16x32_bf16 v[12:15], v[162:165], v[218:221], v[12:15]
	v_mfma_f32_16x16x32_bf16 v[8:11], v[170:173], v[218:221], v[8:11]
	v_mfma_f32_16x16x32_bf16 v[60:63], v[166:169], v[198:201], v[60:63]
	v_mfma_f32_16x16x32_bf16 v[56:59], v[174:177], v[198:201], v[56:59]
	v_mfma_f32_16x16x32_bf16 v[44:47], v[166:169], v[206:209], v[44:47]
	v_mfma_f32_16x16x32_bf16 v[40:43], v[174:177], v[206:209], v[40:43]
	v_mfma_f32_16x16x32_bf16 v[28:31], v[166:169], v[214:217], v[28:31]
	v_mfma_f32_16x16x32_bf16 v[24:27], v[174:177], v[214:217], v[24:27]
	v_mfma_f32_16x16x32_bf16 v[12:15], v[166:169], v[222:225], v[12:15]
	v_mfma_f32_16x16x32_bf16 v[8:11], v[174:177], v[222:225], v[8:11]
	v_mfma_f32_16x16x32_bf16 v[52:55], v[178:181], v[194:197], v[52:55]
	v_mfma_f32_16x16x32_bf16 v[48:51], v[186:189], v[194:197], v[48:51]
	v_mfma_f32_16x16x32_bf16 v[36:39], v[178:181], v[202:205], v[36:39]
	v_mfma_f32_16x16x32_bf16 v[32:35], v[186:189], v[202:205], v[32:35]
	v_mfma_f32_16x16x32_bf16 v[20:23], v[178:181], v[210:213], v[20:23]
	v_mfma_f32_16x16x32_bf16 v[16:19], v[186:189], v[210:213], v[16:19]
	v_mfma_f32_16x16x32_bf16 v[4:7], v[178:181], v[218:221], v[4:7]
	v_mfma_f32_16x16x32_bf16 v[0:3], v[186:189], v[218:221], v[0:3]
	v_mfma_f32_16x16x32_bf16 v[52:55], v[182:185], v[198:201], v[52:55]
	v_mfma_f32_16x16x32_bf16 v[48:51], v[190:193], v[198:201], v[48:51]
	v_mfma_f32_16x16x32_bf16 v[36:39], v[182:185], v[206:209], v[36:39]
	v_mfma_f32_16x16x32_bf16 v[32:35], v[190:193], v[206:209], v[32:35]
	v_mfma_f32_16x16x32_bf16 v[20:23], v[182:185], v[214:217], v[20:23]
	v_mfma_f32_16x16x32_bf16 v[16:19], v[190:193], v[214:217], v[16:19]
	v_mfma_f32_16x16x32_bf16 v[4:7], v[182:185], v[222:225], v[4:7]
	v_mfma_f32_16x16x32_bf16 v[0:3], v[190:193], v[222:225], v[0:3]
	s_barrier
	s_add_i32 s69, s69, 2
	s_add_u32 s36, s36, 0x100
	s_addc_u32 s37, s37, 0
	s_add_u32 s11, s11, 0x100
	s_addc_u32 s14, s14, 0
	s_cmp_gt_u32 s69, 29
	s_cbranch_scc0 .LBB0_1809
	s_and_b64 vcc, exec, s[20:21]
	s_cbranch_vccz .LBB0_1812
	s_barrier

.LBB0_1910:
	v_add_u32_e32 v157, s65, v155
	ds_read_b128 v[158:161], v157
	ds_read_b128 v[162:165], v157 offset:1024
	ds_read_b128 v[166:169], v157 offset:2048
	ds_read_b128 v[170:173], v157 offset:3072
	v_add_u32_e32 v157, s66, v155
	s_add_u32 s40, s36, s38
	ds_read_b128 v[174:177], v157
	ds_read_b128 v[178:181], v157 offset:1024
	ds_read_b128 v[182:185], v157 offset:2048
	ds_read_b128 v[186:189], v157 offset:3072
	s_addc_u32 s41, s37, s39
	s_add_u32 s40, s40, 0x100
	s_addc_u32 s41, s41, 0
	s_add_u32 s73, s70, s38
	s_addc_u32 s74, s71, s39
	s_cmpk_eq_i32 s38, 0x300
	s_cselect_b32 s43, s25, s41
	s_cselect_b32 s42, s24, s40
	s_cselect_b32 s41, s27, s74
	s_cselect_b32 s40, s26, s73
	s_mov_b32 m0, s67
	v_lshl_add_u64 v[222:223], v[150:151], 0, s[38:39]
	ds_read_b128 v[190:193], v156
	ds_read_b128 v[194:197], v156 offset:1024
	ds_read_b128 v[198:201], v156 offset:2048
	ds_read_b128 v[202:205], v156 offset:3072
	ds_read_b128 v[206:209], v156 offset:4096
	ds_read_b128 v[210:213], v156 offset:5120
	ds_read_b128 v[214:217], v156 offset:6144
	ds_read_b128 v[218:221], v156 offset:7168
	global_load_lds_dwordx4 v[222:223], off
	v_lshl_add_u64 v[222:223], v[152:153], 0, s[38:39]
	s_add_i32 m0, s58, 0xe000
	s_nop 0
	global_load_lds_dwordx4 v[222:223], off
	s_waitcnt vmcnt(8)
	s_waitcnt lgkmcnt(0)
	s_barrier
	s_waitcnt lgkmcnt(0)
	v_mfma_f32_16x16x32_bf16 v[124:127], v[158:161], v[190:193], v[124:127]
	v_mfma_f32_16x16x32_bf16 v[120:123], v[166:169], v[190:193], v[120:123]
	v_mfma_f32_16x16x32_bf16 v[112:115], v[158:161], v[198:201], v[112:115]
	v_mfma_f32_16x16x32_bf16 v[104:107], v[166:169], v[198:201], v[104:107]
	v_mfma_f32_16x16x32_bf16 v[96:99], v[158:161], v[206:209], v[96:99]
	v_mfma_f32_16x16x32_bf16 v[88:91], v[166:169], v[206:209], v[88:91]
	v_mfma_f32_16x16x32_bf16 v[80:83], v[158:161], v[214:217], v[80:83]
	v_mfma_f32_16x16x32_bf16 v[72:75], v[166:169], v[214:217], v[72:75]
	v_mfma_f32_16x16x32_bf16 v[124:127], v[162:165], v[194:197], v[124:127]
	v_mfma_f32_16x16x32_bf16 v[120:123], v[170:173], v[194:197], v[120:123]
	v_mfma_f32_16x16x32_bf16 v[112:115], v[162:165], v[202:205], v[112:115]
	v_mfma_f32_16x16x32_bf16 v[104:107], v[170:173], v[202:205], v[104:107]
	v_mfma_f32_16x16x32_bf16 v[96:99], v[162:165], v[210:213], v[96:99]
	v_mfma_f32_16x16x32_bf16 v[88:91], v[170:173], v[210:213], v[88:91]
	v_mfma_f32_16x16x32_bf16 v[80:83], v[162:165], v[218:221], v[80:83]
	v_mfma_f32_16x16x32_bf16 v[72:75], v[170:173], v[218:221], v[72:75]
	v_mfma_f32_16x16x32_bf16 v[116:119], v[174:177], v[190:193], v[116:119]
	v_mfma_f32_16x16x32_bf16 v[108:111], v[182:185], v[190:193], v[108:111]
	v_mfma_f32_16x16x32_bf16 v[100:103], v[174:177], v[198:201], v[100:103]
	v_mfma_f32_16x16x32_bf16 v[92:95], v[182:185], v[198:201], v[92:95]
	v_mfma_f32_16x16x32_bf16 v[84:87], v[174:177], v[206:209], v[84:87]
	v_mfma_f32_16x16x32_bf16 v[76:79], v[182:185], v[206:209], v[76:79]
	v_mfma_f32_16x16x32_bf16 v[68:71], v[174:177], v[214:217], v[68:71]
	v_mfma_f32_16x16x32_bf16 v[64:67], v[182:185], v[214:217], v[64:67]
	v_mfma_f32_16x16x32_bf16 v[116:119], v[178:181], v[194:197], v[116:119]
	v_mfma_f32_16x16x32_bf16 v[108:111], v[186:189], v[194:197], v[108:111]
	v_mfma_f32_16x16x32_bf16 v[100:103], v[178:181], v[202:205], v[100:103]
	v_mfma_f32_16x16x32_bf16 v[92:95], v[186:189], v[202:205], v[92:95]
	v_mfma_f32_16x16x32_bf16 v[84:87], v[178:181], v[210:213], v[84:87]
	v_mfma_f32_16x16x32_bf16 v[76:79], v[186:189], v[210:213], v[76:79]
	v_mfma_f32_16x16x32_bf16 v[68:71], v[178:181], v[218:221], v[68:71]
	v_mfma_f32_16x16x32_bf16 v[64:67], v[186:189], v[218:221], v[64:67]
	s_barrier
	s_add_i32 s73, s65, s11
	v_lshl_add_u64 v[222:223], s[40:41], 0, v[134:135]
	s_mov_b32 m0, s73
	ds_read_b128 v[190:193], v156 offset:16384
	ds_read_b128 v[194:197], v156 offset:17408
	ds_read_b128 v[198:201], v156 offset:18432
	ds_read_b128 v[202:205], v156 offset:19456
	ds_read_b128 v[206:209], v156 offset:20480
	ds_read_b128 v[210:213], v156 offset:21504
	ds_read_b128 v[214:217], v156 offset:22528
	ds_read_b128 v[218:221], v156 offset:23552
	global_load_lds_dwordx4 v[222:223], off
	s_add_i32 m0, s73, 0x2000
	s_add_u32 s74, s40, 0x80000
	v_lshl_add_u64 v[224:225], s[40:41], 0, v[130:131]
	s_addc_u32 s75, s41, 0
	s_add_i32 s73, s66, s11
	global_load_lds_dwordx4 v[224:225], off
	v_lshl_add_u64 v[226:227], s[74:75], 0, v[134:135]
	s_mov_b32 m0, s73
	v_lshl_add_u64 v[228:229], s[42:43], 0, v[132:133]
	global_load_lds_dwordx4 v[226:227], off
	v_lshl_add_u64 v[226:227], s[74:75], 0, v[130:131]
	s_add_i32 m0, s73, 0x2000
	s_nop 0
	global_load_lds_dwordx4 v[226:227], off
	v_lshl_add_u64 v[226:227], s[42:43], 0, v[140:141]
	s_mov_b32 m0, s58
	s_nop 0
	global_load_lds_dwordx4 v[226:227], off
	s_mov_b32 m0, s59
	s_nop 0
	global_load_lds_dwordx4 v[228:229], off
	s_waitcnt vmcnt(8)
	s_waitcnt lgkmcnt(0)
	s_barrier
	s_waitcnt lgkmcnt(0)
	v_mfma_f32_16x16x32_bf16 v[60:63], v[158:161], v[190:193], v[60:63]
	v_mfma_f32_16x16x32_bf16 v[56:59], v[166:169], v[190:193], v[56:59]
	v_mfma_f32_16x16x32_bf16 v[48:51], v[158:161], v[198:201], v[48:51]
	v_mfma_f32_16x16x32_bf16 v[40:43], v[166:169], v[198:201], v[40:43]
	v_mfma_f32_16x16x32_bf16 v[32:35], v[158:161], v[206:209], v[32:35]
	v_mfma_f32_16x16x32_bf16 v[24:27], v[166:169], v[206:209], v[24:27]
	v_mfma_f32_16x16x32_bf16 v[16:19], v[158:161], v[214:217], v[16:19]
	v_mfma_f32_16x16x32_bf16 v[8:11], v[166:169], v[214:217], v[8:11]
	v_mfma_f32_16x16x32_bf16 v[60:63], v[162:165], v[194:197], v[60:63]
	v_mfma_f32_16x16x32_bf16 v[56:59], v[170:173], v[194:197], v[56:59]
	v_mfma_f32_16x16x32_bf16 v[48:51], v[162:165], v[202:205], v[48:51]
	v_mfma_f32_16x16x32_bf16 v[40:43], v[170:173], v[202:205], v[40:43]
	v_mfma_f32_16x16x32_bf16 v[32:35], v[162:165], v[210:213], v[32:35]
	v_mfma_f32_16x16x32_bf16 v[24:27], v[170:173], v[210:213], v[24:27]
	v_mfma_f32_16x16x32_bf16 v[16:19], v[162:165], v[218:221], v[16:19]
	v_mfma_f32_16x16x32_bf16 v[8:11], v[170:173], v[218:221], v[8:11]
	v_mfma_f32_16x16x32_bf16 v[52:55], v[174:177], v[190:193], v[52:55]
	v_mfma_f32_16x16x32_bf16 v[44:47], v[182:185], v[190:193], v[44:47]
	v_mfma_f32_16x16x32_bf16 v[36:39], v[174:177], v[198:201], v[36:39]
	v_mfma_f32_16x16x32_bf16 v[28:31], v[182:185], v[198:201], v[28:31]
	v_mfma_f32_16x16x32_bf16 v[20:23], v[174:177], v[206:209], v[20:23]
	v_mfma_f32_16x16x32_bf16 v[12:15], v[182:185], v[206:209], v[12:15]
	v_mfma_f32_16x16x32_bf16 v[4:7], v[174:177], v[214:217], v[4:7]
	v_mfma_f32_16x16x32_bf16 v[0:3], v[182:185], v[214:217], v[0:3]
	v_mfma_f32_16x16x32_bf16 v[52:55], v[178:181], v[194:197], v[52:55]
	v_mfma_f32_16x16x32_bf16 v[44:47], v[186:189], v[194:197], v[44:47]
	v_mfma_f32_16x16x32_bf16 v[36:39], v[178:181], v[202:205], v[36:39]
	v_mfma_f32_16x16x32_bf16 v[28:31], v[186:189], v[202:205], v[28:31]
	v_mfma_f32_16x16x32_bf16 v[20:23], v[178:181], v[210:213], v[20:23]
	v_mfma_f32_16x16x32_bf16 v[12:15], v[186:189], v[210:213], v[12:15]
	v_mfma_f32_16x16x32_bf16 v[4:7], v[178:181], v[218:221], v[4:7]
	v_mfma_f32_16x16x32_bf16 v[0:3], v[186:189], v[218:221], v[0:3]
	s_barrier
	s_add_i32 s73, 0, 0x18000
	v_add_u32_e32 v157, s73, v155
	s_add_i32 s74, 0, 0x1c000
	ds_read_b128 v[158:161], v157
	ds_read_b128 v[162:165], v157 offset:1024
	ds_read_b128 v[166:169], v157 offset:2048
	ds_read_b128 v[170:173], v157 offset:3072
	v_add_u32_e32 v157, s74, v155
	ds_read_b128 v[174:177], v157
	ds_read_b128 v[178:181], v157 offset:1024
	ds_read_b128 v[182:185], v157 offset:2048
	ds_read_b128 v[186:189], v157 offset:3072
	s_add_u32 s42, s42, 0x80000
	s_addc_u32 s43, s43, 0
	s_mov_b32 m0, s60
	v_lshl_add_u64 v[240:241], s[42:43], 0, v[140:141]
	ds_read_b128 v[190:193], v156 offset:32768
	ds_read_b128 v[194:197], v156 offset:33792
	ds_read_b128 v[198:201], v156 offset:34816
	ds_read_b128 v[202:205], v156 offset:35840
	ds_read_b128 v[206:209], v156 offset:36864
	ds_read_b128 v[210:213], v156 offset:37888
	ds_read_b128 v[214:217], v156 offset:38912
	ds_read_b128 v[218:221], v156 offset:39936
	global_load_lds_dwordx4 v[240:241], off
	v_lshl_add_u64 v[240:241], s[42:43], 0, v[132:133]
	s_mov_b32 m0, s61
	s_nop 0
	global_load_lds_dwordx4 v[240:241], off
	s_waitcnt vmcnt(8)
	s_waitcnt lgkmcnt(0)
	s_barrier
	s_waitcnt lgkmcnt(0)
	v_mfma_f32_16x16x32_bf16 v[124:127], v[158:161], v[190:193], v[124:127]
	v_mfma_f32_16x16x32_bf16 v[120:123], v[166:169], v[190:193], v[120:123]
	v_mfma_f32_16x16x32_bf16 v[112:115], v[158:161], v[198:201], v[112:115]
	v_mfma_f32_16x16x32_bf16 v[104:107], v[166:169], v[198:201], v[104:107]
	v_mfma_f32_16x16x32_bf16 v[96:99], v[158:161], v[206:209], v[96:99]
	v_mfma_f32_16x16x32_bf16 v[88:91], v[166:169], v[206:209], v[88:91]
	v_mfma_f32_16x16x32_bf16 v[80:83], v[158:161], v[214:217], v[80:83]
	v_mfma_f32_16x16x32_bf16 v[72:75], v[166:169], v[214:217], v[72:75]
	v_mfma_f32_16x16x32_bf16 v[124:127], v[162:165], v[194:197], v[124:127]
	v_mfma_f32_16x16x32_bf16 v[120:123], v[170:173], v[194:197], v[120:123]
	v_mfma_f32_16x16x32_bf16 v[112:115], v[162:165], v[202:205], v[112:115]
	v_mfma_f32_16x16x32_bf16 v[104:107], v[170:173], v[202:205], v[104:107]
	v_mfma_f32_16x16x32_bf16 v[96:99], v[162:165], v[210:213], v[96:99]
	v_mfma_f32_16x16x32_bf16 v[88:91], v[170:173], v[210:213], v[88:91]
	v_mfma_f32_16x16x32_bf16 v[80:83], v[162:165], v[218:221], v[80:83]
	v_mfma_f32_16x16x32_bf16 v[72:75], v[170:173], v[218:221], v[72:75]
	v_mfma_f32_16x16x32_bf16 v[116:119], v[174:177], v[190:193], v[116:119]
	v_mfma_f32_16x16x32_bf16 v[108:111], v[182:185], v[190:193], v[108:111]
	v_mfma_f32_16x16x32_bf16 v[100:103], v[174:177], v[198:201], v[100:103]
	v_mfma_f32_16x16x32_bf16 v[92:95], v[182:185], v[198:201], v[92:95]
	v_mfma_f32_16x16x32_bf16 v[84:87], v[174:177], v[206:209], v[84:87]
	v_mfma_f32_16x16x32_bf16 v[76:79], v[182:185], v[206:209], v[76:79]
	v_mfma_f32_16x16x32_bf16 v[68:71], v[174:177], v[214:217], v[68:71]
	v_mfma_f32_16x16x32_bf16 v[64:67], v[182:185], v[214:217], v[64:67]
	v_mfma_f32_16x16x32_bf16 v[116:119], v[178:181], v[194:197], v[116:119]
	v_mfma_f32_16x16x32_bf16 v[108:111], v[186:189], v[194:197], v[108:111]
	v_mfma_f32_16x16x32_bf16 v[100:103], v[178:181], v[202:205], v[100:103]
	v_mfma_f32_16x16x32_bf16 v[92:95], v[186:189], v[202:205], v[92:95]
	v_mfma_f32_16x16x32_bf16 v[84:87], v[178:181], v[210:213], v[84:87]
	v_mfma_f32_16x16x32_bf16 v[76:79], v[186:189], v[210:213], v[76:79]
	v_mfma_f32_16x16x32_bf16 v[68:71], v[178:181], v[218:221], v[68:71]
	v_mfma_f32_16x16x32_bf16 v[64:67], v[186:189], v[218:221], v[64:67]
	s_barrier
	s_add_i32 s42, s73, s11
	v_lshl_add_u64 v[222:223], v[222:223], 0, s[18:19]
	s_mov_b32 m0, s42
	ds_read_b128 v[190:193], v156 offset:49152
	ds_read_b128 v[194:197], v156 offset:50176
	ds_read_b128 v[198:201], v156 offset:51200
	ds_read_b128 v[202:205], v156 offset:52224
	ds_read_b128 v[206:209], v156 offset:53248
	ds_read_b128 v[210:213], v156 offset:54272
	ds_read_b128 v[214:217], v156 offset:55296
	ds_read_b128 v[218:221], v156 offset:56320
	global_load_lds_dwordx4 v[222:223], off
	s_add_i32 m0, s42, 0x2000
	s_add_u32 s40, s40, 0x80080
	v_lshl_add_u64 v[222:223], v[224:225], 0, s[18:19]
	s_addc_u32 s41, s41, 0
	s_add_i32 s42, s74, s11
	global_load_lds_dwordx4 v[222:223], off
	v_lshl_add_u64 v[222:223], s[40:41], 0, v[134:135]
	s_mov_b32 m0, s42
	s_nop 0
	global_load_lds_dwordx4 v[222:223], off
	v_lshl_add_u64 v[222:223], s[40:41], 0, v[130:131]
	s_add_i32 m0, s42, 0x2000
	s_nop 0
	global_load_lds_dwordx4 v[222:223], off
	v_lshl_add_u64 v[222:223], v[226:227], 0, s[18:19]
	s_mov_b32 m0, s63
	s_nop 0
	global_load_lds_dwordx4 v[222:223], off
	v_lshl_add_u64 v[222:223], v[228:229], 0, s[18:19]
	s_mov_b32 m0, s64
	s_nop 0
	global_load_lds_dwordx4 v[222:223], off
	s_waitcnt vmcnt(8)
	s_waitcnt lgkmcnt(0)
	s_barrier
	s_waitcnt lgkmcnt(0)
	v_mfma_f32_16x16x32_bf16 v[60:63], v[158:161], v[190:193], v[60:63]
	v_mfma_f32_16x16x32_bf16 v[56:59], v[166:169], v[190:193], v[56:59]
	v_mfma_f32_16x16x32_bf16 v[48:51], v[158:161], v[198:201], v[48:51]
	v_mfma_f32_16x16x32_bf16 v[40:43], v[166:169], v[198:201], v[40:43]
	v_mfma_f32_16x16x32_bf16 v[32:35], v[158:161], v[206:209], v[32:35]
	v_mfma_f32_16x16x32_bf16 v[24:27], v[166:169], v[206:209], v[24:27]
	v_mfma_f32_16x16x32_bf16 v[16:19], v[158:161], v[214:217], v[16:19]
	v_mfma_f32_16x16x32_bf16 v[8:11], v[166:169], v[214:217], v[8:11]
	v_mfma_f32_16x16x32_bf16 v[60:63], v[162:165], v[194:197], v[60:63]
	v_mfma_f32_16x16x32_bf16 v[56:59], v[170:173], v[194:197], v[56:59]
	v_mfma_f32_16x16x32_bf16 v[48:51], v[162:165], v[202:205], v[48:51]
	v_mfma_f32_16x16x32_bf16 v[40:43], v[170:173], v[202:205], v[40:43]
	v_mfma_f32_16x16x32_bf16 v[32:35], v[162:165], v[210:213], v[32:35]
	v_mfma_f32_16x16x32_bf16 v[24:27], v[170:173], v[210:213], v[24:27]
	v_mfma_f32_16x16x32_bf16 v[16:19], v[162:165], v[218:221], v[16:19]
	v_mfma_f32_16x16x32_bf16 v[8:11], v[170:173], v[218:221], v[8:11]
	v_mfma_f32_16x16x32_bf16 v[52:55], v[174:177], v[190:193], v[52:55]
	v_mfma_f32_16x16x32_bf16 v[44:47], v[182:185], v[190:193], v[44:47]
	v_mfma_f32_16x16x32_bf16 v[36:39], v[174:177], v[198:201], v[36:39]
	v_mfma_f32_16x16x32_bf16 v[28:31], v[182:185], v[198:201], v[28:31]
	v_mfma_f32_16x16x32_bf16 v[20:23], v[174:177], v[206:209], v[20:23]
	v_mfma_f32_16x16x32_bf16 v[12:15], v[182:185], v[206:209], v[12:15]
	v_mfma_f32_16x16x32_bf16 v[4:7], v[174:177], v[214:217], v[4:7]
	v_mfma_f32_16x16x32_bf16 v[0:3], v[182:185], v[214:217], v[0:3]
	v_mfma_f32_16x16x32_bf16 v[52:55], v[178:181], v[194:197], v[52:55]
	v_mfma_f32_16x16x32_bf16 v[44:47], v[186:189], v[194:197], v[44:47]
	v_mfma_f32_16x16x32_bf16 v[36:39], v[178:181], v[202:205], v[36:39]
	v_mfma_f32_16x16x32_bf16 v[28:31], v[186:189], v[202:205], v[28:31]
	v_mfma_f32_16x16x32_bf16 v[20:23], v[178:181], v[210:213], v[20:23]
	v_mfma_f32_16x16x32_bf16 v[12:15], v[186:189], v[210:213], v[12:15]
	v_mfma_f32_16x16x32_bf16 v[4:7], v[178:181], v[218:221], v[4:7]
	v_mfma_f32_16x16x32_bf16 v[0:3], v[186:189], v[218:221], v[0:3]
	s_barrier
	s_add_i32 s72, s72, 2
	s_add_u32 s38, s38, 0x100
	s_addc_u32 s39, s39, 0
	s_cmp_gt_u32 s72, 5
	s_cbranch_scc0 .LBB0_1910
	s_and_b64 vcc, exec, s[20:21]
	s_cbranch_vccz .LBB0_1913
	s_barrier

.LBB0_2035:
	s_add_u32 s11, s38, s46
	s_addc_u32 s12, s39, s47
	s_add_u32 s37, s11, 0x100
	s_addc_u32 s60, s12, 0
	s_and_b64 s[58:59], s[44:45], exec
	s_cselect_b32 s59, s25, s60
	s_cselect_b32 s58, s24, s37
	s_add_u32 s37, s40, s46
	s_addc_u32 s46, s41, s47
	s_add_u32 s37, s37, 0x100
	s_addc_u32 s46, s46, 0
	s_and_b64 s[44:45], s[44:45], exec
	s_cselect_b32 s61, s27, s46
	s_cselect_b32 s60, s26, s37
	s_add_u32 s64, s11, 0x40080
	ds_read_b128 v[156:159], v153
	ds_read_b128 v[160:163], v153 offset:1024
	ds_read_b128 v[164:167], v153 offset:2048
	ds_read_b128 v[168:171], v153 offset:3072
	ds_read_b128 v[172:175], v154
	ds_read_b128 v[176:179], v154 offset:1024
	ds_read_b128 v[180:183], v154 offset:2048
	ds_read_b128 v[184:187], v154 offset:3072
	s_addc_u32 s65, s12, 0
	s_add_i32 s89, s81, s69
	s_add_i32 m0, s70, 0xc000
	s_add_i32 s92, s70, 0xe000
	s_add_i32 s86, s89, 0x2000
	s_add_u32 s62, s60, 0x10000
	s_addc_u32 s63, s61, 0
	s_add_i32 s88, s83, s69
	s_add_i32 s87, s88, 0x2000
	s_add_i32 s85, 0, 0x18000
	s_add_i32 s37, 0, 0x1c000
	s_add_u32 s46, s58, 0x40000
	s_addc_u32 s47, s59, 0
	s_add_i32 s12, s85, s69
	s_add_i32 s11, s12, 0x2000
	s_add_u32 s44, s60, 0x10080
	s_addc_u32 s45, s61, 0
	s_add_i32 s91, s37, s69
	s_add_i32 s90, s91, 0x2000
	v_lshl_add_u64 v[148:149], s[64:65], 0, v[130:131]
	ds_read_b128 v[188:191], v155
	ds_read_b128 v[192:195], v155 offset:1024
	ds_read_b128 v[196:199], v155 offset:2048
	ds_read_b128 v[200:203], v155 offset:3072
	ds_read_b128 v[204:207], v155 offset:4096
	ds_read_b128 v[208:211], v155 offset:5120
	ds_read_b128 v[212:215], v155 offset:6144
	ds_read_b128 v[216:219], v155 offset:7168
	global_load_lds_dwordx4 v[148:149], off
	v_lshl_add_u64 v[148:149], s[64:65], 0, v[134:135]
	s_mov_b32 m0, s92
	s_nop 0
	global_load_lds_dwordx4 v[148:149], off
	s_waitcnt vmcnt(8)
	s_waitcnt lgkmcnt(0)
	s_barrier
	s_waitcnt lgkmcnt(0)
	v_mfma_f32_16x16x32_bf16 v[124:127], v[156:159], v[188:191], v[124:127]
	v_mfma_f32_16x16x32_bf16 v[120:123], v[164:167], v[188:191], v[120:123]
	v_mfma_f32_16x16x32_bf16 v[112:115], v[156:159], v[196:199], v[112:115]
	v_mfma_f32_16x16x32_bf16 v[104:107], v[164:167], v[196:199], v[104:107]
	v_mfma_f32_16x16x32_bf16 v[96:99], v[156:159], v[204:207], v[96:99]
	v_mfma_f32_16x16x32_bf16 v[88:91], v[164:167], v[204:207], v[88:91]
	v_mfma_f32_16x16x32_bf16 v[80:83], v[156:159], v[212:215], v[80:83]
	v_mfma_f32_16x16x32_bf16 v[72:75], v[164:167], v[212:215], v[72:75]
	v_mfma_f32_16x16x32_bf16 v[124:127], v[160:163], v[192:195], v[124:127]
	v_mfma_f32_16x16x32_bf16 v[120:123], v[168:171], v[192:195], v[120:123]
	v_mfma_f32_16x16x32_bf16 v[112:115], v[160:163], v[200:203], v[112:115]
	v_mfma_f32_16x16x32_bf16 v[104:107], v[168:171], v[200:203], v[104:107]
	v_mfma_f32_16x16x32_bf16 v[96:99], v[160:163], v[208:211], v[96:99]
	v_mfma_f32_16x16x32_bf16 v[88:91], v[168:171], v[208:211], v[88:91]
	v_mfma_f32_16x16x32_bf16 v[80:83], v[160:163], v[216:219], v[80:83]
	v_mfma_f32_16x16x32_bf16 v[72:75], v[168:171], v[216:219], v[72:75]
	v_mfma_f32_16x16x32_bf16 v[116:119], v[172:175], v[188:191], v[116:119]
	v_mfma_f32_16x16x32_bf16 v[108:111], v[180:183], v[188:191], v[108:111]
	v_mfma_f32_16x16x32_bf16 v[100:103], v[172:175], v[196:199], v[100:103]
	v_mfma_f32_16x16x32_bf16 v[92:95], v[180:183], v[196:199], v[92:95]
	v_mfma_f32_16x16x32_bf16 v[84:87], v[172:175], v[204:207], v[84:87]
	v_mfma_f32_16x16x32_bf16 v[76:79], v[180:183], v[204:207], v[76:79]
	v_mfma_f32_16x16x32_bf16 v[68:71], v[172:175], v[212:215], v[68:71]
	v_mfma_f32_16x16x32_bf16 v[64:67], v[180:183], v[212:215], v[64:67]
	v_mfma_f32_16x16x32_bf16 v[116:119], v[176:179], v[192:195], v[116:119]
	v_mfma_f32_16x16x32_bf16 v[108:111], v[184:187], v[192:195], v[108:111]
	v_mfma_f32_16x16x32_bf16 v[100:103], v[176:179], v[200:203], v[100:103]
	v_mfma_f32_16x16x32_bf16 v[92:95], v[184:187], v[200:203], v[92:95]
	v_mfma_f32_16x16x32_bf16 v[84:87], v[176:179], v[208:211], v[84:87]
	v_mfma_f32_16x16x32_bf16 v[76:79], v[184:187], v[208:211], v[76:79]
	v_mfma_f32_16x16x32_bf16 v[68:71], v[176:179], v[216:219], v[68:71]
	v_mfma_f32_16x16x32_bf16 v[64:67], v[184:187], v[216:219], v[64:67]
	s_barrier
	s_mov_b32 m0, s89
	v_lshl_add_u64 v[148:149], s[60:61], 0, v[132:133]
	ds_read_b128 v[188:191], v155 offset:16384
	ds_read_b128 v[192:195], v155 offset:17408
	ds_read_b128 v[196:199], v155 offset:18432
	ds_read_b128 v[200:203], v155 offset:19456
	ds_read_b128 v[204:207], v155 offset:20480
	ds_read_b128 v[208:211], v155 offset:21504
	ds_read_b128 v[212:215], v155 offset:22528
	ds_read_b128 v[216:219], v155 offset:23552
	global_load_lds_dwordx4 v[148:149], off
	v_lshl_add_u64 v[220:221], s[60:61], 0, v[140:141]
	s_mov_b32 m0, s86
	v_lshl_add_u64 v[222:223], s[62:63], 0, v[132:133]
	global_load_lds_dwordx4 v[220:221], off
	s_mov_b32 m0, s88
	v_lshl_add_u64 v[224:225], s[58:59], 0, v[134:135]
	global_load_lds_dwordx4 v[222:223], off
	v_lshl_add_u64 v[222:223], s[62:63], 0, v[140:141]
	s_mov_b32 m0, s87
	s_nop 0
	global_load_lds_dwordx4 v[222:223], off
	v_lshl_add_u64 v[222:223], s[58:59], 0, v[130:131]
	s_mov_b32 m0, s70
	s_nop 0
	global_load_lds_dwordx4 v[222:223], off
	s_mov_b32 m0, s71
	s_nop 0
	global_load_lds_dwordx4 v[224:225], off
	s_waitcnt vmcnt(8)
	s_waitcnt lgkmcnt(0)
	s_barrier
	s_waitcnt lgkmcnt(0)
	v_mfma_f32_16x16x32_bf16 v[60:63], v[156:159], v[188:191], v[60:63]
	v_mfma_f32_16x16x32_bf16 v[56:59], v[164:167], v[188:191], v[56:59]
	v_mfma_f32_16x16x32_bf16 v[48:51], v[156:159], v[196:199], v[48:51]
	v_mfma_f32_16x16x32_bf16 v[40:43], v[164:167], v[196:199], v[40:43]
	v_mfma_f32_16x16x32_bf16 v[32:35], v[156:159], v[204:207], v[32:35]
	v_mfma_f32_16x16x32_bf16 v[24:27], v[164:167], v[204:207], v[24:27]
	v_mfma_f32_16x16x32_bf16 v[16:19], v[156:159], v[212:215], v[16:19]
	v_mfma_f32_16x16x32_bf16 v[8:11], v[164:167], v[212:215], v[8:11]
	v_mfma_f32_16x16x32_bf16 v[60:63], v[160:163], v[192:195], v[60:63]
	v_mfma_f32_16x16x32_bf16 v[56:59], v[168:171], v[192:195], v[56:59]
	v_mfma_f32_16x16x32_bf16 v[48:51], v[160:163], v[200:203], v[48:51]
	v_mfma_f32_16x16x32_bf16 v[40:43], v[168:171], v[200:203], v[40:43]
	v_mfma_f32_16x16x32_bf16 v[32:35], v[160:163], v[208:211], v[32:35]
	v_mfma_f32_16x16x32_bf16 v[24:27], v[168:171], v[208:211], v[24:27]
	v_mfma_f32_16x16x32_bf16 v[16:19], v[160:163], v[216:219], v[16:19]
	v_mfma_f32_16x16x32_bf16 v[8:11], v[168:171], v[216:219], v[8:11]
	v_mfma_f32_16x16x32_bf16 v[52:55], v[172:175], v[188:191], v[52:55]
	v_mfma_f32_16x16x32_bf16 v[44:47], v[180:183], v[188:191], v[44:47]
	v_mfma_f32_16x16x32_bf16 v[36:39], v[172:175], v[196:199], v[36:39]
	v_mfma_f32_16x16x32_bf16 v[28:31], v[180:183], v[196:199], v[28:31]
	v_mfma_f32_16x16x32_bf16 v[20:23], v[172:175], v[204:207], v[20:23]
	v_mfma_f32_16x16x32_bf16 v[12:15], v[180:183], v[204:207], v[12:15]
	v_mfma_f32_16x16x32_bf16 v[4:7], v[172:175], v[212:215], v[4:7]
	v_mfma_f32_16x16x32_bf16 v[0:3], v[180:183], v[212:215], v[0:3]
	v_mfma_f32_16x16x32_bf16 v[52:55], v[176:179], v[192:195], v[52:55]
	v_mfma_f32_16x16x32_bf16 v[44:47], v[184:187], v[192:195], v[44:47]
	v_mfma_f32_16x16x32_bf16 v[36:39], v[176:179], v[200:203], v[36:39]
	v_mfma_f32_16x16x32_bf16 v[28:31], v[184:187], v[200:203], v[28:31]
	v_mfma_f32_16x16x32_bf16 v[20:23], v[176:179], v[208:211], v[20:23]
	v_mfma_f32_16x16x32_bf16 v[12:15], v[184:187], v[208:211], v[12:15]
	v_mfma_f32_16x16x32_bf16 v[4:7], v[176:179], v[216:219], v[4:7]
	v_mfma_f32_16x16x32_bf16 v[0:3], v[184:187], v[216:219], v[0:3]
	s_barrier
	v_add_u32_e32 v142, s85, v137
	ds_read_b128 v[156:159], v142
	ds_read_b128 v[160:163], v142 offset:1024
	ds_read_b128 v[164:167], v142 offset:2048
	ds_read_b128 v[168:171], v142 offset:3072
	v_add_u32_e32 v142, s37, v137
	ds_read_b128 v[172:175], v142
	ds_read_b128 v[176:179], v142 offset:1024
	ds_read_b128 v[180:183], v142 offset:2048
	ds_read_b128 v[184:187], v142 offset:3072
	s_mov_b32 m0, s72
	v_lshl_add_u64 v[226:227], s[46:47], 0, v[130:131]
	ds_read_b128 v[188:191], v155 offset:32768
	ds_read_b128 v[192:195], v155 offset:33792
	ds_read_b128 v[196:199], v155 offset:34816
	ds_read_b128 v[200:203], v155 offset:35840
	ds_read_b128 v[204:207], v155 offset:36864
	ds_read_b128 v[208:211], v155 offset:37888
	ds_read_b128 v[212:215], v155 offset:38912
	ds_read_b128 v[216:219], v155 offset:39936
	global_load_lds_dwordx4 v[226:227], off
	v_lshl_add_u64 v[226:227], s[46:47], 0, v[134:135]
	s_mov_b32 m0, s73
	s_nop 0
	global_load_lds_dwordx4 v[226:227], off
	s_waitcnt vmcnt(8)
	s_waitcnt lgkmcnt(0)
	s_barrier
	s_waitcnt lgkmcnt(0)
	v_mfma_f32_16x16x32_bf16 v[124:127], v[156:159], v[188:191], v[124:127]
	v_mfma_f32_16x16x32_bf16 v[120:123], v[164:167], v[188:191], v[120:123]
	v_mfma_f32_16x16x32_bf16 v[112:115], v[156:159], v[196:199], v[112:115]
	v_mfma_f32_16x16x32_bf16 v[104:107], v[164:167], v[196:199], v[104:107]
	v_mfma_f32_16x16x32_bf16 v[96:99], v[156:159], v[204:207], v[96:99]
	v_mfma_f32_16x16x32_bf16 v[88:91], v[164:167], v[204:207], v[88:91]
	v_mfma_f32_16x16x32_bf16 v[80:83], v[156:159], v[212:215], v[80:83]
	v_mfma_f32_16x16x32_bf16 v[72:75], v[164:167], v[212:215], v[72:75]
	v_mfma_f32_16x16x32_bf16 v[124:127], v[160:163], v[192:195], v[124:127]
	v_mfma_f32_16x16x32_bf16 v[120:123], v[168:171], v[192:195], v[120:123]
	v_mfma_f32_16x16x32_bf16 v[112:115], v[160:163], v[200:203], v[112:115]
	v_mfma_f32_16x16x32_bf16 v[104:107], v[168:171], v[200:203], v[104:107]
	v_mfma_f32_16x16x32_bf16 v[96:99], v[160:163], v[208:211], v[96:99]
	v_mfma_f32_16x16x32_bf16 v[88:91], v[168:171], v[208:211], v[88:91]
	v_mfma_f32_16x16x32_bf16 v[80:83], v[160:163], v[216:219], v[80:83]
	v_mfma_f32_16x16x32_bf16 v[72:75], v[168:171], v[216:219], v[72:75]
	v_mfma_f32_16x16x32_bf16 v[116:119], v[172:175], v[188:191], v[116:119]
	v_mfma_f32_16x16x32_bf16 v[108:111], v[180:183], v[188:191], v[108:111]
	v_mfma_f32_16x16x32_bf16 v[100:103], v[172:175], v[196:199], v[100:103]
	v_mfma_f32_16x16x32_bf16 v[92:95], v[180:183], v[196:199], v[92:95]
	v_mfma_f32_16x16x32_bf16 v[84:87], v[172:175], v[204:207], v[84:87]
	v_mfma_f32_16x16x32_bf16 v[76:79], v[180:183], v[204:207], v[76:79]
	v_mfma_f32_16x16x32_bf16 v[68:71], v[172:175], v[212:215], v[68:71]
	v_mfma_f32_16x16x32_bf16 v[64:67], v[180:183], v[212:215], v[64:67]
	v_mfma_f32_16x16x32_bf16 v[116:119], v[176:179], v[192:195], v[116:119]
	v_mfma_f32_16x16x32_bf16 v[108:111], v[184:187], v[192:195], v[108:111]
	v_mfma_f32_16x16x32_bf16 v[100:103], v[176:179], v[200:203], v[100:103]
	v_mfma_f32_16x16x32_bf16 v[92:95], v[184:187], v[200:203], v[92:95]
	v_mfma_f32_16x16x32_bf16 v[84:87], v[176:179], v[208:211], v[84:87]
	v_mfma_f32_16x16x32_bf16 v[76:79], v[184:187], v[208:211], v[76:79]
	v_mfma_f32_16x16x32_bf16 v[68:71], v[176:179], v[216:219], v[68:71]
	v_mfma_f32_16x16x32_bf16 v[64:67], v[184:187], v[216:219], v[64:67]
	s_barrier
	s_mov_b32 m0, s12
	v_lshl_add_u64 v[148:149], v[148:149], 0, s[18:19]
	ds_read_b128 v[188:191], v155 offset:49152
	ds_read_b128 v[192:195], v155 offset:50176
	ds_read_b128 v[196:199], v155 offset:51200
	ds_read_b128 v[200:203], v155 offset:52224
	ds_read_b128 v[204:207], v155 offset:53248
	ds_read_b128 v[208:211], v155 offset:54272
	ds_read_b128 v[212:215], v155 offset:55296
	ds_read_b128 v[216:219], v155 offset:56320
	global_load_lds_dwordx4 v[148:149], off
	v_lshl_add_u64 v[148:149], v[220:221], 0, s[18:19]
	s_mov_b32 m0, s11
	s_nop 0
	global_load_lds_dwordx4 v[148:149], off
	v_lshl_add_u64 v[148:149], s[44:45], 0, v[132:133]
	s_mov_b32 m0, s91
	s_nop 0
	global_load_lds_dwordx4 v[148:149], off
	v_lshl_add_u64 v[148:149], s[44:45], 0, v[140:141]
	s_mov_b32 m0, s90
	s_nop 0
	global_load_lds_dwordx4 v[148:149], off
	v_lshl_add_u64 v[148:149], v[222:223], 0, s[18:19]
	s_mov_b32 m0, s78
	s_nop 0
	global_load_lds_dwordx4 v[148:149], off
	v_lshl_add_u64 v[148:149], v[224:225], 0, s[18:19]
	s_mov_b32 m0, s79
	s_nop 0
	global_load_lds_dwordx4 v[148:149], off
	s_waitcnt vmcnt(8)
	s_waitcnt lgkmcnt(0)
	s_barrier
	s_waitcnt lgkmcnt(0)
	v_mfma_f32_16x16x32_bf16 v[60:63], v[156:159], v[188:191], v[60:63]
	v_mfma_f32_16x16x32_bf16 v[56:59], v[164:167], v[188:191], v[56:59]
	v_mfma_f32_16x16x32_bf16 v[48:51], v[156:159], v[196:199], v[48:51]
	v_mfma_f32_16x16x32_bf16 v[40:43], v[164:167], v[196:199], v[40:43]
	v_mfma_f32_16x16x32_bf16 v[32:35], v[156:159], v[204:207], v[32:35]
	v_mfma_f32_16x16x32_bf16 v[24:27], v[164:167], v[204:207], v[24:27]
	v_mfma_f32_16x16x32_bf16 v[16:19], v[156:159], v[212:215], v[16:19]
	v_mfma_f32_16x16x32_bf16 v[8:11], v[164:167], v[212:215], v[8:11]
	v_mfma_f32_16x16x32_bf16 v[60:63], v[160:163], v[192:195], v[60:63]
	v_mfma_f32_16x16x32_bf16 v[56:59], v[168:171], v[192:195], v[56:59]
	v_mfma_f32_16x16x32_bf16 v[48:51], v[160:163], v[200:203], v[48:51]
	v_mfma_f32_16x16x32_bf16 v[40:43], v[168:171], v[200:203], v[40:43]
	v_mfma_f32_16x16x32_bf16 v[32:35], v[160:163], v[208:211], v[32:35]
	v_mfma_f32_16x16x32_bf16 v[24:27], v[168:171], v[208:211], v[24:27]
	v_mfma_f32_16x16x32_bf16 v[16:19], v[160:163], v[216:219], v[16:19]
	v_mfma_f32_16x16x32_bf16 v[8:11], v[168:171], v[216:219], v[8:11]
	v_mfma_f32_16x16x32_bf16 v[52:55], v[172:175], v[188:191], v[52:55]
	v_mfma_f32_16x16x32_bf16 v[44:47], v[180:183], v[188:191], v[44:47]
	v_mfma_f32_16x16x32_bf16 v[36:39], v[172:175], v[196:199], v[36:39]
	v_mfma_f32_16x16x32_bf16 v[28:31], v[180:183], v[196:199], v[28:31]
	v_mfma_f32_16x16x32_bf16 v[20:23], v[172:175], v[204:207], v[20:23]
	v_mfma_f32_16x16x32_bf16 v[12:15], v[180:183], v[204:207], v[12:15]
	v_mfma_f32_16x16x32_bf16 v[4:7], v[172:175], v[212:215], v[4:7]
	v_mfma_f32_16x16x32_bf16 v[0:3], v[180:183], v[212:215], v[0:3]
	v_mfma_f32_16x16x32_bf16 v[52:55], v[176:179], v[192:195], v[52:55]
	v_mfma_f32_16x16x32_bf16 v[44:47], v[184:187], v[192:195], v[44:47]
	v_mfma_f32_16x16x32_bf16 v[36:39], v[176:179], v[200:203], v[36:39]
	v_mfma_f32_16x16x32_bf16 v[28:31], v[184:187], v[200:203], v[28:31]
	v_mfma_f32_16x16x32_bf16 v[20:23], v[176:179], v[208:211], v[20:23]
	v_mfma_f32_16x16x32_bf16 v[12:15], v[184:187], v[208:211], v[12:15]
	v_mfma_f32_16x16x32_bf16 v[4:7], v[176:179], v[216:219], v[4:7]
	v_mfma_f32_16x16x32_bf16 v[0:3], v[184:187], v[216:219], v[0:3]
	s_barrier
	s_andn2_b64 vcc, exec, s[42:43]
	s_mov_b64 s[44:45], -1
	s_mov_b64 s[42:43], 0
	s_mov_b64 s[46:47], 0x100
	s_cbranch_vccz .LBB0_2035
	s_and_b64 vcc, exec, s[20:21]
	s_cbranch_vccz .LBB0_2038
	s_barrier

.LBB0_2285:
	ds_read_b128 v[156:159], v152
	ds_read_b128 v[160:163], v152 offset:1024
	ds_read_b128 v[164:167], v152 offset:2048
	ds_read_b128 v[168:171], v152 offset:3072
	ds_read_b128 v[172:175], v153
	ds_read_b128 v[176:179], v153 offset:1024
	ds_read_b128 v[180:183], v153 offset:2048
	ds_read_b128 v[184:187], v153 offset:3072
	s_add_u32 s26, s24, 0xfff80080
	s_addc_u32 s27, s25, -1
	s_cmp_eq_u32 s68, 28
	s_cselect_b32 s37, s21, s27
	s_cselect_b32 s36, s20, s26
	s_cselect_b32 s27, s23, s67
	s_cselect_b32 s26, s22, s66
	v_lshl_add_u64 v[220:221], s[24:25], 0, v[144:145]
	s_add_i32 m0, s40, 0xc000
	ds_read_b128 v[188:191], v154
	ds_read_b128 v[192:195], v154 offset:1024
	ds_read_b128 v[196:199], v154 offset:2048
	ds_read_b128 v[200:203], v154 offset:3072
	ds_read_b128 v[204:207], v154 offset:4096
	ds_read_b128 v[208:211], v154 offset:5120
	ds_read_b128 v[212:215], v154 offset:6144
	ds_read_b128 v[216:219], v154 offset:7168
	global_load_lds_dwordx4 v[220:221], off
	v_lshl_add_u64 v[220:221], s[24:25], 0, v[146:147]
	s_add_i32 m0, s40, 0xe000
	s_nop 0
	global_load_lds_dwordx4 v[220:221], off
	s_waitcnt vmcnt(8)
	s_waitcnt lgkmcnt(0)
	s_barrier
	s_waitcnt lgkmcnt(0)
	v_mfma_f32_16x16x32_bf16 v[124:127], v[156:159], v[188:191], v[124:127]
	v_mfma_f32_16x16x32_bf16 v[120:123], v[164:167], v[188:191], v[120:123]
	v_mfma_f32_16x16x32_bf16 v[108:111], v[156:159], v[196:199], v[108:111]
	v_mfma_f32_16x16x32_bf16 v[104:107], v[164:167], v[196:199], v[104:107]
	v_mfma_f32_16x16x32_bf16 v[92:95], v[156:159], v[204:207], v[92:95]
	v_mfma_f32_16x16x32_bf16 v[88:91], v[164:167], v[204:207], v[88:91]
	v_mfma_f32_16x16x32_bf16 v[76:79], v[156:159], v[212:215], v[76:79]
	v_mfma_f32_16x16x32_bf16 v[72:75], v[164:167], v[212:215], v[72:75]
	v_mfma_f32_16x16x32_bf16 v[124:127], v[160:163], v[192:195], v[124:127]
	v_mfma_f32_16x16x32_bf16 v[120:123], v[168:171], v[192:195], v[120:123]
	v_mfma_f32_16x16x32_bf16 v[108:111], v[160:163], v[200:203], v[108:111]
	v_mfma_f32_16x16x32_bf16 v[104:107], v[168:171], v[200:203], v[104:107]
	v_mfma_f32_16x16x32_bf16 v[92:95], v[160:163], v[208:211], v[92:95]
	v_mfma_f32_16x16x32_bf16 v[88:91], v[168:171], v[208:211], v[88:91]
	v_mfma_f32_16x16x32_bf16 v[76:79], v[160:163], v[216:219], v[76:79]
	v_mfma_f32_16x16x32_bf16 v[72:75], v[168:171], v[216:219], v[72:75]
	v_mfma_f32_16x16x32_bf16 v[116:119], v[172:175], v[188:191], v[116:119]
	v_mfma_f32_16x16x32_bf16 v[112:115], v[180:183], v[188:191], v[112:115]
	v_mfma_f32_16x16x32_bf16 v[100:103], v[172:175], v[196:199], v[100:103]
	v_mfma_f32_16x16x32_bf16 v[96:99], v[180:183], v[196:199], v[96:99]
	v_mfma_f32_16x16x32_bf16 v[84:87], v[172:175], v[204:207], v[84:87]
	v_mfma_f32_16x16x32_bf16 v[80:83], v[180:183], v[204:207], v[80:83]
	v_mfma_f32_16x16x32_bf16 v[68:71], v[172:175], v[212:215], v[68:71]
	v_mfma_f32_16x16x32_bf16 v[64:67], v[180:183], v[212:215], v[64:67]
	v_mfma_f32_16x16x32_bf16 v[116:119], v[176:179], v[192:195], v[116:119]
	v_mfma_f32_16x16x32_bf16 v[112:115], v[184:187], v[192:195], v[112:115]
	v_mfma_f32_16x16x32_bf16 v[100:103], v[176:179], v[200:203], v[100:103]
	v_mfma_f32_16x16x32_bf16 v[96:99], v[184:187], v[200:203], v[96:99]
	v_mfma_f32_16x16x32_bf16 v[84:87], v[176:179], v[208:211], v[84:87]
	v_mfma_f32_16x16x32_bf16 v[80:83], v[184:187], v[208:211], v[80:83]
	v_mfma_f32_16x16x32_bf16 v[68:71], v[176:179], v[216:219], v[68:71]
	v_mfma_f32_16x16x32_bf16 v[64:67], v[184:187], v[216:219], v[64:67]
	s_barrier
	s_add_i32 s69, s60, s39
	v_lshl_add_u64 v[220:221], s[26:27], 0, v[132:133]
	s_mov_b32 m0, s69
	ds_read_b128 v[188:191], v154 offset:16384
	ds_read_b128 v[192:195], v154 offset:17408
	ds_read_b128 v[196:199], v154 offset:18432
	ds_read_b128 v[200:203], v154 offset:19456
	ds_read_b128 v[204:207], v154 offset:20480
	ds_read_b128 v[208:211], v154 offset:21504
	ds_read_b128 v[212:215], v154 offset:22528
	ds_read_b128 v[216:219], v154 offset:23552
	global_load_lds_dwordx4 v[220:221], off
	s_add_i32 m0, s69, 0x2000
	s_add_u32 s70, s26, 0x80000
	v_lshl_add_u64 v[222:223], s[26:27], 0, v[140:141]
	s_addc_u32 s71, s27, 0
	s_add_i32 s69, s61, s39
	global_load_lds_dwordx4 v[222:223], off
	v_lshl_add_u64 v[224:225], s[70:71], 0, v[132:133]
	s_mov_b32 m0, s69
	v_lshl_add_u64 v[226:227], s[36:37], 0, v[134:135]
	global_load_lds_dwordx4 v[224:225], off
	v_lshl_add_u64 v[224:225], s[70:71], 0, v[140:141]
	s_add_i32 m0, s69, 0x2000
	s_nop 0
	global_load_lds_dwordx4 v[224:225], off
	v_lshl_add_u64 v[224:225], s[36:37], 0, v[130:131]
	s_mov_b32 m0, s40
	s_nop 0
	global_load_lds_dwordx4 v[224:225], off
	s_mov_b32 m0, s41
	s_nop 0
	global_load_lds_dwordx4 v[226:227], off
	s_waitcnt vmcnt(8)
	s_waitcnt lgkmcnt(0)
	s_barrier
	s_waitcnt lgkmcnt(0)
	v_mfma_f32_16x16x32_bf16 v[60:63], v[156:159], v[188:191], v[60:63]
	v_mfma_f32_16x16x32_bf16 v[56:59], v[164:167], v[188:191], v[56:59]
	v_mfma_f32_16x16x32_bf16 v[44:47], v[156:159], v[196:199], v[44:47]
	v_mfma_f32_16x16x32_bf16 v[40:43], v[164:167], v[196:199], v[40:43]
	v_mfma_f32_16x16x32_bf16 v[28:31], v[156:159], v[204:207], v[28:31]
	v_mfma_f32_16x16x32_bf16 v[24:27], v[164:167], v[204:207], v[24:27]
	v_mfma_f32_16x16x32_bf16 v[12:15], v[156:159], v[212:215], v[12:15]
	v_mfma_f32_16x16x32_bf16 v[8:11], v[164:167], v[212:215], v[8:11]
	v_mfma_f32_16x16x32_bf16 v[60:63], v[160:163], v[192:195], v[60:63]
	v_mfma_f32_16x16x32_bf16 v[56:59], v[168:171], v[192:195], v[56:59]
	v_mfma_f32_16x16x32_bf16 v[44:47], v[160:163], v[200:203], v[44:47]
	v_mfma_f32_16x16x32_bf16 v[40:43], v[168:171], v[200:203], v[40:43]
	v_mfma_f32_16x16x32_bf16 v[28:31], v[160:163], v[208:211], v[28:31]
	v_mfma_f32_16x16x32_bf16 v[24:27], v[168:171], v[208:211], v[24:27]
	v_mfma_f32_16x16x32_bf16 v[12:15], v[160:163], v[216:219], v[12:15]
	v_mfma_f32_16x16x32_bf16 v[8:11], v[168:171], v[216:219], v[8:11]
	v_mfma_f32_16x16x32_bf16 v[52:55], v[172:175], v[188:191], v[52:55]
	v_mfma_f32_16x16x32_bf16 v[48:51], v[180:183], v[188:191], v[48:51]
	v_mfma_f32_16x16x32_bf16 v[36:39], v[172:175], v[196:199], v[36:39]
	v_mfma_f32_16x16x32_bf16 v[32:35], v[180:183], v[196:199], v[32:35]
	v_mfma_f32_16x16x32_bf16 v[20:23], v[172:175], v[204:207], v[20:23]
	v_mfma_f32_16x16x32_bf16 v[16:19], v[180:183], v[204:207], v[16:19]
	v_mfma_f32_16x16x32_bf16 v[4:7], v[172:175], v[212:215], v[4:7]
	v_mfma_f32_16x16x32_bf16 v[0:3], v[180:183], v[212:215], v[0:3]
	v_mfma_f32_16x16x32_bf16 v[52:55], v[176:179], v[192:195], v[52:55]
	v_mfma_f32_16x16x32_bf16 v[48:51], v[184:187], v[192:195], v[48:51]
	v_mfma_f32_16x16x32_bf16 v[36:39], v[176:179], v[200:203], v[36:39]
	v_mfma_f32_16x16x32_bf16 v[32:35], v[184:187], v[200:203], v[32:35]
	v_mfma_f32_16x16x32_bf16 v[20:23], v[176:179], v[208:211], v[20:23]
	v_mfma_f32_16x16x32_bf16 v[16:19], v[184:187], v[208:211], v[16:19]
	v_mfma_f32_16x16x32_bf16 v[4:7], v[176:179], v[216:219], v[4:7]
	v_mfma_f32_16x16x32_bf16 v[0:3], v[184:187], v[216:219], v[0:3]
	s_barrier
	s_add_i32 s69, 0, 0x18000
	v_add_u32_e32 v142, s69, v137
	s_add_i32 s70, 0, 0x1c000
	ds_read_b128 v[156:159], v142
	ds_read_b128 v[160:163], v142 offset:1024
	ds_read_b128 v[164:167], v142 offset:2048
	ds_read_b128 v[168:171], v142 offset:3072
	v_add_u32_e32 v142, s70, v137
	ds_read_b128 v[172:175], v142
	ds_read_b128 v[176:179], v142 offset:1024
	ds_read_b128 v[180:183], v142 offset:2048
	ds_read_b128 v[184:187], v142 offset:3072
	s_add_u32 s36, s36, 0x80000
	s_addc_u32 s37, s37, 0
	s_mov_b32 m0, s42
	v_lshl_add_u64 v[228:229], s[36:37], 0, v[130:131]
	ds_read_b128 v[188:191], v154 offset:32768
	ds_read_b128 v[192:195], v154 offset:33792
	ds_read_b128 v[196:199], v154 offset:34816
	ds_read_b128 v[200:203], v154 offset:35840
	ds_read_b128 v[204:207], v154 offset:36864
	ds_read_b128 v[208:211], v154 offset:37888
	ds_read_b128 v[212:215], v154 offset:38912
	ds_read_b128 v[216:219], v154 offset:39936
	global_load_lds_dwordx4 v[228:229], off
	v_lshl_add_u64 v[228:229], s[36:37], 0, v[134:135]
	s_mov_b32 m0, s43
	s_nop 0
	global_load_lds_dwordx4 v[228:229], off
	s_waitcnt vmcnt(8)
	s_waitcnt lgkmcnt(0)
	s_barrier
	s_waitcnt lgkmcnt(0)
	v_mfma_f32_16x16x32_bf16 v[124:127], v[156:159], v[188:191], v[124:127]
	v_mfma_f32_16x16x32_bf16 v[120:123], v[164:167], v[188:191], v[120:123]
	v_mfma_f32_16x16x32_bf16 v[108:111], v[156:159], v[196:199], v[108:111]
	v_mfma_f32_16x16x32_bf16 v[104:107], v[164:167], v[196:199], v[104:107]
	v_mfma_f32_16x16x32_bf16 v[92:95], v[156:159], v[204:207], v[92:95]
	v_mfma_f32_16x16x32_bf16 v[88:91], v[164:167], v[204:207], v[88:91]
	v_mfma_f32_16x16x32_bf16 v[76:79], v[156:159], v[212:215], v[76:79]
	v_mfma_f32_16x16x32_bf16 v[72:75], v[164:167], v[212:215], v[72:75]
	v_mfma_f32_16x16x32_bf16 v[124:127], v[160:163], v[192:195], v[124:127]
	v_mfma_f32_16x16x32_bf16 v[120:123], v[168:171], v[192:195], v[120:123]
	v_mfma_f32_16x16x32_bf16 v[108:111], v[160:163], v[200:203], v[108:111]
	v_mfma_f32_16x16x32_bf16 v[104:107], v[168:171], v[200:203], v[104:107]
	v_mfma_f32_16x16x32_bf16 v[92:95], v[160:163], v[208:211], v[92:95]
	v_mfma_f32_16x16x32_bf16 v[88:91], v[168:171], v[208:211], v[88:91]
	v_mfma_f32_16x16x32_bf16 v[76:79], v[160:163], v[216:219], v[76:79]
	v_mfma_f32_16x16x32_bf16 v[72:75], v[168:171], v[216:219], v[72:75]
	v_mfma_f32_16x16x32_bf16 v[116:119], v[172:175], v[188:191], v[116:119]
	v_mfma_f32_16x16x32_bf16 v[112:115], v[180:183], v[188:191], v[112:115]
	v_mfma_f32_16x16x32_bf16 v[100:103], v[172:175], v[196:199], v[100:103]
	v_mfma_f32_16x16x32_bf16 v[96:99], v[180:183], v[196:199], v[96:99]
	v_mfma_f32_16x16x32_bf16 v[84:87], v[172:175], v[204:207], v[84:87]
	v_mfma_f32_16x16x32_bf16 v[80:83], v[180:183], v[204:207], v[80:83]
	v_mfma_f32_16x16x32_bf16 v[68:71], v[172:175], v[212:215], v[68:71]
	v_mfma_f32_16x16x32_bf16 v[64:67], v[180:183], v[212:215], v[64:67]
	v_mfma_f32_16x16x32_bf16 v[116:119], v[176:179], v[192:195], v[116:119]
	v_mfma_f32_16x16x32_bf16 v[112:115], v[184:187], v[192:195], v[112:115]
	v_mfma_f32_16x16x32_bf16 v[100:103], v[176:179], v[200:203], v[100:103]
	v_mfma_f32_16x16x32_bf16 v[96:99], v[184:187], v[200:203], v[96:99]
	v_mfma_f32_16x16x32_bf16 v[84:87], v[176:179], v[208:211], v[84:87]
	v_mfma_f32_16x16x32_bf16 v[80:83], v[184:187], v[208:211], v[80:83]
	v_mfma_f32_16x16x32_bf16 v[68:71], v[176:179], v[216:219], v[68:71]
	v_mfma_f32_16x16x32_bf16 v[64:67], v[184:187], v[216:219], v[64:67]
	s_barrier
	s_add_i32 s36, s69, s39
	v_lshl_add_u64 v[220:221], v[220:221], 0, s[14:15]
	s_mov_b32 m0, s36
	ds_read_b128 v[188:191], v154 offset:49152
	ds_read_b128 v[192:195], v154 offset:50176
	ds_read_b128 v[196:199], v154 offset:51200
	ds_read_b128 v[200:203], v154 offset:52224
	ds_read_b128 v[204:207], v154 offset:53248
	ds_read_b128 v[208:211], v154 offset:54272
	ds_read_b128 v[212:215], v154 offset:55296
	ds_read_b128 v[216:219], v154 offset:56320
	global_load_lds_dwordx4 v[220:221], off
	s_add_i32 m0, s36, 0x2000
	s_add_u32 s26, s26, 0x80080
	v_lshl_add_u64 v[220:221], v[222:223], 0, s[14:15]
	s_addc_u32 s27, s27, 0
	s_add_i32 s36, s70, s39
	global_load_lds_dwordx4 v[220:221], off
	v_lshl_add_u64 v[220:221], s[26:27], 0, v[132:133]
	s_mov_b32 m0, s36
	s_nop 0
	global_load_lds_dwordx4 v[220:221], off
	v_lshl_add_u64 v[220:221], s[26:27], 0, v[140:141]
	s_add_i32 m0, s36, 0x2000
	s_nop 0
	global_load_lds_dwordx4 v[220:221], off
	v_lshl_add_u64 v[220:221], v[224:225], 0, s[14:15]
	s_mov_b32 m0, s47
	s_nop 0
	global_load_lds_dwordx4 v[220:221], off
	v_lshl_add_u64 v[220:221], v[226:227], 0, s[14:15]
	s_mov_b32 m0, s58
	s_nop 0
	global_load_lds_dwordx4 v[220:221], off
	s_waitcnt vmcnt(8)
	s_waitcnt lgkmcnt(0)
	s_barrier
	s_waitcnt lgkmcnt(0)
	v_mfma_f32_16x16x32_bf16 v[60:63], v[156:159], v[188:191], v[60:63]
	v_mfma_f32_16x16x32_bf16 v[56:59], v[164:167], v[188:191], v[56:59]
	v_mfma_f32_16x16x32_bf16 v[44:47], v[156:159], v[196:199], v[44:47]
	v_mfma_f32_16x16x32_bf16 v[40:43], v[164:167], v[196:199], v[40:43]
	v_mfma_f32_16x16x32_bf16 v[28:31], v[156:159], v[204:207], v[28:31]
	v_mfma_f32_16x16x32_bf16 v[24:27], v[164:167], v[204:207], v[24:27]
	v_mfma_f32_16x16x32_bf16 v[12:15], v[156:159], v[212:215], v[12:15]
	v_mfma_f32_16x16x32_bf16 v[8:11], v[164:167], v[212:215], v[8:11]
	v_mfma_f32_16x16x32_bf16 v[60:63], v[160:163], v[192:195], v[60:63]
	v_mfma_f32_16x16x32_bf16 v[56:59], v[168:171], v[192:195], v[56:59]
	v_mfma_f32_16x16x32_bf16 v[44:47], v[160:163], v[200:203], v[44:47]
	v_mfma_f32_16x16x32_bf16 v[40:43], v[168:171], v[200:203], v[40:43]
	v_mfma_f32_16x16x32_bf16 v[28:31], v[160:163], v[208:211], v[28:31]
	v_mfma_f32_16x16x32_bf16 v[24:27], v[168:171], v[208:211], v[24:27]
	v_mfma_f32_16x16x32_bf16 v[12:15], v[160:163], v[216:219], v[12:15]
	v_mfma_f32_16x16x32_bf16 v[8:11], v[168:171], v[216:219], v[8:11]
	v_mfma_f32_16x16x32_bf16 v[52:55], v[172:175], v[188:191], v[52:55]
	v_mfma_f32_16x16x32_bf16 v[48:51], v[180:183], v[188:191], v[48:51]
	v_mfma_f32_16x16x32_bf16 v[36:39], v[172:175], v[196:199], v[36:39]
	v_mfma_f32_16x16x32_bf16 v[32:35], v[180:183], v[196:199], v[32:35]
	v_mfma_f32_16x16x32_bf16 v[20:23], v[172:175], v[204:207], v[20:23]
	v_mfma_f32_16x16x32_bf16 v[16:19], v[180:183], v[204:207], v[16:19]
	v_mfma_f32_16x16x32_bf16 v[4:7], v[172:175], v[212:215], v[4:7]
	v_mfma_f32_16x16x32_bf16 v[0:3], v[180:183], v[212:215], v[0:3]
	v_mfma_f32_16x16x32_bf16 v[52:55], v[176:179], v[192:195], v[52:55]
	v_mfma_f32_16x16x32_bf16 v[48:51], v[184:187], v[192:195], v[48:51]
	v_mfma_f32_16x16x32_bf16 v[36:39], v[176:179], v[200:203], v[36:39]
	v_mfma_f32_16x16x32_bf16 v[32:35], v[184:187], v[200:203], v[32:35]
	v_mfma_f32_16x16x32_bf16 v[20:23], v[176:179], v[208:211], v[20:23]
	v_mfma_f32_16x16x32_bf16 v[16:19], v[184:187], v[208:211], v[16:19]
	v_mfma_f32_16x16x32_bf16 v[4:7], v[176:179], v[216:219], v[4:7]
	v_mfma_f32_16x16x32_bf16 v[0:3], v[184:187], v[216:219], v[0:3]
	s_barrier
	s_add_i32 s68, s68, 2
	s_add_u32 s24, s24, 0x100
	s_addc_u32 s25, s25, 0
	s_add_u32 s66, s66, 0x100
	s_addc_u32 s67, s67, 0
	s_cmp_gt_u32 s68, 29
	s_cbranch_scc0 .LBB0_2285
	s_and_b64 vcc, exec, s[16:17]
	s_cbranch_vccz .LBB0_2288
	s_barrier

.LBB0_2376:
	ds_read_b128 v[146:149], v155
	ds_read_b128 v[158:161], v155 offset:1024
	ds_read_b128 v[162:165], v155 offset:2048
	ds_read_b128 v[166:169], v155 offset:3072
	ds_read_b128 v[170:173], v156
	ds_read_b128 v[174:177], v156 offset:1024
	ds_read_b128 v[178:181], v156 offset:2048
	ds_read_b128 v[182:185], v156 offset:3072
	s_add_u32 s24, s22, 0xffea0080
	s_addc_u32 s25, s23, -1
	s_cmpk_eq_i32 s64, 0x54
	s_cselect_b32 s27, s19, s25
	s_cselect_b32 s26, s18, s24
	s_cselect_b32 s25, s21, s63
	s_cselect_b32 s24, s20, s62
	v_lshl_add_u64 v[218:219], s[22:23], 0, v[138:139]
	s_add_i32 m0, s36, 0xc000
	ds_read_b128 v[186:189], v157
	ds_read_b128 v[190:193], v157 offset:1024
	ds_read_b128 v[194:197], v157 offset:2048
	ds_read_b128 v[198:201], v157 offset:3072
	ds_read_b128 v[202:205], v157 offset:4096
	ds_read_b128 v[206:209], v157 offset:5120
	ds_read_b128 v[210:213], v157 offset:6144
	ds_read_b128 v[214:217], v157 offset:7168
	global_load_lds_dwordx4 v[218:219], off
	v_lshl_add_u64 v[218:219], s[22:23], 0, v[140:141]
	s_add_i32 m0, s36, 0xe000
	s_nop 0
	global_load_lds_dwordx4 v[218:219], off
	s_waitcnt vmcnt(8)
	s_waitcnt lgkmcnt(0)
	s_barrier
	s_waitcnt lgkmcnt(0)
	v_mfma_f32_16x16x32_bf16 v[124:127], v[146:149], v[186:189], v[124:127]
	v_mfma_f32_16x16x32_bf16 v[120:123], v[162:165], v[186:189], v[120:123]
	v_mfma_f32_16x16x32_bf16 v[108:111], v[146:149], v[194:197], v[108:111]
	v_mfma_f32_16x16x32_bf16 v[104:107], v[162:165], v[194:197], v[104:107]
	v_mfma_f32_16x16x32_bf16 v[92:95], v[146:149], v[202:205], v[92:95]
	v_mfma_f32_16x16x32_bf16 v[88:91], v[162:165], v[202:205], v[88:91]
	v_mfma_f32_16x16x32_bf16 v[76:79], v[146:149], v[210:213], v[76:79]
	v_mfma_f32_16x16x32_bf16 v[72:75], v[162:165], v[210:213], v[72:75]
	v_mfma_f32_16x16x32_bf16 v[124:127], v[158:161], v[190:193], v[124:127]
	v_mfma_f32_16x16x32_bf16 v[120:123], v[166:169], v[190:193], v[120:123]
	v_mfma_f32_16x16x32_bf16 v[108:111], v[158:161], v[198:201], v[108:111]
	v_mfma_f32_16x16x32_bf16 v[104:107], v[166:169], v[198:201], v[104:107]
	v_mfma_f32_16x16x32_bf16 v[92:95], v[158:161], v[206:209], v[92:95]
	v_mfma_f32_16x16x32_bf16 v[88:91], v[166:169], v[206:209], v[88:91]
	v_mfma_f32_16x16x32_bf16 v[76:79], v[158:161], v[214:217], v[76:79]
	v_mfma_f32_16x16x32_bf16 v[72:75], v[166:169], v[214:217], v[72:75]
	v_mfma_f32_16x16x32_bf16 v[116:119], v[170:173], v[186:189], v[116:119]
	v_mfma_f32_16x16x32_bf16 v[112:115], v[178:181], v[186:189], v[112:115]
	v_mfma_f32_16x16x32_bf16 v[100:103], v[170:173], v[194:197], v[100:103]
	v_mfma_f32_16x16x32_bf16 v[96:99], v[178:181], v[194:197], v[96:99]
	v_mfma_f32_16x16x32_bf16 v[84:87], v[170:173], v[202:205], v[84:87]
	v_mfma_f32_16x16x32_bf16 v[80:83], v[178:181], v[202:205], v[80:83]
	v_mfma_f32_16x16x32_bf16 v[68:71], v[170:173], v[210:213], v[68:71]
	v_mfma_f32_16x16x32_bf16 v[64:67], v[178:181], v[210:213], v[64:67]
	v_mfma_f32_16x16x32_bf16 v[116:119], v[174:177], v[190:193], v[116:119]
	v_mfma_f32_16x16x32_bf16 v[112:115], v[182:185], v[190:193], v[112:115]
	v_mfma_f32_16x16x32_bf16 v[100:103], v[174:177], v[198:201], v[100:103]
	v_mfma_f32_16x16x32_bf16 v[96:99], v[182:185], v[198:201], v[96:99]
	v_mfma_f32_16x16x32_bf16 v[84:87], v[174:177], v[206:209], v[84:87]
	v_mfma_f32_16x16x32_bf16 v[80:83], v[182:185], v[206:209], v[80:83]
	v_mfma_f32_16x16x32_bf16 v[68:71], v[174:177], v[214:217], v[68:71]
	v_mfma_f32_16x16x32_bf16 v[64:67], v[182:185], v[214:217], v[64:67]
	s_barrier
	s_add_i32 s65, s43, s17
	v_lshl_add_u64 v[218:219], s[24:25], 0, v[130:131]
	s_mov_b32 m0, s65
	ds_read_b128 v[186:189], v157 offset:16384
	ds_read_b128 v[190:193], v157 offset:17408
	ds_read_b128 v[194:197], v157 offset:18432
	ds_read_b128 v[198:201], v157 offset:19456
	ds_read_b128 v[202:205], v157 offset:20480
	ds_read_b128 v[206:209], v157 offset:21504
	ds_read_b128 v[210:213], v157 offset:22528
	ds_read_b128 v[214:217], v157 offset:23552
	global_load_lds_dwordx4 v[218:219], off
	s_add_i32 m0, s65, 0x2000
	s_add_u32 s66, s24, 0x160000
	v_lshl_add_u64 v[220:221], s[24:25], 0, v[134:135]
	s_addc_u32 s67, s25, 0
	s_add_i32 s65, s44, s17
	global_load_lds_dwordx4 v[220:221], off
	v_lshl_add_u64 v[222:223], s[66:67], 0, v[130:131]
	s_mov_b32 m0, s65
	v_lshl_add_u64 v[224:225], s[26:27], 0, v[132:133]
	global_load_lds_dwordx4 v[222:223], off
	v_lshl_add_u64 v[222:223], s[66:67], 0, v[134:135]
	s_add_i32 m0, s65, 0x2000
	s_nop 0
	global_load_lds_dwordx4 v[222:223], off
	v_lshl_add_u64 v[222:223], s[26:27], 0, v[128:129]
	s_mov_b32 m0, s36
	s_nop 0
	global_load_lds_dwordx4 v[222:223], off
	s_mov_b32 m0, s37
	s_nop 0
	global_load_lds_dwordx4 v[224:225], off
	s_waitcnt vmcnt(8)
	s_waitcnt lgkmcnt(0)
	s_barrier
	s_waitcnt lgkmcnt(0)
	v_mfma_f32_16x16x32_bf16 v[60:63], v[146:149], v[186:189], v[60:63]
	v_mfma_f32_16x16x32_bf16 v[56:59], v[162:165], v[186:189], v[56:59]
	v_mfma_f32_16x16x32_bf16 v[44:47], v[146:149], v[194:197], v[44:47]
	v_mfma_f32_16x16x32_bf16 v[40:43], v[162:165], v[194:197], v[40:43]
	v_mfma_f32_16x16x32_bf16 v[28:31], v[146:149], v[202:205], v[28:31]
	v_mfma_f32_16x16x32_bf16 v[24:27], v[162:165], v[202:205], v[24:27]
	v_mfma_f32_16x16x32_bf16 v[12:15], v[146:149], v[210:213], v[12:15]
	v_mfma_f32_16x16x32_bf16 v[8:11], v[162:165], v[210:213], v[8:11]
	v_mfma_f32_16x16x32_bf16 v[60:63], v[158:161], v[190:193], v[60:63]
	v_mfma_f32_16x16x32_bf16 v[56:59], v[166:169], v[190:193], v[56:59]
	v_mfma_f32_16x16x32_bf16 v[44:47], v[158:161], v[198:201], v[44:47]
	v_mfma_f32_16x16x32_bf16 v[40:43], v[166:169], v[198:201], v[40:43]
	v_mfma_f32_16x16x32_bf16 v[28:31], v[158:161], v[206:209], v[28:31]
	v_mfma_f32_16x16x32_bf16 v[24:27], v[166:169], v[206:209], v[24:27]
	v_mfma_f32_16x16x32_bf16 v[12:15], v[158:161], v[214:217], v[12:15]
	v_mfma_f32_16x16x32_bf16 v[8:11], v[166:169], v[214:217], v[8:11]
	v_mfma_f32_16x16x32_bf16 v[52:55], v[170:173], v[186:189], v[52:55]
	v_mfma_f32_16x16x32_bf16 v[48:51], v[178:181], v[186:189], v[48:51]
	v_mfma_f32_16x16x32_bf16 v[36:39], v[170:173], v[194:197], v[36:39]
	v_mfma_f32_16x16x32_bf16 v[32:35], v[178:181], v[194:197], v[32:35]
	v_mfma_f32_16x16x32_bf16 v[20:23], v[170:173], v[202:205], v[20:23]
	v_mfma_f32_16x16x32_bf16 v[16:19], v[178:181], v[202:205], v[16:19]
	v_mfma_f32_16x16x32_bf16 v[4:7], v[170:173], v[210:213], v[4:7]
	v_mfma_f32_16x16x32_bf16 v[0:3], v[178:181], v[210:213], v[0:3]
	v_mfma_f32_16x16x32_bf16 v[52:55], v[174:177], v[190:193], v[52:55]
	v_mfma_f32_16x16x32_bf16 v[48:51], v[182:185], v[190:193], v[48:51]
	v_mfma_f32_16x16x32_bf16 v[36:39], v[174:177], v[198:201], v[36:39]
	v_mfma_f32_16x16x32_bf16 v[32:35], v[182:185], v[198:201], v[32:35]
	v_mfma_f32_16x16x32_bf16 v[20:23], v[174:177], v[206:209], v[20:23]
	v_mfma_f32_16x16x32_bf16 v[16:19], v[182:185], v[206:209], v[16:19]
	v_mfma_f32_16x16x32_bf16 v[4:7], v[174:177], v[214:217], v[4:7]
	v_mfma_f32_16x16x32_bf16 v[0:3], v[182:185], v[214:217], v[0:3]
	s_barrier
	s_add_i32 s65, 0, 0x18000
	s_add_i32 s66, 0, 0x1c000
	v_add_u32_e32 v166, s65, v153
	v_add_u32_e32 v182, s66, v153
	ds_read_b128 v[146:149], v166
	ds_read_b128 v[158:161], v166 offset:1024
	ds_read_b128 v[162:165], v166 offset:2048
	ds_read_b128 v[166:169], v166 offset:3072
	ds_read_b128 v[170:173], v182
	ds_read_b128 v[174:177], v182 offset:1024
	ds_read_b128 v[178:181], v182 offset:2048
	ds_read_b128 v[182:185], v182 offset:3072
	s_add_u32 s26, s26, 0x160000
	s_addc_u32 s27, s27, 0
	s_mov_b32 m0, s38
	v_lshl_add_u64 v[226:227], s[26:27], 0, v[128:129]
	ds_read_b128 v[186:189], v157 offset:32768
	ds_read_b128 v[190:193], v157 offset:33792
	ds_read_b128 v[194:197], v157 offset:34816
	ds_read_b128 v[198:201], v157 offset:35840
	ds_read_b128 v[202:205], v157 offset:36864
	ds_read_b128 v[206:209], v157 offset:37888
	ds_read_b128 v[210:213], v157 offset:38912
	ds_read_b128 v[214:217], v157 offset:39936
	global_load_lds_dwordx4 v[226:227], off
	v_lshl_add_u64 v[226:227], s[26:27], 0, v[132:133]
	s_mov_b32 m0, s39
	s_nop 0
	global_load_lds_dwordx4 v[226:227], off
	s_waitcnt vmcnt(8)
	s_waitcnt lgkmcnt(0)
	s_barrier
	s_waitcnt lgkmcnt(0)
	v_mfma_f32_16x16x32_bf16 v[124:127], v[146:149], v[186:189], v[124:127]
	v_mfma_f32_16x16x32_bf16 v[120:123], v[162:165], v[186:189], v[120:123]
	v_mfma_f32_16x16x32_bf16 v[108:111], v[146:149], v[194:197], v[108:111]
	v_mfma_f32_16x16x32_bf16 v[104:107], v[162:165], v[194:197], v[104:107]
	v_mfma_f32_16x16x32_bf16 v[92:95], v[146:149], v[202:205], v[92:95]
	v_mfma_f32_16x16x32_bf16 v[88:91], v[162:165], v[202:205], v[88:91]
	v_mfma_f32_16x16x32_bf16 v[76:79], v[146:149], v[210:213], v[76:79]
	v_mfma_f32_16x16x32_bf16 v[72:75], v[162:165], v[210:213], v[72:75]
	v_mfma_f32_16x16x32_bf16 v[124:127], v[158:161], v[190:193], v[124:127]
	v_mfma_f32_16x16x32_bf16 v[120:123], v[166:169], v[190:193], v[120:123]
	v_mfma_f32_16x16x32_bf16 v[108:111], v[158:161], v[198:201], v[108:111]
	v_mfma_f32_16x16x32_bf16 v[104:107], v[166:169], v[198:201], v[104:107]
	v_mfma_f32_16x16x32_bf16 v[92:95], v[158:161], v[206:209], v[92:95]
	v_mfma_f32_16x16x32_bf16 v[88:91], v[166:169], v[206:209], v[88:91]
	v_mfma_f32_16x16x32_bf16 v[76:79], v[158:161], v[214:217], v[76:79]
	v_mfma_f32_16x16x32_bf16 v[72:75], v[166:169], v[214:217], v[72:75]
	v_mfma_f32_16x16x32_bf16 v[116:119], v[170:173], v[186:189], v[116:119]
	v_mfma_f32_16x16x32_bf16 v[112:115], v[178:181], v[186:189], v[112:115]
	v_mfma_f32_16x16x32_bf16 v[100:103], v[170:173], v[194:197], v[100:103]
	v_mfma_f32_16x16x32_bf16 v[96:99], v[178:181], v[194:197], v[96:99]
	v_mfma_f32_16x16x32_bf16 v[84:87], v[170:173], v[202:205], v[84:87]
	v_mfma_f32_16x16x32_bf16 v[80:83], v[178:181], v[202:205], v[80:83]
	v_mfma_f32_16x16x32_bf16 v[68:71], v[170:173], v[210:213], v[68:71]
	v_mfma_f32_16x16x32_bf16 v[64:67], v[178:181], v[210:213], v[64:67]
	v_mfma_f32_16x16x32_bf16 v[116:119], v[174:177], v[190:193], v[116:119]
	v_mfma_f32_16x16x32_bf16 v[112:115], v[182:185], v[190:193], v[112:115]
	v_mfma_f32_16x16x32_bf16 v[100:103], v[174:177], v[198:201], v[100:103]
	v_mfma_f32_16x16x32_bf16 v[96:99], v[182:185], v[198:201], v[96:99]
	v_mfma_f32_16x16x32_bf16 v[84:87], v[174:177], v[206:209], v[84:87]
	v_mfma_f32_16x16x32_bf16 v[80:83], v[182:185], v[206:209], v[80:83]
	v_mfma_f32_16x16x32_bf16 v[68:71], v[174:177], v[214:217], v[68:71]
	v_mfma_f32_16x16x32_bf16 v[64:67], v[182:185], v[214:217], v[64:67]
	s_barrier
	s_add_i32 s26, s65, s17
	v_lshl_add_u64 v[218:219], v[218:219], 0, s[12:13]
	s_mov_b32 m0, s26
	ds_read_b128 v[186:189], v157 offset:49152
	ds_read_b128 v[190:193], v157 offset:50176
	ds_read_b128 v[194:197], v157 offset:51200
	ds_read_b128 v[198:201], v157 offset:52224
	ds_read_b128 v[202:205], v157 offset:53248
	ds_read_b128 v[206:209], v157 offset:54272
	ds_read_b128 v[210:213], v157 offset:55296
	ds_read_b128 v[214:217], v157 offset:56320
	global_load_lds_dwordx4 v[218:219], off
	s_add_i32 m0, s26, 0x2000
	s_add_u32 s24, s24, 0x160080
	v_lshl_add_u64 v[218:219], v[220:221], 0, s[12:13]
	s_addc_u32 s25, s25, 0
	s_add_i32 s26, s66, s17
	global_load_lds_dwordx4 v[218:219], off
	v_lshl_add_u64 v[218:219], s[24:25], 0, v[130:131]
	s_mov_b32 m0, s26
	s_nop 0
	global_load_lds_dwordx4 v[218:219], off
	v_lshl_add_u64 v[218:219], s[24:25], 0, v[134:135]
	s_add_i32 m0, s26, 0x2000
	s_nop 0
	global_load_lds_dwordx4 v[218:219], off
	v_lshl_add_u64 v[218:219], v[222:223], 0, s[12:13]
	s_mov_b32 m0, s41
	s_nop 0
	global_load_lds_dwordx4 v[218:219], off
	v_lshl_add_u64 v[218:219], v[224:225], 0, s[12:13]
	s_mov_b32 m0, s42
	s_nop 0
	global_load_lds_dwordx4 v[218:219], off
	s_waitcnt vmcnt(8)
	s_waitcnt lgkmcnt(0)
	s_barrier
	s_waitcnt lgkmcnt(0)
	v_mfma_f32_16x16x32_bf16 v[60:63], v[146:149], v[186:189], v[60:63]
	v_mfma_f32_16x16x32_bf16 v[56:59], v[162:165], v[186:189], v[56:59]
	v_mfma_f32_16x16x32_bf16 v[44:47], v[146:149], v[194:197], v[44:47]
	v_mfma_f32_16x16x32_bf16 v[40:43], v[162:165], v[194:197], v[40:43]
	v_mfma_f32_16x16x32_bf16 v[28:31], v[146:149], v[202:205], v[28:31]
	v_mfma_f32_16x16x32_bf16 v[24:27], v[162:165], v[202:205], v[24:27]
	v_mfma_f32_16x16x32_bf16 v[12:15], v[146:149], v[210:213], v[12:15]
	v_mfma_f32_16x16x32_bf16 v[8:11], v[162:165], v[210:213], v[8:11]
	v_mfma_f32_16x16x32_bf16 v[60:63], v[158:161], v[190:193], v[60:63]
	v_mfma_f32_16x16x32_bf16 v[56:59], v[166:169], v[190:193], v[56:59]
	v_mfma_f32_16x16x32_bf16 v[44:47], v[158:161], v[198:201], v[44:47]
	v_mfma_f32_16x16x32_bf16 v[40:43], v[166:169], v[198:201], v[40:43]
	v_mfma_f32_16x16x32_bf16 v[28:31], v[158:161], v[206:209], v[28:31]
	v_mfma_f32_16x16x32_bf16 v[24:27], v[166:169], v[206:209], v[24:27]
	v_mfma_f32_16x16x32_bf16 v[12:15], v[158:161], v[214:217], v[12:15]
	v_mfma_f32_16x16x32_bf16 v[8:11], v[166:169], v[214:217], v[8:11]
	v_mfma_f32_16x16x32_bf16 v[52:55], v[170:173], v[186:189], v[52:55]
	v_mfma_f32_16x16x32_bf16 v[48:51], v[178:181], v[186:189], v[48:51]
	v_mfma_f32_16x16x32_bf16 v[36:39], v[170:173], v[194:197], v[36:39]
	v_mfma_f32_16x16x32_bf16 v[32:35], v[178:181], v[194:197], v[32:35]
	v_mfma_f32_16x16x32_bf16 v[20:23], v[170:173], v[202:205], v[20:23]
	v_mfma_f32_16x16x32_bf16 v[16:19], v[178:181], v[202:205], v[16:19]
	v_mfma_f32_16x16x32_bf16 v[4:7], v[170:173], v[210:213], v[4:7]
	v_mfma_f32_16x16x32_bf16 v[0:3], v[178:181], v[210:213], v[0:3]
	v_mfma_f32_16x16x32_bf16 v[52:55], v[174:177], v[190:193], v[52:55]
	v_mfma_f32_16x16x32_bf16 v[48:51], v[182:185], v[190:193], v[48:51]
	v_mfma_f32_16x16x32_bf16 v[36:39], v[174:177], v[198:201], v[36:39]
	v_mfma_f32_16x16x32_bf16 v[32:35], v[182:185], v[198:201], v[32:35]
	v_mfma_f32_16x16x32_bf16 v[20:23], v[174:177], v[206:209], v[20:23]
	v_mfma_f32_16x16x32_bf16 v[16:19], v[182:185], v[206:209], v[16:19]
	v_mfma_f32_16x16x32_bf16 v[4:7], v[174:177], v[214:217], v[4:7]
	v_mfma_f32_16x16x32_bf16 v[0:3], v[182:185], v[214:217], v[0:3]
	s_barrier
	s_add_i32 s64, s64, 2
	s_add_u32 s22, s22, 0x100
	s_addc_u32 s23, s23, 0
	s_add_u32 s62, s62, 0x100
	s_addc_u32 s63, s63, 0
	s_cmpk_gt_u32 s64, 0x55
	s_cbranch_scc0 .LBB0_2376
	s_and_b64 vcc, exec, s[14:15]
	s_cbranch_vccz .LBB0_2379
	s_barrier
